# hand-scheduled 4-step chunk bodies for the latent (R=2) and context (R=4) WKV scan chains
# speedup vs baseline: 1.0114x; 1.0114x over previous
.LBB0_963:
	s_or_b64 exec, exec, s[14:15]
	v_cvt_f32_u32_sdwa v36, v22 dst_sel:DWORD dst_unused:UNUSED_PAD src0_sel:WORD_0
	v_cvt_f32_u32_sdwa v37, v22 dst_sel:DWORD dst_unused:UNUSED_PAD src0_sel:WORD_1
	v_cvt_f32_u32_sdwa v22, v23 dst_sel:DWORD dst_unused:UNUSED_PAD src0_sel:WORD_0
	v_cvt_f32_u32_sdwa v23, v23 dst_sel:DWORD dst_unused:UNUSED_PAD src0_sel:WORD_1
	s_lshl_b32 s14, s48, 1
	s_add_u32 s14, s39, s14
	s_addc_u32 s15, s50, 0
	v_pk_fma_f32 v[24:25], v[22:23], s[56:57], 0.5 op_sel_hi:[1,0,0]
	v_pk_fma_f32 v[22:23], v[36:37], s[56:57], 0.5 op_sel_hi:[1,0,0]
	v_lshlrev_b32_e32 v36, 16, v20
	v_and_b32_e32 v37, 0xffff0000, v20
	v_add_f32_e32 v20, v34, v35
	s_mul_i32 s20, s30, 0x180000
	v_max_f32_e32 v20, 0x179abe15, v20
	s_add_u32 s14, s14, s20
	v_rsq_f32_e32 v20, v20
	s_addc_u32 s15, s15, 0
	v_lshl_add_u64 v[124:125], v[114:115], 1, s[14:15]
	s_and_b64 s[14:15], s[10:11], exec
	s_cselect_b32 s14, 4, 0xf8
	v_add_u32_e32 v234, s33, v117
	v_pk_mul_f32 v[42:43], v[26:27], v[20:21] op_sel_hi:[1,0] neg_lo:[0,1] neg_hi:[0,1]
	v_pk_mul_f32 v[40:41], v[28:29], v[20:21] op_sel_hi:[1,0] neg_lo:[0,1] neg_hi:[0,1]
	v_add_u32_e32 v126, s14, v234
	v_lshlrev_b32_e32 v38, 16, v21
	v_and_b32_e32 v39, 0xffff0000, v21
	ds_write_b128 v230, v[40:43]
	ds_write_b128 v230, v[22:25] offset:256
	v_pk_mul_f32 v[22:23], v[30:31], v[42:43] neg_lo:[0,1] neg_hi:[0,1]
	v_pk_mul_f32 v[20:21], v[32:33], v[40:41] neg_lo:[0,1] neg_hi:[0,1]
	v_ashrrev_i32_e32 v127, 31, v126
	ds_write_b128 v230, v[20:23] offset:512
	ds_write_b128 v230, v[16:19] offset:768
	ds_write_b128 v230, v[12:15] offset:1024
	ds_write_b128 v230, v[36:39] offset:1280
	v_lshl_add_u64 v[12:13], s[42:43], 0, v[126:127]
	v_lshlrev_b64 v[12:13], 7, v[12:13]
	v_lshlrev_b32_e32 v16, 1, v112
	v_or_b32_e32 v12, v12, v16
	v_lshl_add_u64 v[14:15], s[86:87], 0, v[12:13]
	global_load_dwordx2 v[128:129], v[14:15], off
	v_lshl_add_u64 v[14:15], s[90:91], 0, v[12:13]
	s_cselect_b32 s14, 8, 0xf4
	global_load_dwordx2 v[130:131], v[14:15], off
	v_lshl_add_u64 v[14:15], s[88:89], 0, v[12:13]
	v_add_u32_e32 v134, s14, v234
	global_load_dwordx2 v[132:133], v[14:15], off
	v_lshl_add_u64 v[14:15], s[34:35], 0, v[12:13]
	v_lshl_add_u64 v[12:13], s[36:37], 0, v[12:13]
	v_ashrrev_i32_e32 v135, 31, v134
	global_load_dwordx2 v[136:137], v[14:15], off
	global_load_dwordx2 v[138:139], v[12:13], off
	v_lshl_add_u64 v[12:13], s[42:43], 0, v[134:135]
	v_lshlrev_b64 v[12:13], 7, v[12:13]
	v_or_b32_e32 v12, v12, v16
	v_lshl_add_u64 v[14:15], s[86:87], 0, v[12:13]
	global_load_dwordx2 v[140:141], v[14:15], off
	v_lshl_add_u64 v[14:15], s[90:91], 0, v[12:13]
	global_load_dwordx2 v[142:143], v[14:15], off
	v_lshl_add_u64 v[14:15], s[88:89], 0, v[12:13]
	global_load_dwordx2 v[144:145], v[14:15], off
	v_lshl_add_u64 v[14:15], s[34:35], 0, v[12:13]
	v_lshl_add_u64 v[12:13], s[36:37], 0, v[12:13]
	global_load_dwordx2 v[146:147], v[14:15], off
	global_load_dwordx2 v[148:149], v[12:13], off
	s_lshl_b32 s14, s30, 2
	s_add_u32 s48, s12, s14
	s_addc_u32 s49, s13, 0
	s_and_b64 s[12:13], s[10:11], exec
	v_mov_b32_e32 v168, v169
	s_mov_b32 s14, 0
	s_cselect_b32 s55, 0, 0x1200
	v_mov_b64_e32 v[14:15], v[168:169]
	v_mov_b64_e32 v[12:13], v[168:169]
	v_mov_b64_e32 v[18:19], v[168:169]
	v_mov_b64_e32 v[16:17], v[168:169]
	v_mov_b64_e32 v[26:27], v[168:169]
	v_mov_b64_e32 v[24:25], v[168:169]
	v_mov_b64_e32 v[34:35], v[168:169]
	v_mov_b64_e32 v[32:33], v[168:169]
	v_mov_b64_e32 v[22:23], v[168:169]
	v_mov_b64_e32 v[20:21], v[168:169]
	v_mov_b64_e32 v[30:31], v[168:169]
	v_mov_b64_e32 v[28:29], v[168:169]
	v_mov_b64_e32 v[42:43], v[168:169]
	v_mov_b64_e32 v[40:41], v[168:169]
	v_mov_b64_e32 v[50:51], v[168:169]
	v_mov_b64_e32 v[48:49], v[168:169]
	v_mov_b64_e32 v[38:39], v[168:169]
	v_mov_b64_e32 v[36:37], v[168:169]
	v_mov_b64_e32 v[46:47], v[168:169]
	v_mov_b64_e32 v[44:45], v[168:169]
	v_mov_b64_e32 v[54:55], v[168:169]
	v_mov_b64_e32 v[52:53], v[168:169]
	v_mov_b64_e32 v[62:63], v[168:169]
	v_mov_b64_e32 v[60:61], v[168:169]
	v_mov_b64_e32 v[58:59], v[168:169]
	v_mov_b64_e32 v[56:57], v[168:169]
	v_mov_b64_e32 v[66:67], v[168:169]
	v_mov_b64_e32 v[64:65], v[168:169]
	v_mov_b64_e32 v[70:71], v[168:169]
	v_mov_b64_e32 v[68:69], v[168:169]
	v_mov_b64_e32 v[74:75], v[168:169]
	v_mov_b64_e32 v[72:73], v[168:169]
	s_and_b64 s[82:83], s[10:11], exec
	s_mov_b32 s97, 0x1200
	s_cselect_b32 s97, 0, s97
	s_mov_b32 s98, 0xfffffa00
	s_cselect_b32 s98, 0x600, s98
	s_mov_b32 s80, 0xffffff80
	s_cselect_b32 s80, 0x80, s80
	s_cselect_b32 s81, 0, -1
	s_cselect_b32 s99, 0, 3

.LBB0_965:
	s_add_i32 s82, s67, s99
	s_ashr_i32 s83, s82, 31
	s_lshl_b64 s[82:83], s[82:83], 7
	v_lshl_add_u64 v[238:239], v[124:125], 0, s[82:83]
	v_add_u32_e32 v218, s97, v232
	v_lshl_add_u32 v222, v114, 2, s57
	v_add_u32_e32 v219, s98, v218
	v_add_u32_e32 v222, s97, v222
	v_add_u32_e32 v220, s98, v219
	v_add_u32_e32 v223, s98, v222
	v_add_u32_e32 v221, s98, v220
	v_add_u32_e32 v236, s98, v223
	v_add_u32_e32 v237, s98, v236
	ds_read_b128 v[92:95], v218 offset:256
	ds_read_b128 v[96:99], v218 offset:272
	ds_read_b128 v[100:103], v218 offset:288
	ds_read_b128 v[104:107], v218 offset:304
	ds_read_b128 v[108:111], v218 offset:512
	ds_read_b128 v[170:173], v218 offset:528
	ds_read_b128 v[174:177], v218 offset:544
	ds_read_b128 v[178:181], v218 offset:560
	ds_read_b128 v[198:201], v222 offset:1280
	s_waitcnt lgkmcnt(9)
	v_pk_mul_f32 v[202:203], v[72:73], v[76:77]
	v_pk_mul_f32 v[204:205], v[74:75], v[78:79]
	v_pk_mul_f32 v[206:207], v[60:61], v[76:77]
	v_pk_mul_f32 v[208:209], v[62:63], v[78:79]
	v_pk_mul_f32 v[210:211], v[48:49], v[76:77]
	v_pk_mul_f32 v[212:213], v[50:51], v[78:79]
	v_pk_mul_f32 v[214:215], v[32:33], v[76:77]
	v_pk_mul_f32 v[216:217], v[34:35], v[78:79]
	v_pk_fma_f32 v[202:203], v[68:69], v[80:81], v[202:203]
	v_pk_fma_f32 v[204:205], v[70:71], v[82:83], v[204:205]
	v_pk_fma_f32 v[206:207], v[52:53], v[80:81], v[206:207]
	v_pk_fma_f32 v[208:209], v[54:55], v[82:83], v[208:209]
	v_pk_fma_f32 v[210:211], v[40:41], v[80:81], v[210:211]
	v_pk_fma_f32 v[212:213], v[42:43], v[82:83], v[212:213]
	v_pk_fma_f32 v[214:215], v[24:25], v[80:81], v[214:215]
	v_pk_fma_f32 v[216:217], v[26:27], v[82:83], v[216:217]
	v_pk_fma_f32 v[202:203], v[64:65], v[84:85], v[202:203]
	v_pk_fma_f32 v[204:205], v[66:67], v[86:87], v[204:205]
	v_pk_fma_f32 v[206:207], v[44:45], v[84:85], v[206:207]
	v_pk_fma_f32 v[208:209], v[46:47], v[86:87], v[208:209]
	v_pk_fma_f32 v[210:211], v[28:29], v[84:85], v[210:211]
	v_pk_fma_f32 v[212:213], v[30:31], v[86:87], v[212:213]
	v_pk_fma_f32 v[214:215], v[16:17], v[84:85], v[214:215]
	v_pk_fma_f32 v[216:217], v[18:19], v[86:87], v[216:217]
	v_pk_fma_f32 v[202:203], v[56:57], v[88:89], v[202:203]
	v_pk_fma_f32 v[204:205], v[58:59], v[90:91], v[204:205]
	v_pk_fma_f32 v[206:207], v[36:37], v[88:89], v[206:207]
	v_pk_fma_f32 v[208:209], v[38:39], v[90:91], v[208:209]
	v_pk_fma_f32 v[210:211], v[20:21], v[88:89], v[210:211]
	v_pk_fma_f32 v[212:213], v[22:23], v[90:91], v[212:213]
	v_pk_fma_f32 v[214:215], v[12:13], v[88:89], v[214:215]
	v_pk_fma_f32 v[216:217], v[14:15], v[90:91], v[216:217]
	s_waitcnt lgkmcnt(1)
	v_pk_add_f32 v[202:203], v[202:203], v[204:205]
	v_pk_add_f32 v[206:207], v[206:207], v[208:209]
	v_pk_add_f32 v[210:211], v[210:211], v[212:213]
	v_pk_add_f32 v[214:215], v[214:215], v[216:217]
	ds_read_b128 v[182:185], v218 offset:768
	v_add_f32_e32 v202, v202, v203
	v_add_f32_e32 v206, v206, v207
	v_add_f32_e32 v210, v210, v211
	v_add_f32_e32 v214, v214, v215
	ds_read_b128 v[186:189], v218 offset:784
	v_add_f32_dpp v202, v202, v202 quad_perm:[1,0,3,2] row_mask:0xf bank_mask:0xf bound_ctrl:1
	v_add_f32_dpp v206, v206, v206 quad_perm:[1,0,3,2] row_mask:0xf bank_mask:0xf bound_ctrl:1
	v_add_f32_dpp v210, v210, v210 quad_perm:[1,0,3,2] row_mask:0xf bank_mask:0xf bound_ctrl:1
	v_add_f32_dpp v214, v214, v214 quad_perm:[1,0,3,2] row_mask:0xf bank_mask:0xf bound_ctrl:1
	ds_read_b128 v[190:193], v218 offset:800
	v_add_f32_dpp v202, v202, v202 quad_perm:[2,3,0,1] row_mask:0xf bank_mask:0xf bound_ctrl:1
	v_add_f32_dpp v206, v206, v206 quad_perm:[2,3,0,1] row_mask:0xf bank_mask:0xf bound_ctrl:1
	v_add_f32_dpp v210, v210, v210 quad_perm:[2,3,0,1] row_mask:0xf bank_mask:0xf bound_ctrl:1
	v_add_f32_dpp v214, v214, v214 quad_perm:[2,3,0,1] row_mask:0xf bank_mask:0xf bound_ctrl:1
	ds_read_b128 v[194:197], v218 offset:816
	v_pk_mul_f32 v[204:205], v[108:109], v[202:203] op_sel_hi:[1,0]
	v_pk_mul_f32 v[208:209], v[108:109], v[206:207] op_sel_hi:[1,0]
	v_pk_mul_f32 v[212:213], v[108:109], v[210:211] op_sel_hi:[1,0]
	v_pk_mul_f32 v[108:109], v[108:109], v[214:215] op_sel_hi:[1,0]
	v_pk_fma_f32 v[72:73], v[72:73], v[92:93], v[204:205]
	v_pk_fma_f32 v[60:61], v[60:61], v[92:93], v[208:209]
	v_pk_fma_f32 v[48:49], v[48:49], v[92:93], v[212:213]
	v_pk_fma_f32 v[32:33], v[32:33], v[92:93], v[108:109]
	v_pk_mul_f32 v[216:217], v[110:111], v[202:203] op_sel_hi:[1,0]
	v_pk_mul_f32 v[242:243], v[110:111], v[206:207] op_sel_hi:[1,0]
	v_pk_mul_f32 v[244:245], v[110:111], v[210:211] op_sel_hi:[1,0]
	v_pk_mul_f32 v[110:111], v[110:111], v[214:215] op_sel_hi:[1,0]
	v_pk_fma_f32 v[74:75], v[74:75], v[94:95], v[216:217]
	v_pk_fma_f32 v[62:63], v[62:63], v[94:95], v[242:243]
	v_pk_fma_f32 v[50:51], v[50:51], v[94:95], v[244:245]
	v_pk_fma_f32 v[34:35], v[34:35], v[94:95], v[110:111]
	v_pk_mul_f32 v[204:205], v[170:171], v[202:203] op_sel_hi:[1,0]
	v_pk_mul_f32 v[208:209], v[170:171], v[206:207] op_sel_hi:[1,0]
	v_pk_mul_f32 v[212:213], v[170:171], v[210:211] op_sel_hi:[1,0]
	v_pk_mul_f32 v[170:171], v[170:171], v[214:215] op_sel_hi:[1,0]
	v_pk_fma_f32 v[68:69], v[68:69], v[96:97], v[204:205]
	v_pk_fma_f32 v[52:53], v[52:53], v[96:97], v[208:209]
	v_pk_fma_f32 v[40:41], v[40:41], v[96:97], v[212:213]
	v_pk_fma_f32 v[24:25], v[24:25], v[96:97], v[170:171]
	v_pk_mul_f32 v[216:217], v[172:173], v[202:203] op_sel_hi:[1,0]
	v_pk_mul_f32 v[242:243], v[172:173], v[206:207] op_sel_hi:[1,0]
	v_pk_mul_f32 v[244:245], v[172:173], v[210:211] op_sel_hi:[1,0]
	v_pk_mul_f32 v[172:173], v[172:173], v[214:215] op_sel_hi:[1,0]
	v_pk_fma_f32 v[70:71], v[70:71], v[98:99], v[216:217]
	v_pk_fma_f32 v[54:55], v[54:55], v[98:99], v[242:243]
	v_pk_fma_f32 v[42:43], v[42:43], v[98:99], v[244:245]
	v_pk_fma_f32 v[26:27], v[26:27], v[98:99], v[172:173]
	v_pk_mul_f32 v[204:205], v[174:175], v[202:203] op_sel_hi:[1,0]
	v_pk_mul_f32 v[208:209], v[174:175], v[206:207] op_sel_hi:[1,0]
	v_pk_mul_f32 v[212:213], v[174:175], v[210:211] op_sel_hi:[1,0]
	v_pk_mul_f32 v[174:175], v[174:175], v[214:215] op_sel_hi:[1,0]
	v_pk_fma_f32 v[64:65], v[64:65], v[100:101], v[204:205]
	v_pk_fma_f32 v[44:45], v[44:45], v[100:101], v[208:209]
	v_pk_fma_f32 v[28:29], v[28:29], v[100:101], v[212:213]
	v_pk_fma_f32 v[16:17], v[16:17], v[100:101], v[174:175]
	v_pk_mul_f32 v[216:217], v[176:177], v[202:203] op_sel_hi:[1,0]
	v_pk_mul_f32 v[242:243], v[176:177], v[206:207] op_sel_hi:[1,0]
	v_pk_mul_f32 v[244:245], v[176:177], v[210:211] op_sel_hi:[1,0]
	v_pk_mul_f32 v[176:177], v[176:177], v[214:215] op_sel_hi:[1,0]
	v_pk_fma_f32 v[66:67], v[66:67], v[102:103], v[216:217]
	v_pk_fma_f32 v[46:47], v[46:47], v[102:103], v[242:243]
	v_pk_fma_f32 v[30:31], v[30:31], v[102:103], v[244:245]
	v_pk_fma_f32 v[18:19], v[18:19], v[102:103], v[176:177]
	v_pk_mul_f32 v[204:205], v[178:179], v[202:203] op_sel_hi:[1,0]
	v_pk_mul_f32 v[208:209], v[178:179], v[206:207] op_sel_hi:[1,0]
	v_pk_mul_f32 v[212:213], v[178:179], v[210:211] op_sel_hi:[1,0]
	v_pk_mul_f32 v[178:179], v[178:179], v[214:215] op_sel_hi:[1,0]
	v_pk_fma_f32 v[56:57], v[56:57], v[104:105], v[204:205]
	v_pk_fma_f32 v[36:37], v[36:37], v[104:105], v[208:209]
	v_pk_fma_f32 v[20:21], v[20:21], v[104:105], v[212:213]
	v_pk_fma_f32 v[12:13], v[12:13], v[104:105], v[178:179]
	v_pk_mul_f32 v[216:217], v[180:181], v[202:203] op_sel_hi:[1,0]
	v_pk_mul_f32 v[242:243], v[180:181], v[206:207] op_sel_hi:[1,0]
	v_pk_mul_f32 v[244:245], v[180:181], v[210:211] op_sel_hi:[1,0]
	v_pk_mul_f32 v[180:181], v[180:181], v[214:215] op_sel_hi:[1,0]
	v_pk_fma_f32 v[58:59], v[58:59], v[106:107], v[216:217]
	v_pk_fma_f32 v[38:39], v[38:39], v[106:107], v[242:243]
	v_pk_fma_f32 v[22:23], v[22:23], v[106:107], v[244:245]
	v_pk_fma_f32 v[14:15], v[14:15], v[106:107], v[180:181]
	ds_read_b128 v[92:95], v218 offset:1024
	ds_read_b128 v[96:99], v218 offset:1040
	ds_read_b128 v[100:103], v218 offset:1056
	ds_read_b128 v[104:107], v218 offset:1072
	ds_read_b128 v[76:79], v219 offset:0
	ds_read_b128 v[80:83], v219 offset:16
	ds_read_b128 v[84:87], v219 offset:32
	ds_read_b128 v[88:91], v219 offset:48
	s_waitcnt lgkmcnt(8)
	v_pk_fma_f32 v[72:73], v[198:199], v[182:183], v[72:73] op_sel_hi:[0,1,1]
	v_pk_fma_f32 v[60:61], v[198:199], v[182:183], v[60:61] op_sel:[1,0,0]
	v_pk_fma_f32 v[48:49], v[200:201], v[182:183], v[48:49] op_sel_hi:[0,1,1]
	v_pk_fma_f32 v[32:33], v[200:201], v[182:183], v[32:33] op_sel:[1,0,0]
	v_pk_fma_f32 v[74:75], v[198:199], v[184:185], v[74:75] op_sel_hi:[0,1,1]
	v_pk_fma_f32 v[62:63], v[198:199], v[184:185], v[62:63] op_sel:[1,0,0]
	v_pk_fma_f32 v[50:51], v[200:201], v[184:185], v[50:51] op_sel_hi:[0,1,1]
	v_pk_fma_f32 v[34:35], v[200:201], v[184:185], v[34:35] op_sel:[1,0,0]
	v_pk_fma_f32 v[68:69], v[198:199], v[186:187], v[68:69] op_sel_hi:[0,1,1]
	v_pk_fma_f32 v[52:53], v[198:199], v[186:187], v[52:53] op_sel:[1,0,0]
	v_pk_fma_f32 v[40:41], v[200:201], v[186:187], v[40:41] op_sel_hi:[0,1,1]
	v_pk_fma_f32 v[24:25], v[200:201], v[186:187], v[24:25] op_sel:[1,0,0]
	v_pk_fma_f32 v[70:71], v[198:199], v[188:189], v[70:71] op_sel_hi:[0,1,1]
	v_pk_fma_f32 v[54:55], v[198:199], v[188:189], v[54:55] op_sel:[1,0,0]
	v_pk_fma_f32 v[42:43], v[200:201], v[188:189], v[42:43] op_sel_hi:[0,1,1]
	v_pk_fma_f32 v[26:27], v[200:201], v[188:189], v[26:27] op_sel:[1,0,0]
	v_pk_fma_f32 v[64:65], v[198:199], v[190:191], v[64:65] op_sel_hi:[0,1,1]
	v_pk_fma_f32 v[44:45], v[198:199], v[190:191], v[44:45] op_sel:[1,0,0]
	v_pk_fma_f32 v[28:29], v[200:201], v[190:191], v[28:29] op_sel_hi:[0,1,1]
	v_pk_fma_f32 v[16:17], v[200:201], v[190:191], v[16:17] op_sel:[1,0,0]
	v_pk_fma_f32 v[66:67], v[198:199], v[192:193], v[66:67] op_sel_hi:[0,1,1]
	v_pk_fma_f32 v[46:47], v[198:199], v[192:193], v[46:47] op_sel:[1,0,0]
	v_pk_fma_f32 v[30:31], v[200:201], v[192:193], v[30:31] op_sel_hi:[0,1,1]
	v_pk_fma_f32 v[18:19], v[200:201], v[192:193], v[18:19] op_sel:[1,0,0]
	v_pk_fma_f32 v[56:57], v[198:199], v[194:195], v[56:57] op_sel_hi:[0,1,1]
	v_pk_fma_f32 v[36:37], v[198:199], v[194:195], v[36:37] op_sel:[1,0,0]
	v_pk_fma_f32 v[20:21], v[200:201], v[194:195], v[20:21] op_sel_hi:[0,1,1]
	v_pk_fma_f32 v[12:13], v[200:201], v[194:195], v[12:13] op_sel:[1,0,0]
	v_pk_fma_f32 v[58:59], v[198:199], v[196:197], v[58:59] op_sel_hi:[0,1,1]
	v_pk_fma_f32 v[38:39], v[198:199], v[196:197], v[38:39] op_sel:[1,0,0]
	v_pk_fma_f32 v[22:23], v[200:201], v[196:197], v[22:23] op_sel_hi:[0,1,1]
	v_pk_fma_f32 v[14:15], v[200:201], v[196:197], v[14:15] op_sel:[1,0,0]
	s_waitcnt lgkmcnt(4)
	v_pk_mul_f32 v[202:203], v[72:73], v[92:93]
	v_pk_mul_f32 v[204:205], v[74:75], v[94:95]
	v_pk_mul_f32 v[206:207], v[60:61], v[92:93]
	v_pk_mul_f32 v[208:209], v[62:63], v[94:95]
	v_pk_mul_f32 v[210:211], v[48:49], v[92:93]
	v_pk_mul_f32 v[212:213], v[50:51], v[94:95]
	v_pk_mul_f32 v[214:215], v[32:33], v[92:93]
	v_pk_mul_f32 v[216:217], v[34:35], v[94:95]
	v_pk_fma_f32 v[202:203], v[68:69], v[96:97], v[202:203]
	v_pk_fma_f32 v[204:205], v[70:71], v[98:99], v[204:205]
	v_pk_fma_f32 v[206:207], v[52:53], v[96:97], v[206:207]
	v_pk_fma_f32 v[208:209], v[54:55], v[98:99], v[208:209]
	v_pk_fma_f32 v[210:211], v[40:41], v[96:97], v[210:211]
	v_pk_fma_f32 v[212:213], v[42:43], v[98:99], v[212:213]
	v_pk_fma_f32 v[214:215], v[24:25], v[96:97], v[214:215]
	v_pk_fma_f32 v[216:217], v[26:27], v[98:99], v[216:217]
	v_pk_fma_f32 v[202:203], v[64:65], v[100:101], v[202:203]
	v_pk_fma_f32 v[204:205], v[66:67], v[102:103], v[204:205]
	v_pk_fma_f32 v[206:207], v[44:45], v[100:101], v[206:207]
	v_pk_fma_f32 v[208:209], v[46:47], v[102:103], v[208:209]
	v_pk_fma_f32 v[210:211], v[28:29], v[100:101], v[210:211]
	v_pk_fma_f32 v[212:213], v[30:31], v[102:103], v[212:213]
	v_pk_fma_f32 v[214:215], v[16:17], v[100:101], v[214:215]
	v_pk_fma_f32 v[216:217], v[18:19], v[102:103], v[216:217]
	v_pk_fma_f32 v[202:203], v[56:57], v[104:105], v[202:203]
	v_pk_fma_f32 v[204:205], v[58:59], v[106:107], v[204:205]
	v_pk_fma_f32 v[206:207], v[36:37], v[104:105], v[206:207]
	v_pk_fma_f32 v[208:209], v[38:39], v[106:107], v[208:209]
	v_pk_fma_f32 v[210:211], v[20:21], v[104:105], v[210:211]
	v_pk_fma_f32 v[212:213], v[22:23], v[106:107], v[212:213]
	v_pk_fma_f32 v[214:215], v[12:13], v[104:105], v[214:215]
	v_pk_fma_f32 v[216:217], v[14:15], v[106:107], v[216:217]
	v_pk_add_f32 v[202:203], v[202:203], v[204:205]
	v_pk_add_f32 v[206:207], v[206:207], v[208:209]
	v_pk_add_f32 v[210:211], v[210:211], v[212:213]
	v_pk_add_f32 v[214:215], v[214:215], v[216:217]
	ds_read_b128 v[92:95], v219 offset:256
	v_add_f32_e32 v202, v202, v203
	v_add_f32_e32 v206, v206, v207
	v_add_f32_e32 v210, v210, v211
	v_add_f32_e32 v214, v214, v215
	ds_read_b128 v[96:99], v219 offset:272
	v_add_f32_dpp v202, v202, v202 quad_perm:[1,0,3,2] row_mask:0xf bank_mask:0xf bound_ctrl:1
	v_add_f32_dpp v206, v206, v206 quad_perm:[1,0,3,2] row_mask:0xf bank_mask:0xf bound_ctrl:1
	v_add_f32_dpp v210, v210, v210 quad_perm:[1,0,3,2] row_mask:0xf bank_mask:0xf bound_ctrl:1
	v_add_f32_dpp v214, v214, v214 quad_perm:[1,0,3,2] row_mask:0xf bank_mask:0xf bound_ctrl:1
	ds_read_b128 v[100:103], v219 offset:288
	v_add_f32_dpp v202, v202, v202 quad_perm:[2,3,0,1] row_mask:0xf bank_mask:0xf bound_ctrl:1
	v_add_f32_dpp v206, v206, v206 quad_perm:[2,3,0,1] row_mask:0xf bank_mask:0xf bound_ctrl:1
	v_add_f32_dpp v210, v210, v210 quad_perm:[2,3,0,1] row_mask:0xf bank_mask:0xf bound_ctrl:1
	v_add_f32_dpp v214, v214, v214 quad_perm:[2,3,0,1] row_mask:0xf bank_mask:0xf bound_ctrl:1
	ds_read_b128 v[104:107], v219 offset:304
	ds_read_b128 v[108:111], v219 offset:512
	v_cvt_pk_bf16_f32 v240, v202, v206
	v_cvt_pk_bf16_f32 v241, v210, v214
	ds_read_b128 v[170:173], v219 offset:528
	ds_read_b128 v[174:177], v219 offset:544
	s_mov_b64 exec, s[6:7]
	global_store_dwordx2 v[238:239], v[240:241], off
	s_mov_b64 exec, -1
	ds_read_b128 v[178:181], v219 offset:560
	ds_read_b128 v[198:201], v223 offset:1280
	v_lshl_add_u64 v[238:239], v[238:239], 0, s[80:81]
	s_waitcnt lgkmcnt(9)
	v_pk_mul_f32 v[202:203], v[72:73], v[76:77]
	v_pk_mul_f32 v[204:205], v[74:75], v[78:79]
	v_pk_mul_f32 v[206:207], v[60:61], v[76:77]
	v_pk_mul_f32 v[208:209], v[62:63], v[78:79]
	v_pk_mul_f32 v[210:211], v[48:49], v[76:77]
	v_pk_mul_f32 v[212:213], v[50:51], v[78:79]
	v_pk_mul_f32 v[214:215], v[32:33], v[76:77]
	v_pk_mul_f32 v[216:217], v[34:35], v[78:79]
	v_pk_fma_f32 v[202:203], v[68:69], v[80:81], v[202:203]
	v_pk_fma_f32 v[204:205], v[70:71], v[82:83], v[204:205]
	v_pk_fma_f32 v[206:207], v[52:53], v[80:81], v[206:207]
	v_pk_fma_f32 v[208:209], v[54:55], v[82:83], v[208:209]
	v_pk_fma_f32 v[210:211], v[40:41], v[80:81], v[210:211]
	v_pk_fma_f32 v[212:213], v[42:43], v[82:83], v[212:213]
	v_pk_fma_f32 v[214:215], v[24:25], v[80:81], v[214:215]
	v_pk_fma_f32 v[216:217], v[26:27], v[82:83], v[216:217]
	v_pk_fma_f32 v[202:203], v[64:65], v[84:85], v[202:203]
	v_pk_fma_f32 v[204:205], v[66:67], v[86:87], v[204:205]
	v_pk_fma_f32 v[206:207], v[44:45], v[84:85], v[206:207]
	v_pk_fma_f32 v[208:209], v[46:47], v[86:87], v[208:209]
	v_pk_fma_f32 v[210:211], v[28:29], v[84:85], v[210:211]
	v_pk_fma_f32 v[212:213], v[30:31], v[86:87], v[212:213]
	v_pk_fma_f32 v[214:215], v[16:17], v[84:85], v[214:215]
	v_pk_fma_f32 v[216:217], v[18:19], v[86:87], v[216:217]
	v_pk_fma_f32 v[202:203], v[56:57], v[88:89], v[202:203]
	v_pk_fma_f32 v[204:205], v[58:59], v[90:91], v[204:205]
	v_pk_fma_f32 v[206:207], v[36:37], v[88:89], v[206:207]
	v_pk_fma_f32 v[208:209], v[38:39], v[90:91], v[208:209]
	v_pk_fma_f32 v[210:211], v[20:21], v[88:89], v[210:211]
	v_pk_fma_f32 v[212:213], v[22:23], v[90:91], v[212:213]
	v_pk_fma_f32 v[214:215], v[12:13], v[88:89], v[214:215]
	v_pk_fma_f32 v[216:217], v[14:15], v[90:91], v[216:217]
	s_waitcnt lgkmcnt(1)
	v_pk_add_f32 v[202:203], v[202:203], v[204:205]
	v_pk_add_f32 v[206:207], v[206:207], v[208:209]
	v_pk_add_f32 v[210:211], v[210:211], v[212:213]
	v_pk_add_f32 v[214:215], v[214:215], v[216:217]
	ds_read_b128 v[182:185], v219 offset:768
	v_add_f32_e32 v202, v202, v203
	v_add_f32_e32 v206, v206, v207
	v_add_f32_e32 v210, v210, v211
	v_add_f32_e32 v214, v214, v215
	ds_read_b128 v[186:189], v219 offset:784
	v_add_f32_dpp v202, v202, v202 quad_perm:[1,0,3,2] row_mask:0xf bank_mask:0xf bound_ctrl:1
	v_add_f32_dpp v206, v206, v206 quad_perm:[1,0,3,2] row_mask:0xf bank_mask:0xf bound_ctrl:1
	v_add_f32_dpp v210, v210, v210 quad_perm:[1,0,3,2] row_mask:0xf bank_mask:0xf bound_ctrl:1
	v_add_f32_dpp v214, v214, v214 quad_perm:[1,0,3,2] row_mask:0xf bank_mask:0xf bound_ctrl:1
	ds_read_b128 v[190:193], v219 offset:800
	v_add_f32_dpp v202, v202, v202 quad_perm:[2,3,0,1] row_mask:0xf bank_mask:0xf bound_ctrl:1
	v_add_f32_dpp v206, v206, v206 quad_perm:[2,3,0,1] row_mask:0xf bank_mask:0xf bound_ctrl:1
	v_add_f32_dpp v210, v210, v210 quad_perm:[2,3,0,1] row_mask:0xf bank_mask:0xf bound_ctrl:1
	v_add_f32_dpp v214, v214, v214 quad_perm:[2,3,0,1] row_mask:0xf bank_mask:0xf bound_ctrl:1
	ds_read_b128 v[194:197], v219 offset:816
	v_pk_mul_f32 v[204:205], v[108:109], v[202:203] op_sel_hi:[1,0]
	v_pk_mul_f32 v[208:209], v[108:109], v[206:207] op_sel_hi:[1,0]
	v_pk_mul_f32 v[212:213], v[108:109], v[210:211] op_sel_hi:[1,0]
	v_pk_mul_f32 v[108:109], v[108:109], v[214:215] op_sel_hi:[1,0]
	v_pk_fma_f32 v[72:73], v[72:73], v[92:93], v[204:205]
	v_pk_fma_f32 v[60:61], v[60:61], v[92:93], v[208:209]
	v_pk_fma_f32 v[48:49], v[48:49], v[92:93], v[212:213]
	v_pk_fma_f32 v[32:33], v[32:33], v[92:93], v[108:109]
	v_pk_mul_f32 v[216:217], v[110:111], v[202:203] op_sel_hi:[1,0]
	v_pk_mul_f32 v[242:243], v[110:111], v[206:207] op_sel_hi:[1,0]
	v_pk_mul_f32 v[244:245], v[110:111], v[210:211] op_sel_hi:[1,0]
	v_pk_mul_f32 v[110:111], v[110:111], v[214:215] op_sel_hi:[1,0]
	v_pk_fma_f32 v[74:75], v[74:75], v[94:95], v[216:217]
	v_pk_fma_f32 v[62:63], v[62:63], v[94:95], v[242:243]
	v_pk_fma_f32 v[50:51], v[50:51], v[94:95], v[244:245]
	v_pk_fma_f32 v[34:35], v[34:35], v[94:95], v[110:111]
	v_pk_mul_f32 v[204:205], v[170:171], v[202:203] op_sel_hi:[1,0]
	v_pk_mul_f32 v[208:209], v[170:171], v[206:207] op_sel_hi:[1,0]
	v_pk_mul_f32 v[212:213], v[170:171], v[210:211] op_sel_hi:[1,0]
	v_pk_mul_f32 v[170:171], v[170:171], v[214:215] op_sel_hi:[1,0]
	v_pk_fma_f32 v[68:69], v[68:69], v[96:97], v[204:205]
	v_pk_fma_f32 v[52:53], v[52:53], v[96:97], v[208:209]
	v_pk_fma_f32 v[40:41], v[40:41], v[96:97], v[212:213]
	v_pk_fma_f32 v[24:25], v[24:25], v[96:97], v[170:171]
	v_pk_mul_f32 v[216:217], v[172:173], v[202:203] op_sel_hi:[1,0]
	v_pk_mul_f32 v[242:243], v[172:173], v[206:207] op_sel_hi:[1,0]
	v_pk_mul_f32 v[244:245], v[172:173], v[210:211] op_sel_hi:[1,0]
	v_pk_mul_f32 v[172:173], v[172:173], v[214:215] op_sel_hi:[1,0]
	v_pk_fma_f32 v[70:71], v[70:71], v[98:99], v[216:217]
	v_pk_fma_f32 v[54:55], v[54:55], v[98:99], v[242:243]
	v_pk_fma_f32 v[42:43], v[42:43], v[98:99], v[244:245]
	v_pk_fma_f32 v[26:27], v[26:27], v[98:99], v[172:173]
	v_pk_mul_f32 v[204:205], v[174:175], v[202:203] op_sel_hi:[1,0]
	v_pk_mul_f32 v[208:209], v[174:175], v[206:207] op_sel_hi:[1,0]
	v_pk_mul_f32 v[212:213], v[174:175], v[210:211] op_sel_hi:[1,0]
	v_pk_mul_f32 v[174:175], v[174:175], v[214:215] op_sel_hi:[1,0]
	v_pk_fma_f32 v[64:65], v[64:65], v[100:101], v[204:205]
	v_pk_fma_f32 v[44:45], v[44:45], v[100:101], v[208:209]
	v_pk_fma_f32 v[28:29], v[28:29], v[100:101], v[212:213]
	v_pk_fma_f32 v[16:17], v[16:17], v[100:101], v[174:175]
	v_pk_mul_f32 v[216:217], v[176:177], v[202:203] op_sel_hi:[1,0]
	v_pk_mul_f32 v[242:243], v[176:177], v[206:207] op_sel_hi:[1,0]
	v_pk_mul_f32 v[244:245], v[176:177], v[210:211] op_sel_hi:[1,0]
	v_pk_mul_f32 v[176:177], v[176:177], v[214:215] op_sel_hi:[1,0]
	v_pk_fma_f32 v[66:67], v[66:67], v[102:103], v[216:217]
	v_pk_fma_f32 v[46:47], v[46:47], v[102:103], v[242:243]
	v_pk_fma_f32 v[30:31], v[30:31], v[102:103], v[244:245]
	v_pk_fma_f32 v[18:19], v[18:19], v[102:103], v[176:177]
	v_pk_mul_f32 v[204:205], v[178:179], v[202:203] op_sel_hi:[1,0]
	v_pk_mul_f32 v[208:209], v[178:179], v[206:207] op_sel_hi:[1,0]
	v_pk_mul_f32 v[212:213], v[178:179], v[210:211] op_sel_hi:[1,0]
	v_pk_mul_f32 v[178:179], v[178:179], v[214:215] op_sel_hi:[1,0]
	v_pk_fma_f32 v[56:57], v[56:57], v[104:105], v[204:205]
	v_pk_fma_f32 v[36:37], v[36:37], v[104:105], v[208:209]
	v_pk_fma_f32 v[20:21], v[20:21], v[104:105], v[212:213]
	v_pk_fma_f32 v[12:13], v[12:13], v[104:105], v[178:179]
	v_pk_mul_f32 v[216:217], v[180:181], v[202:203] op_sel_hi:[1,0]
	v_pk_mul_f32 v[242:243], v[180:181], v[206:207] op_sel_hi:[1,0]
	v_pk_mul_f32 v[244:245], v[180:181], v[210:211] op_sel_hi:[1,0]
	v_pk_mul_f32 v[180:181], v[180:181], v[214:215] op_sel_hi:[1,0]
	v_pk_fma_f32 v[58:59], v[58:59], v[106:107], v[216:217]
	v_pk_fma_f32 v[38:39], v[38:39], v[106:107], v[242:243]
	v_pk_fma_f32 v[22:23], v[22:23], v[106:107], v[244:245]
	v_pk_fma_f32 v[14:15], v[14:15], v[106:107], v[180:181]
	ds_read_b128 v[92:95], v219 offset:1024
	ds_read_b128 v[96:99], v219 offset:1040
	ds_read_b128 v[100:103], v219 offset:1056
	ds_read_b128 v[104:107], v219 offset:1072
	ds_read_b128 v[76:79], v220 offset:0
	ds_read_b128 v[80:83], v220 offset:16
	ds_read_b128 v[84:87], v220 offset:32
	ds_read_b128 v[88:91], v220 offset:48
	s_waitcnt lgkmcnt(8)
	v_pk_fma_f32 v[72:73], v[198:199], v[182:183], v[72:73] op_sel_hi:[0,1,1]
	v_pk_fma_f32 v[60:61], v[198:199], v[182:183], v[60:61] op_sel:[1,0,0]
	v_pk_fma_f32 v[48:49], v[200:201], v[182:183], v[48:49] op_sel_hi:[0,1,1]
	v_pk_fma_f32 v[32:33], v[200:201], v[182:183], v[32:33] op_sel:[1,0,0]
	v_pk_fma_f32 v[74:75], v[198:199], v[184:185], v[74:75] op_sel_hi:[0,1,1]
	v_pk_fma_f32 v[62:63], v[198:199], v[184:185], v[62:63] op_sel:[1,0,0]
	v_pk_fma_f32 v[50:51], v[200:201], v[184:185], v[50:51] op_sel_hi:[0,1,1]
	v_pk_fma_f32 v[34:35], v[200:201], v[184:185], v[34:35] op_sel:[1,0,0]
	v_pk_fma_f32 v[68:69], v[198:199], v[186:187], v[68:69] op_sel_hi:[0,1,1]
	v_pk_fma_f32 v[52:53], v[198:199], v[186:187], v[52:53] op_sel:[1,0,0]
	v_pk_fma_f32 v[40:41], v[200:201], v[186:187], v[40:41] op_sel_hi:[0,1,1]
	v_pk_fma_f32 v[24:25], v[200:201], v[186:187], v[24:25] op_sel:[1,0,0]
	v_pk_fma_f32 v[70:71], v[198:199], v[188:189], v[70:71] op_sel_hi:[0,1,1]
	v_pk_fma_f32 v[54:55], v[198:199], v[188:189], v[54:55] op_sel:[1,0,0]
	v_pk_fma_f32 v[42:43], v[200:201], v[188:189], v[42:43] op_sel_hi:[0,1,1]
	v_pk_fma_f32 v[26:27], v[200:201], v[188:189], v[26:27] op_sel:[1,0,0]
	v_pk_fma_f32 v[64:65], v[198:199], v[190:191], v[64:65] op_sel_hi:[0,1,1]
	v_pk_fma_f32 v[44:45], v[198:199], v[190:191], v[44:45] op_sel:[1,0,0]
	v_pk_fma_f32 v[28:29], v[200:201], v[190:191], v[28:29] op_sel_hi:[0,1,1]
	v_pk_fma_f32 v[16:17], v[200:201], v[190:191], v[16:17] op_sel:[1,0,0]
	v_pk_fma_f32 v[66:67], v[198:199], v[192:193], v[66:67] op_sel_hi:[0,1,1]
	v_pk_fma_f32 v[46:47], v[198:199], v[192:193], v[46:47] op_sel:[1,0,0]
	v_pk_fma_f32 v[30:31], v[200:201], v[192:193], v[30:31] op_sel_hi:[0,1,1]
	v_pk_fma_f32 v[18:19], v[200:201], v[192:193], v[18:19] op_sel:[1,0,0]
	v_pk_fma_f32 v[56:57], v[198:199], v[194:195], v[56:57] op_sel_hi:[0,1,1]
	v_pk_fma_f32 v[36:37], v[198:199], v[194:195], v[36:37] op_sel:[1,0,0]
	v_pk_fma_f32 v[20:21], v[200:201], v[194:195], v[20:21] op_sel_hi:[0,1,1]
	v_pk_fma_f32 v[12:13], v[200:201], v[194:195], v[12:13] op_sel:[1,0,0]
	v_pk_fma_f32 v[58:59], v[198:199], v[196:197], v[58:59] op_sel_hi:[0,1,1]
	v_pk_fma_f32 v[38:39], v[198:199], v[196:197], v[38:39] op_sel:[1,0,0]
	v_pk_fma_f32 v[22:23], v[200:201], v[196:197], v[22:23] op_sel_hi:[0,1,1]
	v_pk_fma_f32 v[14:15], v[200:201], v[196:197], v[14:15] op_sel:[1,0,0]
	s_waitcnt lgkmcnt(4)
	v_pk_mul_f32 v[202:203], v[72:73], v[92:93]
	v_pk_mul_f32 v[204:205], v[74:75], v[94:95]
	v_pk_mul_f32 v[206:207], v[60:61], v[92:93]
	v_pk_mul_f32 v[208:209], v[62:63], v[94:95]
	v_pk_mul_f32 v[210:211], v[48:49], v[92:93]
	v_pk_mul_f32 v[212:213], v[50:51], v[94:95]
	v_pk_mul_f32 v[214:215], v[32:33], v[92:93]
	v_pk_mul_f32 v[216:217], v[34:35], v[94:95]
	v_pk_fma_f32 v[202:203], v[68:69], v[96:97], v[202:203]
	v_pk_fma_f32 v[204:205], v[70:71], v[98:99], v[204:205]
	v_pk_fma_f32 v[206:207], v[52:53], v[96:97], v[206:207]
	v_pk_fma_f32 v[208:209], v[54:55], v[98:99], v[208:209]
	v_pk_fma_f32 v[210:211], v[40:41], v[96:97], v[210:211]
	v_pk_fma_f32 v[212:213], v[42:43], v[98:99], v[212:213]
	v_pk_fma_f32 v[214:215], v[24:25], v[96:97], v[214:215]
	v_pk_fma_f32 v[216:217], v[26:27], v[98:99], v[216:217]
	v_pk_fma_f32 v[202:203], v[64:65], v[100:101], v[202:203]
	v_pk_fma_f32 v[204:205], v[66:67], v[102:103], v[204:205]
	v_pk_fma_f32 v[206:207], v[44:45], v[100:101], v[206:207]
	v_pk_fma_f32 v[208:209], v[46:47], v[102:103], v[208:209]
	v_pk_fma_f32 v[210:211], v[28:29], v[100:101], v[210:211]
	v_pk_fma_f32 v[212:213], v[30:31], v[102:103], v[212:213]
	v_pk_fma_f32 v[214:215], v[16:17], v[100:101], v[214:215]
	v_pk_fma_f32 v[216:217], v[18:19], v[102:103], v[216:217]
	v_pk_fma_f32 v[202:203], v[56:57], v[104:105], v[202:203]
	v_pk_fma_f32 v[204:205], v[58:59], v[106:107], v[204:205]
	v_pk_fma_f32 v[206:207], v[36:37], v[104:105], v[206:207]
	v_pk_fma_f32 v[208:209], v[38:39], v[106:107], v[208:209]
	v_pk_fma_f32 v[210:211], v[20:21], v[104:105], v[210:211]
	v_pk_fma_f32 v[212:213], v[22:23], v[106:107], v[212:213]
	v_pk_fma_f32 v[214:215], v[12:13], v[104:105], v[214:215]
	v_pk_fma_f32 v[216:217], v[14:15], v[106:107], v[216:217]
	v_pk_add_f32 v[202:203], v[202:203], v[204:205]
	v_pk_add_f32 v[206:207], v[206:207], v[208:209]
	v_pk_add_f32 v[210:211], v[210:211], v[212:213]
	v_pk_add_f32 v[214:215], v[214:215], v[216:217]
	ds_read_b128 v[92:95], v220 offset:256
	v_add_f32_e32 v202, v202, v203
	v_add_f32_e32 v206, v206, v207
	v_add_f32_e32 v210, v210, v211
	v_add_f32_e32 v214, v214, v215
	ds_read_b128 v[96:99], v220 offset:272
	v_add_f32_dpp v202, v202, v202 quad_perm:[1,0,3,2] row_mask:0xf bank_mask:0xf bound_ctrl:1
	v_add_f32_dpp v206, v206, v206 quad_perm:[1,0,3,2] row_mask:0xf bank_mask:0xf bound_ctrl:1
	v_add_f32_dpp v210, v210, v210 quad_perm:[1,0,3,2] row_mask:0xf bank_mask:0xf bound_ctrl:1
	v_add_f32_dpp v214, v214, v214 quad_perm:[1,0,3,2] row_mask:0xf bank_mask:0xf bound_ctrl:1
	ds_read_b128 v[100:103], v220 offset:288
	v_add_f32_dpp v202, v202, v202 quad_perm:[2,3,0,1] row_mask:0xf bank_mask:0xf bound_ctrl:1
	v_add_f32_dpp v206, v206, v206 quad_perm:[2,3,0,1] row_mask:0xf bank_mask:0xf bound_ctrl:1
	v_add_f32_dpp v210, v210, v210 quad_perm:[2,3,0,1] row_mask:0xf bank_mask:0xf bound_ctrl:1
	v_add_f32_dpp v214, v214, v214 quad_perm:[2,3,0,1] row_mask:0xf bank_mask:0xf bound_ctrl:1
	ds_read_b128 v[104:107], v220 offset:304
	ds_read_b128 v[108:111], v220 offset:512
	v_cvt_pk_bf16_f32 v240, v202, v206
	v_cvt_pk_bf16_f32 v241, v210, v214
	ds_read_b128 v[170:173], v220 offset:528
	ds_read_b128 v[174:177], v220 offset:544
	s_mov_b64 exec, s[6:7]
	global_store_dwordx2 v[238:239], v[240:241], off
	s_mov_b64 exec, -1
	ds_read_b128 v[178:181], v220 offset:560
	ds_read_b128 v[198:201], v236 offset:1280
	v_lshl_add_u64 v[238:239], v[238:239], 0, s[80:81]
	s_waitcnt lgkmcnt(9)
	v_pk_mul_f32 v[202:203], v[72:73], v[76:77]
	v_pk_mul_f32 v[204:205], v[74:75], v[78:79]
	v_pk_mul_f32 v[206:207], v[60:61], v[76:77]
	v_pk_mul_f32 v[208:209], v[62:63], v[78:79]
	v_pk_mul_f32 v[210:211], v[48:49], v[76:77]
	v_pk_mul_f32 v[212:213], v[50:51], v[78:79]
	v_pk_mul_f32 v[214:215], v[32:33], v[76:77]
	v_pk_mul_f32 v[216:217], v[34:35], v[78:79]
	v_pk_fma_f32 v[202:203], v[68:69], v[80:81], v[202:203]
	v_pk_fma_f32 v[204:205], v[70:71], v[82:83], v[204:205]
	v_pk_fma_f32 v[206:207], v[52:53], v[80:81], v[206:207]
	v_pk_fma_f32 v[208:209], v[54:55], v[82:83], v[208:209]
	v_pk_fma_f32 v[210:211], v[40:41], v[80:81], v[210:211]
	v_pk_fma_f32 v[212:213], v[42:43], v[82:83], v[212:213]
	v_pk_fma_f32 v[214:215], v[24:25], v[80:81], v[214:215]
	v_pk_fma_f32 v[216:217], v[26:27], v[82:83], v[216:217]
	v_pk_fma_f32 v[202:203], v[64:65], v[84:85], v[202:203]
	v_pk_fma_f32 v[204:205], v[66:67], v[86:87], v[204:205]
	v_pk_fma_f32 v[206:207], v[44:45], v[84:85], v[206:207]
	v_pk_fma_f32 v[208:209], v[46:47], v[86:87], v[208:209]
	v_pk_fma_f32 v[210:211], v[28:29], v[84:85], v[210:211]
	v_pk_fma_f32 v[212:213], v[30:31], v[86:87], v[212:213]
	v_pk_fma_f32 v[214:215], v[16:17], v[84:85], v[214:215]
	v_pk_fma_f32 v[216:217], v[18:19], v[86:87], v[216:217]
	v_pk_fma_f32 v[202:203], v[56:57], v[88:89], v[202:203]
	v_pk_fma_f32 v[204:205], v[58:59], v[90:91], v[204:205]
	v_pk_fma_f32 v[206:207], v[36:37], v[88:89], v[206:207]
	v_pk_fma_f32 v[208:209], v[38:39], v[90:91], v[208:209]
	v_pk_fma_f32 v[210:211], v[20:21], v[88:89], v[210:211]
	v_pk_fma_f32 v[212:213], v[22:23], v[90:91], v[212:213]
	v_pk_fma_f32 v[214:215], v[12:13], v[88:89], v[214:215]
	v_pk_fma_f32 v[216:217], v[14:15], v[90:91], v[216:217]
	s_waitcnt lgkmcnt(1)
	v_pk_add_f32 v[202:203], v[202:203], v[204:205]
	v_pk_add_f32 v[206:207], v[206:207], v[208:209]
	v_pk_add_f32 v[210:211], v[210:211], v[212:213]
	v_pk_add_f32 v[214:215], v[214:215], v[216:217]
	ds_read_b128 v[182:185], v220 offset:768
	v_add_f32_e32 v202, v202, v203
	v_add_f32_e32 v206, v206, v207
	v_add_f32_e32 v210, v210, v211
	v_add_f32_e32 v214, v214, v215
	ds_read_b128 v[186:189], v220 offset:784
	v_add_f32_dpp v202, v202, v202 quad_perm:[1,0,3,2] row_mask:0xf bank_mask:0xf bound_ctrl:1
	v_add_f32_dpp v206, v206, v206 quad_perm:[1,0,3,2] row_mask:0xf bank_mask:0xf bound_ctrl:1
	v_add_f32_dpp v210, v210, v210 quad_perm:[1,0,3,2] row_mask:0xf bank_mask:0xf bound_ctrl:1
	v_add_f32_dpp v214, v214, v214 quad_perm:[1,0,3,2] row_mask:0xf bank_mask:0xf bound_ctrl:1
	ds_read_b128 v[190:193], v220 offset:800
	v_add_f32_dpp v202, v202, v202 quad_perm:[2,3,0,1] row_mask:0xf bank_mask:0xf bound_ctrl:1
	v_add_f32_dpp v206, v206, v206 quad_perm:[2,3,0,1] row_mask:0xf bank_mask:0xf bound_ctrl:1
	v_add_f32_dpp v210, v210, v210 quad_perm:[2,3,0,1] row_mask:0xf bank_mask:0xf bound_ctrl:1
	v_add_f32_dpp v214, v214, v214 quad_perm:[2,3,0,1] row_mask:0xf bank_mask:0xf bound_ctrl:1
	ds_read_b128 v[194:197], v220 offset:816
	v_pk_mul_f32 v[204:205], v[108:109], v[202:203] op_sel_hi:[1,0]
	v_pk_mul_f32 v[208:209], v[108:109], v[206:207] op_sel_hi:[1,0]
	v_pk_mul_f32 v[212:213], v[108:109], v[210:211] op_sel_hi:[1,0]
	v_pk_mul_f32 v[108:109], v[108:109], v[214:215] op_sel_hi:[1,0]
	v_pk_fma_f32 v[72:73], v[72:73], v[92:93], v[204:205]
	v_pk_fma_f32 v[60:61], v[60:61], v[92:93], v[208:209]
	v_pk_fma_f32 v[48:49], v[48:49], v[92:93], v[212:213]
	v_pk_fma_f32 v[32:33], v[32:33], v[92:93], v[108:109]
	v_pk_mul_f32 v[216:217], v[110:111], v[202:203] op_sel_hi:[1,0]
	v_pk_mul_f32 v[242:243], v[110:111], v[206:207] op_sel_hi:[1,0]
	v_pk_mul_f32 v[244:245], v[110:111], v[210:211] op_sel_hi:[1,0]
	v_pk_mul_f32 v[110:111], v[110:111], v[214:215] op_sel_hi:[1,0]
	v_pk_fma_f32 v[74:75], v[74:75], v[94:95], v[216:217]
	v_pk_fma_f32 v[62:63], v[62:63], v[94:95], v[242:243]
	v_pk_fma_f32 v[50:51], v[50:51], v[94:95], v[244:245]
	v_pk_fma_f32 v[34:35], v[34:35], v[94:95], v[110:111]
	v_pk_mul_f32 v[204:205], v[170:171], v[202:203] op_sel_hi:[1,0]
	v_pk_mul_f32 v[208:209], v[170:171], v[206:207] op_sel_hi:[1,0]
	v_pk_mul_f32 v[212:213], v[170:171], v[210:211] op_sel_hi:[1,0]
	v_pk_mul_f32 v[170:171], v[170:171], v[214:215] op_sel_hi:[1,0]
	v_pk_fma_f32 v[68:69], v[68:69], v[96:97], v[204:205]
	v_pk_fma_f32 v[52:53], v[52:53], v[96:97], v[208:209]
	v_pk_fma_f32 v[40:41], v[40:41], v[96:97], v[212:213]
	v_pk_fma_f32 v[24:25], v[24:25], v[96:97], v[170:171]
	v_pk_mul_f32 v[216:217], v[172:173], v[202:203] op_sel_hi:[1,0]
	v_pk_mul_f32 v[242:243], v[172:173], v[206:207] op_sel_hi:[1,0]
	v_pk_mul_f32 v[244:245], v[172:173], v[210:211] op_sel_hi:[1,0]
	v_pk_mul_f32 v[172:173], v[172:173], v[214:215] op_sel_hi:[1,0]
	v_pk_fma_f32 v[70:71], v[70:71], v[98:99], v[216:217]
	v_pk_fma_f32 v[54:55], v[54:55], v[98:99], v[242:243]
	v_pk_fma_f32 v[42:43], v[42:43], v[98:99], v[244:245]
	v_pk_fma_f32 v[26:27], v[26:27], v[98:99], v[172:173]
	v_pk_mul_f32 v[204:205], v[174:175], v[202:203] op_sel_hi:[1,0]
	v_pk_mul_f32 v[208:209], v[174:175], v[206:207] op_sel_hi:[1,0]
	v_pk_mul_f32 v[212:213], v[174:175], v[210:211] op_sel_hi:[1,0]
	v_pk_mul_f32 v[174:175], v[174:175], v[214:215] op_sel_hi:[1,0]
	v_pk_fma_f32 v[64:65], v[64:65], v[100:101], v[204:205]
	v_pk_fma_f32 v[44:45], v[44:45], v[100:101], v[208:209]
	v_pk_fma_f32 v[28:29], v[28:29], v[100:101], v[212:213]
	v_pk_fma_f32 v[16:17], v[16:17], v[100:101], v[174:175]
	v_pk_mul_f32 v[216:217], v[176:177], v[202:203] op_sel_hi:[1,0]
	v_pk_mul_f32 v[242:243], v[176:177], v[206:207] op_sel_hi:[1,0]
	v_pk_mul_f32 v[244:245], v[176:177], v[210:211] op_sel_hi:[1,0]
	v_pk_mul_f32 v[176:177], v[176:177], v[214:215] op_sel_hi:[1,0]
	v_pk_fma_f32 v[66:67], v[66:67], v[102:103], v[216:217]
	v_pk_fma_f32 v[46:47], v[46:47], v[102:103], v[242:243]
	v_pk_fma_f32 v[30:31], v[30:31], v[102:103], v[244:245]
	v_pk_fma_f32 v[18:19], v[18:19], v[102:103], v[176:177]
	v_pk_mul_f32 v[204:205], v[178:179], v[202:203] op_sel_hi:[1,0]
	v_pk_mul_f32 v[208:209], v[178:179], v[206:207] op_sel_hi:[1,0]
	v_pk_mul_f32 v[212:213], v[178:179], v[210:211] op_sel_hi:[1,0]
	v_pk_mul_f32 v[178:179], v[178:179], v[214:215] op_sel_hi:[1,0]
	v_pk_fma_f32 v[56:57], v[56:57], v[104:105], v[204:205]
	v_pk_fma_f32 v[36:37], v[36:37], v[104:105], v[208:209]
	v_pk_fma_f32 v[20:21], v[20:21], v[104:105], v[212:213]
	v_pk_fma_f32 v[12:13], v[12:13], v[104:105], v[178:179]
	v_pk_mul_f32 v[216:217], v[180:181], v[202:203] op_sel_hi:[1,0]
	v_pk_mul_f32 v[242:243], v[180:181], v[206:207] op_sel_hi:[1,0]
	v_pk_mul_f32 v[244:245], v[180:181], v[210:211] op_sel_hi:[1,0]
	v_pk_mul_f32 v[180:181], v[180:181], v[214:215] op_sel_hi:[1,0]
	v_pk_fma_f32 v[58:59], v[58:59], v[106:107], v[216:217]
	v_pk_fma_f32 v[38:39], v[38:39], v[106:107], v[242:243]
	v_pk_fma_f32 v[22:23], v[22:23], v[106:107], v[244:245]
	v_pk_fma_f32 v[14:15], v[14:15], v[106:107], v[180:181]
	ds_read_b128 v[92:95], v220 offset:1024
	ds_read_b128 v[96:99], v220 offset:1040
	ds_read_b128 v[100:103], v220 offset:1056
	ds_read_b128 v[104:107], v220 offset:1072
	ds_read_b128 v[76:79], v221 offset:0
	ds_read_b128 v[80:83], v221 offset:16
	ds_read_b128 v[84:87], v221 offset:32
	ds_read_b128 v[88:91], v221 offset:48
	s_waitcnt lgkmcnt(8)
	v_pk_fma_f32 v[72:73], v[198:199], v[182:183], v[72:73] op_sel_hi:[0,1,1]
	v_pk_fma_f32 v[60:61], v[198:199], v[182:183], v[60:61] op_sel:[1,0,0]
	v_pk_fma_f32 v[48:49], v[200:201], v[182:183], v[48:49] op_sel_hi:[0,1,1]
	v_pk_fma_f32 v[32:33], v[200:201], v[182:183], v[32:33] op_sel:[1,0,0]
	v_pk_fma_f32 v[74:75], v[198:199], v[184:185], v[74:75] op_sel_hi:[0,1,1]
	v_pk_fma_f32 v[62:63], v[198:199], v[184:185], v[62:63] op_sel:[1,0,0]
	v_pk_fma_f32 v[50:51], v[200:201], v[184:185], v[50:51] op_sel_hi:[0,1,1]
	v_pk_fma_f32 v[34:35], v[200:201], v[184:185], v[34:35] op_sel:[1,0,0]
	v_pk_fma_f32 v[68:69], v[198:199], v[186:187], v[68:69] op_sel_hi:[0,1,1]
	v_pk_fma_f32 v[52:53], v[198:199], v[186:187], v[52:53] op_sel:[1,0,0]
	v_pk_fma_f32 v[40:41], v[200:201], v[186:187], v[40:41] op_sel_hi:[0,1,1]
	v_pk_fma_f32 v[24:25], v[200:201], v[186:187], v[24:25] op_sel:[1,0,0]
	v_pk_fma_f32 v[70:71], v[198:199], v[188:189], v[70:71] op_sel_hi:[0,1,1]
	v_pk_fma_f32 v[54:55], v[198:199], v[188:189], v[54:55] op_sel:[1,0,0]
	v_pk_fma_f32 v[42:43], v[200:201], v[188:189], v[42:43] op_sel_hi:[0,1,1]
	v_pk_fma_f32 v[26:27], v[200:201], v[188:189], v[26:27] op_sel:[1,0,0]
	v_pk_fma_f32 v[64:65], v[198:199], v[190:191], v[64:65] op_sel_hi:[0,1,1]
	v_pk_fma_f32 v[44:45], v[198:199], v[190:191], v[44:45] op_sel:[1,0,0]
	v_pk_fma_f32 v[28:29], v[200:201], v[190:191], v[28:29] op_sel_hi:[0,1,1]
	v_pk_fma_f32 v[16:17], v[200:201], v[190:191], v[16:17] op_sel:[1,0,0]
	v_pk_fma_f32 v[66:67], v[198:199], v[192:193], v[66:67] op_sel_hi:[0,1,1]
	v_pk_fma_f32 v[46:47], v[198:199], v[192:193], v[46:47] op_sel:[1,0,0]
	v_pk_fma_f32 v[30:31], v[200:201], v[192:193], v[30:31] op_sel_hi:[0,1,1]
	v_pk_fma_f32 v[18:19], v[200:201], v[192:193], v[18:19] op_sel:[1,0,0]
	v_pk_fma_f32 v[56:57], v[198:199], v[194:195], v[56:57] op_sel_hi:[0,1,1]
	v_pk_fma_f32 v[36:37], v[198:199], v[194:195], v[36:37] op_sel:[1,0,0]
	v_pk_fma_f32 v[20:21], v[200:201], v[194:195], v[20:21] op_sel_hi:[0,1,1]
	v_pk_fma_f32 v[12:13], v[200:201], v[194:195], v[12:13] op_sel:[1,0,0]
	v_pk_fma_f32 v[58:59], v[198:199], v[196:197], v[58:59] op_sel_hi:[0,1,1]
	v_pk_fma_f32 v[38:39], v[198:199], v[196:197], v[38:39] op_sel:[1,0,0]
	v_pk_fma_f32 v[22:23], v[200:201], v[196:197], v[22:23] op_sel_hi:[0,1,1]
	v_pk_fma_f32 v[14:15], v[200:201], v[196:197], v[14:15] op_sel:[1,0,0]
	s_waitcnt lgkmcnt(4)
	v_pk_mul_f32 v[202:203], v[72:73], v[92:93]
	v_pk_mul_f32 v[204:205], v[74:75], v[94:95]
	v_pk_mul_f32 v[206:207], v[60:61], v[92:93]
	v_pk_mul_f32 v[208:209], v[62:63], v[94:95]
	v_pk_mul_f32 v[210:211], v[48:49], v[92:93]
	v_pk_mul_f32 v[212:213], v[50:51], v[94:95]
	v_pk_mul_f32 v[214:215], v[32:33], v[92:93]
	v_pk_mul_f32 v[216:217], v[34:35], v[94:95]
	v_pk_fma_f32 v[202:203], v[68:69], v[96:97], v[202:203]
	v_pk_fma_f32 v[204:205], v[70:71], v[98:99], v[204:205]
	v_pk_fma_f32 v[206:207], v[52:53], v[96:97], v[206:207]
	v_pk_fma_f32 v[208:209], v[54:55], v[98:99], v[208:209]
	v_pk_fma_f32 v[210:211], v[40:41], v[96:97], v[210:211]
	v_pk_fma_f32 v[212:213], v[42:43], v[98:99], v[212:213]
	v_pk_fma_f32 v[214:215], v[24:25], v[96:97], v[214:215]
	v_pk_fma_f32 v[216:217], v[26:27], v[98:99], v[216:217]
	v_pk_fma_f32 v[202:203], v[64:65], v[100:101], v[202:203]
	v_pk_fma_f32 v[204:205], v[66:67], v[102:103], v[204:205]
	v_pk_fma_f32 v[206:207], v[44:45], v[100:101], v[206:207]
	v_pk_fma_f32 v[208:209], v[46:47], v[102:103], v[208:209]
	v_pk_fma_f32 v[210:211], v[28:29], v[100:101], v[210:211]
	v_pk_fma_f32 v[212:213], v[30:31], v[102:103], v[212:213]
	v_pk_fma_f32 v[214:215], v[16:17], v[100:101], v[214:215]
	v_pk_fma_f32 v[216:217], v[18:19], v[102:103], v[216:217]
	v_pk_fma_f32 v[202:203], v[56:57], v[104:105], v[202:203]
	v_pk_fma_f32 v[204:205], v[58:59], v[106:107], v[204:205]
	v_pk_fma_f32 v[206:207], v[36:37], v[104:105], v[206:207]
	v_pk_fma_f32 v[208:209], v[38:39], v[106:107], v[208:209]
	v_pk_fma_f32 v[210:211], v[20:21], v[104:105], v[210:211]
	v_pk_fma_f32 v[212:213], v[22:23], v[106:107], v[212:213]
	v_pk_fma_f32 v[214:215], v[12:13], v[104:105], v[214:215]
	v_pk_fma_f32 v[216:217], v[14:15], v[106:107], v[216:217]
	v_pk_add_f32 v[202:203], v[202:203], v[204:205]
	v_pk_add_f32 v[206:207], v[206:207], v[208:209]
	v_pk_add_f32 v[210:211], v[210:211], v[212:213]
	v_pk_add_f32 v[214:215], v[214:215], v[216:217]
	ds_read_b128 v[92:95], v221 offset:256
	v_add_f32_e32 v202, v202, v203
	v_add_f32_e32 v206, v206, v207
	v_add_f32_e32 v210, v210, v211
	v_add_f32_e32 v214, v214, v215
	ds_read_b128 v[96:99], v221 offset:272
	v_add_f32_dpp v202, v202, v202 quad_perm:[1,0,3,2] row_mask:0xf bank_mask:0xf bound_ctrl:1
	v_add_f32_dpp v206, v206, v206 quad_perm:[1,0,3,2] row_mask:0xf bank_mask:0xf bound_ctrl:1
	v_add_f32_dpp v210, v210, v210 quad_perm:[1,0,3,2] row_mask:0xf bank_mask:0xf bound_ctrl:1
	v_add_f32_dpp v214, v214, v214 quad_perm:[1,0,3,2] row_mask:0xf bank_mask:0xf bound_ctrl:1
	ds_read_b128 v[100:103], v221 offset:288
	v_add_f32_dpp v202, v202, v202 quad_perm:[2,3,0,1] row_mask:0xf bank_mask:0xf bound_ctrl:1
	v_add_f32_dpp v206, v206, v206 quad_perm:[2,3,0,1] row_mask:0xf bank_mask:0xf bound_ctrl:1
	v_add_f32_dpp v210, v210, v210 quad_perm:[2,3,0,1] row_mask:0xf bank_mask:0xf bound_ctrl:1
	v_add_f32_dpp v214, v214, v214 quad_perm:[2,3,0,1] row_mask:0xf bank_mask:0xf bound_ctrl:1
	ds_read_b128 v[104:107], v221 offset:304
	ds_read_b128 v[108:111], v221 offset:512
	v_cvt_pk_bf16_f32 v240, v202, v206
	v_cvt_pk_bf16_f32 v241, v210, v214
	ds_read_b128 v[170:173], v221 offset:528
	ds_read_b128 v[174:177], v221 offset:544
	s_mov_b64 exec, s[6:7]
	global_store_dwordx2 v[238:239], v[240:241], off
	s_mov_b64 exec, -1
	ds_read_b128 v[178:181], v221 offset:560
	ds_read_b128 v[198:201], v237 offset:1280
	v_lshl_add_u64 v[238:239], v[238:239], 0, s[80:81]
	s_waitcnt lgkmcnt(9)
	v_pk_mul_f32 v[202:203], v[72:73], v[76:77]
	v_pk_mul_f32 v[204:205], v[74:75], v[78:79]
	v_pk_mul_f32 v[206:207], v[60:61], v[76:77]
	v_pk_mul_f32 v[208:209], v[62:63], v[78:79]
	v_pk_mul_f32 v[210:211], v[48:49], v[76:77]
	v_pk_mul_f32 v[212:213], v[50:51], v[78:79]
	v_pk_mul_f32 v[214:215], v[32:33], v[76:77]
	v_pk_mul_f32 v[216:217], v[34:35], v[78:79]
	v_pk_fma_f32 v[202:203], v[68:69], v[80:81], v[202:203]
	v_pk_fma_f32 v[204:205], v[70:71], v[82:83], v[204:205]
	v_pk_fma_f32 v[206:207], v[52:53], v[80:81], v[206:207]
	v_pk_fma_f32 v[208:209], v[54:55], v[82:83], v[208:209]
	v_pk_fma_f32 v[210:211], v[40:41], v[80:81], v[210:211]
	v_pk_fma_f32 v[212:213], v[42:43], v[82:83], v[212:213]
	v_pk_fma_f32 v[214:215], v[24:25], v[80:81], v[214:215]
	v_pk_fma_f32 v[216:217], v[26:27], v[82:83], v[216:217]
	v_pk_fma_f32 v[202:203], v[64:65], v[84:85], v[202:203]
	v_pk_fma_f32 v[204:205], v[66:67], v[86:87], v[204:205]
	v_pk_fma_f32 v[206:207], v[44:45], v[84:85], v[206:207]
	v_pk_fma_f32 v[208:209], v[46:47], v[86:87], v[208:209]
	v_pk_fma_f32 v[210:211], v[28:29], v[84:85], v[210:211]
	v_pk_fma_f32 v[212:213], v[30:31], v[86:87], v[212:213]
	v_pk_fma_f32 v[214:215], v[16:17], v[84:85], v[214:215]
	v_pk_fma_f32 v[216:217], v[18:19], v[86:87], v[216:217]
	v_pk_fma_f32 v[202:203], v[56:57], v[88:89], v[202:203]
	v_pk_fma_f32 v[204:205], v[58:59], v[90:91], v[204:205]
	v_pk_fma_f32 v[206:207], v[36:37], v[88:89], v[206:207]
	v_pk_fma_f32 v[208:209], v[38:39], v[90:91], v[208:209]
	v_pk_fma_f32 v[210:211], v[20:21], v[88:89], v[210:211]
	v_pk_fma_f32 v[212:213], v[22:23], v[90:91], v[212:213]
	v_pk_fma_f32 v[214:215], v[12:13], v[88:89], v[214:215]
	v_pk_fma_f32 v[216:217], v[14:15], v[90:91], v[216:217]
	s_waitcnt lgkmcnt(1)
	v_pk_add_f32 v[202:203], v[202:203], v[204:205]
	v_pk_add_f32 v[206:207], v[206:207], v[208:209]
	v_pk_add_f32 v[210:211], v[210:211], v[212:213]
	v_pk_add_f32 v[214:215], v[214:215], v[216:217]
	ds_read_b128 v[182:185], v221 offset:768
	v_add_f32_e32 v202, v202, v203
	v_add_f32_e32 v206, v206, v207
	v_add_f32_e32 v210, v210, v211
	v_add_f32_e32 v214, v214, v215
	ds_read_b128 v[186:189], v221 offset:784
	v_add_f32_dpp v202, v202, v202 quad_perm:[1,0,3,2] row_mask:0xf bank_mask:0xf bound_ctrl:1
	v_add_f32_dpp v206, v206, v206 quad_perm:[1,0,3,2] row_mask:0xf bank_mask:0xf bound_ctrl:1
	v_add_f32_dpp v210, v210, v210 quad_perm:[1,0,3,2] row_mask:0xf bank_mask:0xf bound_ctrl:1
	v_add_f32_dpp v214, v214, v214 quad_perm:[1,0,3,2] row_mask:0xf bank_mask:0xf bound_ctrl:1
	ds_read_b128 v[190:193], v221 offset:800
	v_add_f32_dpp v202, v202, v202 quad_perm:[2,3,0,1] row_mask:0xf bank_mask:0xf bound_ctrl:1
	v_add_f32_dpp v206, v206, v206 quad_perm:[2,3,0,1] row_mask:0xf bank_mask:0xf bound_ctrl:1
	v_add_f32_dpp v210, v210, v210 quad_perm:[2,3,0,1] row_mask:0xf bank_mask:0xf bound_ctrl:1
	v_add_f32_dpp v214, v214, v214 quad_perm:[2,3,0,1] row_mask:0xf bank_mask:0xf bound_ctrl:1
	ds_read_b128 v[194:197], v221 offset:816
	v_pk_mul_f32 v[204:205], v[108:109], v[202:203] op_sel_hi:[1,0]
	v_pk_mul_f32 v[208:209], v[108:109], v[206:207] op_sel_hi:[1,0]
	v_pk_mul_f32 v[212:213], v[108:109], v[210:211] op_sel_hi:[1,0]
	v_pk_mul_f32 v[108:109], v[108:109], v[214:215] op_sel_hi:[1,0]
	v_pk_fma_f32 v[72:73], v[72:73], v[92:93], v[204:205]
	v_pk_fma_f32 v[60:61], v[60:61], v[92:93], v[208:209]
	v_pk_fma_f32 v[48:49], v[48:49], v[92:93], v[212:213]
	v_pk_fma_f32 v[32:33], v[32:33], v[92:93], v[108:109]
	v_pk_mul_f32 v[216:217], v[110:111], v[202:203] op_sel_hi:[1,0]
	v_pk_mul_f32 v[242:243], v[110:111], v[206:207] op_sel_hi:[1,0]
	v_pk_mul_f32 v[244:245], v[110:111], v[210:211] op_sel_hi:[1,0]
	v_pk_mul_f32 v[110:111], v[110:111], v[214:215] op_sel_hi:[1,0]
	v_pk_fma_f32 v[74:75], v[74:75], v[94:95], v[216:217]
	v_pk_fma_f32 v[62:63], v[62:63], v[94:95], v[242:243]
	v_pk_fma_f32 v[50:51], v[50:51], v[94:95], v[244:245]
	v_pk_fma_f32 v[34:35], v[34:35], v[94:95], v[110:111]
	v_pk_mul_f32 v[204:205], v[170:171], v[202:203] op_sel_hi:[1,0]
	v_pk_mul_f32 v[208:209], v[170:171], v[206:207] op_sel_hi:[1,0]
	v_pk_mul_f32 v[212:213], v[170:171], v[210:211] op_sel_hi:[1,0]
	v_pk_mul_f32 v[170:171], v[170:171], v[214:215] op_sel_hi:[1,0]
	v_pk_fma_f32 v[68:69], v[68:69], v[96:97], v[204:205]
	v_pk_fma_f32 v[52:53], v[52:53], v[96:97], v[208:209]
	v_pk_fma_f32 v[40:41], v[40:41], v[96:97], v[212:213]
	v_pk_fma_f32 v[24:25], v[24:25], v[96:97], v[170:171]
	v_pk_mul_f32 v[216:217], v[172:173], v[202:203] op_sel_hi:[1,0]
	v_pk_mul_f32 v[242:243], v[172:173], v[206:207] op_sel_hi:[1,0]
	v_pk_mul_f32 v[244:245], v[172:173], v[210:211] op_sel_hi:[1,0]
	v_pk_mul_f32 v[172:173], v[172:173], v[214:215] op_sel_hi:[1,0]
	v_pk_fma_f32 v[70:71], v[70:71], v[98:99], v[216:217]
	v_pk_fma_f32 v[54:55], v[54:55], v[98:99], v[242:243]
	v_pk_fma_f32 v[42:43], v[42:43], v[98:99], v[244:245]
	v_pk_fma_f32 v[26:27], v[26:27], v[98:99], v[172:173]
	v_pk_mul_f32 v[204:205], v[174:175], v[202:203] op_sel_hi:[1,0]
	v_pk_mul_f32 v[208:209], v[174:175], v[206:207] op_sel_hi:[1,0]
	v_pk_mul_f32 v[212:213], v[174:175], v[210:211] op_sel_hi:[1,0]
	v_pk_mul_f32 v[174:175], v[174:175], v[214:215] op_sel_hi:[1,0]
	v_pk_fma_f32 v[64:65], v[64:65], v[100:101], v[204:205]
	v_pk_fma_f32 v[44:45], v[44:45], v[100:101], v[208:209]
	v_pk_fma_f32 v[28:29], v[28:29], v[100:101], v[212:213]
	v_pk_fma_f32 v[16:17], v[16:17], v[100:101], v[174:175]
	v_pk_mul_f32 v[216:217], v[176:177], v[202:203] op_sel_hi:[1,0]
	v_pk_mul_f32 v[242:243], v[176:177], v[206:207] op_sel_hi:[1,0]
	v_pk_mul_f32 v[244:245], v[176:177], v[210:211] op_sel_hi:[1,0]
	v_pk_mul_f32 v[176:177], v[176:177], v[214:215] op_sel_hi:[1,0]
	v_pk_fma_f32 v[66:67], v[66:67], v[102:103], v[216:217]
	v_pk_fma_f32 v[46:47], v[46:47], v[102:103], v[242:243]
	v_pk_fma_f32 v[30:31], v[30:31], v[102:103], v[244:245]
	v_pk_fma_f32 v[18:19], v[18:19], v[102:103], v[176:177]
	v_pk_mul_f32 v[204:205], v[178:179], v[202:203] op_sel_hi:[1,0]
	v_pk_mul_f32 v[208:209], v[178:179], v[206:207] op_sel_hi:[1,0]
	v_pk_mul_f32 v[212:213], v[178:179], v[210:211] op_sel_hi:[1,0]
	v_pk_mul_f32 v[178:179], v[178:179], v[214:215] op_sel_hi:[1,0]
	v_pk_fma_f32 v[56:57], v[56:57], v[104:105], v[204:205]
	v_pk_fma_f32 v[36:37], v[36:37], v[104:105], v[208:209]
	v_pk_fma_f32 v[20:21], v[20:21], v[104:105], v[212:213]
	v_pk_fma_f32 v[12:13], v[12:13], v[104:105], v[178:179]
	v_pk_mul_f32 v[216:217], v[180:181], v[202:203] op_sel_hi:[1,0]
	v_pk_mul_f32 v[242:243], v[180:181], v[206:207] op_sel_hi:[1,0]
	v_pk_mul_f32 v[244:245], v[180:181], v[210:211] op_sel_hi:[1,0]
	v_pk_mul_f32 v[180:181], v[180:181], v[214:215] op_sel_hi:[1,0]
	v_pk_fma_f32 v[58:59], v[58:59], v[106:107], v[216:217]
	v_pk_fma_f32 v[38:39], v[38:39], v[106:107], v[242:243]
	v_pk_fma_f32 v[22:23], v[22:23], v[106:107], v[244:245]
	v_pk_fma_f32 v[14:15], v[14:15], v[106:107], v[180:181]
	ds_read_b128 v[92:95], v221 offset:1024
	ds_read_b128 v[96:99], v221 offset:1040
	ds_read_b128 v[100:103], v221 offset:1056
	ds_read_b128 v[104:107], v221 offset:1072
	s_waitcnt lgkmcnt(4)
	v_pk_fma_f32 v[72:73], v[198:199], v[182:183], v[72:73] op_sel_hi:[0,1,1]
	v_pk_fma_f32 v[60:61], v[198:199], v[182:183], v[60:61] op_sel:[1,0,0]
	v_pk_fma_f32 v[48:49], v[200:201], v[182:183], v[48:49] op_sel_hi:[0,1,1]
	v_pk_fma_f32 v[32:33], v[200:201], v[182:183], v[32:33] op_sel:[1,0,0]
	v_pk_fma_f32 v[74:75], v[198:199], v[184:185], v[74:75] op_sel_hi:[0,1,1]
	v_pk_fma_f32 v[62:63], v[198:199], v[184:185], v[62:63] op_sel:[1,0,0]
	v_pk_fma_f32 v[50:51], v[200:201], v[184:185], v[50:51] op_sel_hi:[0,1,1]
	v_pk_fma_f32 v[34:35], v[200:201], v[184:185], v[34:35] op_sel:[1,0,0]
	v_pk_fma_f32 v[68:69], v[198:199], v[186:187], v[68:69] op_sel_hi:[0,1,1]
	v_pk_fma_f32 v[52:53], v[198:199], v[186:187], v[52:53] op_sel:[1,0,0]
	v_pk_fma_f32 v[40:41], v[200:201], v[186:187], v[40:41] op_sel_hi:[0,1,1]
	v_pk_fma_f32 v[24:25], v[200:201], v[186:187], v[24:25] op_sel:[1,0,0]
	v_pk_fma_f32 v[70:71], v[198:199], v[188:189], v[70:71] op_sel_hi:[0,1,1]
	v_pk_fma_f32 v[54:55], v[198:199], v[188:189], v[54:55] op_sel:[1,0,0]
	v_pk_fma_f32 v[42:43], v[200:201], v[188:189], v[42:43] op_sel_hi:[0,1,1]
	v_pk_fma_f32 v[26:27], v[200:201], v[188:189], v[26:27] op_sel:[1,0,0]
	v_pk_fma_f32 v[64:65], v[198:199], v[190:191], v[64:65] op_sel_hi:[0,1,1]
	v_pk_fma_f32 v[44:45], v[198:199], v[190:191], v[44:45] op_sel:[1,0,0]
	v_pk_fma_f32 v[28:29], v[200:201], v[190:191], v[28:29] op_sel_hi:[0,1,1]
	v_pk_fma_f32 v[16:17], v[200:201], v[190:191], v[16:17] op_sel:[1,0,0]
	v_pk_fma_f32 v[66:67], v[198:199], v[192:193], v[66:67] op_sel_hi:[0,1,1]
	v_pk_fma_f32 v[46:47], v[198:199], v[192:193], v[46:47] op_sel:[1,0,0]
	v_pk_fma_f32 v[30:31], v[200:201], v[192:193], v[30:31] op_sel_hi:[0,1,1]
	v_pk_fma_f32 v[18:19], v[200:201], v[192:193], v[18:19] op_sel:[1,0,0]
	v_pk_fma_f32 v[56:57], v[198:199], v[194:195], v[56:57] op_sel_hi:[0,1,1]
	v_pk_fma_f32 v[36:37], v[198:199], v[194:195], v[36:37] op_sel:[1,0,0]
	v_pk_fma_f32 v[20:21], v[200:201], v[194:195], v[20:21] op_sel_hi:[0,1,1]
	v_pk_fma_f32 v[12:13], v[200:201], v[194:195], v[12:13] op_sel:[1,0,0]
	v_pk_fma_f32 v[58:59], v[198:199], v[196:197], v[58:59] op_sel_hi:[0,1,1]
	v_pk_fma_f32 v[38:39], v[198:199], v[196:197], v[38:39] op_sel:[1,0,0]
	v_pk_fma_f32 v[22:23], v[200:201], v[196:197], v[22:23] op_sel_hi:[0,1,1]
	v_pk_fma_f32 v[14:15], v[200:201], v[196:197], v[14:15] op_sel:[1,0,0]
	s_waitcnt lgkmcnt(0)
	v_pk_mul_f32 v[202:203], v[72:73], v[92:93]
	v_pk_mul_f32 v[204:205], v[74:75], v[94:95]
	v_pk_mul_f32 v[206:207], v[60:61], v[92:93]
	v_pk_mul_f32 v[208:209], v[62:63], v[94:95]
	v_pk_mul_f32 v[210:211], v[48:49], v[92:93]
	v_pk_mul_f32 v[212:213], v[50:51], v[94:95]
	v_pk_mul_f32 v[214:215], v[32:33], v[92:93]
	v_pk_mul_f32 v[216:217], v[34:35], v[94:95]
	v_pk_fma_f32 v[202:203], v[68:69], v[96:97], v[202:203]
	v_pk_fma_f32 v[204:205], v[70:71], v[98:99], v[204:205]
	v_pk_fma_f32 v[206:207], v[52:53], v[96:97], v[206:207]
	v_pk_fma_f32 v[208:209], v[54:55], v[98:99], v[208:209]
	v_pk_fma_f32 v[210:211], v[40:41], v[96:97], v[210:211]
	v_pk_fma_f32 v[212:213], v[42:43], v[98:99], v[212:213]
	v_pk_fma_f32 v[214:215], v[24:25], v[96:97], v[214:215]
	v_pk_fma_f32 v[216:217], v[26:27], v[98:99], v[216:217]
	v_pk_fma_f32 v[202:203], v[64:65], v[100:101], v[202:203]
	v_pk_fma_f32 v[204:205], v[66:67], v[102:103], v[204:205]
	v_pk_fma_f32 v[206:207], v[44:45], v[100:101], v[206:207]
	v_pk_fma_f32 v[208:209], v[46:47], v[102:103], v[208:209]
	v_pk_fma_f32 v[210:211], v[28:29], v[100:101], v[210:211]
	v_pk_fma_f32 v[212:213], v[30:31], v[102:103], v[212:213]
	v_pk_fma_f32 v[214:215], v[16:17], v[100:101], v[214:215]
	v_pk_fma_f32 v[216:217], v[18:19], v[102:103], v[216:217]
	v_pk_fma_f32 v[202:203], v[56:57], v[104:105], v[202:203]
	v_pk_fma_f32 v[204:205], v[58:59], v[106:107], v[204:205]
	v_pk_fma_f32 v[206:207], v[36:37], v[104:105], v[206:207]
	v_pk_fma_f32 v[208:209], v[38:39], v[106:107], v[208:209]
	v_pk_fma_f32 v[210:211], v[20:21], v[104:105], v[210:211]
	v_pk_fma_f32 v[212:213], v[22:23], v[106:107], v[212:213]
	v_pk_fma_f32 v[214:215], v[12:13], v[104:105], v[214:215]
	v_pk_fma_f32 v[216:217], v[14:15], v[106:107], v[216:217]
	v_pk_add_f32 v[202:203], v[202:203], v[204:205]
	v_pk_add_f32 v[206:207], v[206:207], v[208:209]
	v_pk_add_f32 v[210:211], v[210:211], v[212:213]
	v_pk_add_f32 v[214:215], v[214:215], v[216:217]
	v_add_f32_e32 v202, v202, v203
	v_add_f32_e32 v206, v206, v207
	v_add_f32_e32 v210, v210, v211
	v_add_f32_e32 v214, v214, v215
	v_add_f32_dpp v202, v202, v202 quad_perm:[1,0,3,2] row_mask:0xf bank_mask:0xf bound_ctrl:1
	v_add_f32_dpp v206, v206, v206 quad_perm:[1,0,3,2] row_mask:0xf bank_mask:0xf bound_ctrl:1
	v_add_f32_dpp v210, v210, v210 quad_perm:[1,0,3,2] row_mask:0xf bank_mask:0xf bound_ctrl:1
	v_add_f32_dpp v214, v214, v214 quad_perm:[1,0,3,2] row_mask:0xf bank_mask:0xf bound_ctrl:1
	v_add_f32_dpp v202, v202, v202 quad_perm:[2,3,0,1] row_mask:0xf bank_mask:0xf bound_ctrl:1
	v_add_f32_dpp v206, v206, v206 quad_perm:[2,3,0,1] row_mask:0xf bank_mask:0xf bound_ctrl:1
	v_add_f32_dpp v210, v210, v210 quad_perm:[2,3,0,1] row_mask:0xf bank_mask:0xf bound_ctrl:1
	v_add_f32_dpp v214, v214, v214 quad_perm:[2,3,0,1] row_mask:0xf bank_mask:0xf bound_ctrl:1
	s_nop 0
	v_cvt_pk_bf16_f32 v240, v202, v206
	v_cvt_pk_bf16_f32 v241, v210, v214
	s_mov_b64 exec, s[6:7]
	global_store_dwordx2 v[238:239], v[240:241], off
	s_mov_b64 exec, -1
	s_waitcnt lgkmcnt(0)

.LBB0_978:
	s_add_i32 s82, s65, s99
	s_ashr_i32 s83, s82, 31
	s_lshl_b64 s[82:83], s[82:83], 7
	v_lshl_add_u64 v[238:239], v[124:125], 0, s[82:83]
	v_add_u32_e32 v218, s97, v232
	v_lshl_add_u32 v222, v114, 2, s57
	v_add_u32_e32 v219, s98, v218
	v_add_u32_e32 v222, s97, v222
	v_add_u32_e32 v220, s98, v219
	v_add_u32_e32 v223, s98, v222
	v_add_u32_e32 v221, s98, v220
	v_add_u32_e32 v236, s98, v223
	v_add_u32_e32 v237, s98, v236
	ds_read_b128 v[92:95], v218 offset:256
	ds_read_b128 v[96:99], v218 offset:272
	ds_read_b128 v[100:103], v218 offset:288
	ds_read_b128 v[104:107], v218 offset:304
	ds_read_b128 v[108:111], v218 offset:512
	ds_read_b128 v[170:173], v218 offset:528
	ds_read_b128 v[174:177], v218 offset:544
	ds_read_b128 v[178:181], v218 offset:560
	ds_read_b128 v[198:201], v222 offset:1280
	s_waitcnt lgkmcnt(9)
	v_pk_mul_f32 v[202:203], v[72:73], v[76:77]
	v_pk_mul_f32 v[204:205], v[74:75], v[78:79]
	v_pk_mul_f32 v[206:207], v[60:61], v[76:77]
	v_pk_mul_f32 v[208:209], v[62:63], v[78:79]
	v_pk_mul_f32 v[210:211], v[48:49], v[76:77]
	v_pk_mul_f32 v[212:213], v[50:51], v[78:79]
	v_pk_mul_f32 v[214:215], v[32:33], v[76:77]
	v_pk_mul_f32 v[216:217], v[34:35], v[78:79]
	v_pk_fma_f32 v[202:203], v[68:69], v[80:81], v[202:203]
	v_pk_fma_f32 v[204:205], v[70:71], v[82:83], v[204:205]
	v_pk_fma_f32 v[206:207], v[52:53], v[80:81], v[206:207]
	v_pk_fma_f32 v[208:209], v[54:55], v[82:83], v[208:209]
	v_pk_fma_f32 v[210:211], v[40:41], v[80:81], v[210:211]
	v_pk_fma_f32 v[212:213], v[42:43], v[82:83], v[212:213]
	v_pk_fma_f32 v[214:215], v[24:25], v[80:81], v[214:215]
	v_pk_fma_f32 v[216:217], v[26:27], v[82:83], v[216:217]
	v_pk_fma_f32 v[202:203], v[64:65], v[84:85], v[202:203]
	v_pk_fma_f32 v[204:205], v[66:67], v[86:87], v[204:205]
	v_pk_fma_f32 v[206:207], v[44:45], v[84:85], v[206:207]
	v_pk_fma_f32 v[208:209], v[46:47], v[86:87], v[208:209]
	v_pk_fma_f32 v[210:211], v[28:29], v[84:85], v[210:211]
	v_pk_fma_f32 v[212:213], v[30:31], v[86:87], v[212:213]
	v_pk_fma_f32 v[214:215], v[16:17], v[84:85], v[214:215]
	v_pk_fma_f32 v[216:217], v[18:19], v[86:87], v[216:217]
	v_pk_fma_f32 v[202:203], v[56:57], v[88:89], v[202:203]
	v_pk_fma_f32 v[204:205], v[58:59], v[90:91], v[204:205]
	v_pk_fma_f32 v[206:207], v[36:37], v[88:89], v[206:207]
	v_pk_fma_f32 v[208:209], v[38:39], v[90:91], v[208:209]
	v_pk_fma_f32 v[210:211], v[20:21], v[88:89], v[210:211]
	v_pk_fma_f32 v[212:213], v[22:23], v[90:91], v[212:213]
	v_pk_fma_f32 v[214:215], v[12:13], v[88:89], v[214:215]
	v_pk_fma_f32 v[216:217], v[14:15], v[90:91], v[216:217]
	s_waitcnt lgkmcnt(1)
	v_pk_add_f32 v[202:203], v[202:203], v[204:205]
	v_pk_add_f32 v[206:207], v[206:207], v[208:209]
	v_pk_add_f32 v[210:211], v[210:211], v[212:213]
	v_pk_add_f32 v[214:215], v[214:215], v[216:217]
	ds_read_b128 v[182:185], v218 offset:768
	v_add_f32_e32 v202, v202, v203
	v_add_f32_e32 v206, v206, v207
	v_add_f32_e32 v210, v210, v211
	v_add_f32_e32 v214, v214, v215
	ds_read_b128 v[186:189], v218 offset:784
	v_add_f32_dpp v202, v202, v202 quad_perm:[1,0,3,2] row_mask:0xf bank_mask:0xf bound_ctrl:1
	v_add_f32_dpp v206, v206, v206 quad_perm:[1,0,3,2] row_mask:0xf bank_mask:0xf bound_ctrl:1
	v_add_f32_dpp v210, v210, v210 quad_perm:[1,0,3,2] row_mask:0xf bank_mask:0xf bound_ctrl:1
	v_add_f32_dpp v214, v214, v214 quad_perm:[1,0,3,2] row_mask:0xf bank_mask:0xf bound_ctrl:1
	ds_read_b128 v[190:193], v218 offset:800
	v_add_f32_dpp v202, v202, v202 quad_perm:[2,3,0,1] row_mask:0xf bank_mask:0xf bound_ctrl:1
	v_add_f32_dpp v206, v206, v206 quad_perm:[2,3,0,1] row_mask:0xf bank_mask:0xf bound_ctrl:1
	v_add_f32_dpp v210, v210, v210 quad_perm:[2,3,0,1] row_mask:0xf bank_mask:0xf bound_ctrl:1
	v_add_f32_dpp v214, v214, v214 quad_perm:[2,3,0,1] row_mask:0xf bank_mask:0xf bound_ctrl:1
	ds_read_b128 v[194:197], v218 offset:816
	v_pk_mul_f32 v[204:205], v[108:109], v[202:203] op_sel_hi:[1,0]
	v_pk_mul_f32 v[208:209], v[108:109], v[206:207] op_sel_hi:[1,0]
	v_pk_mul_f32 v[212:213], v[108:109], v[210:211] op_sel_hi:[1,0]
	v_pk_mul_f32 v[108:109], v[108:109], v[214:215] op_sel_hi:[1,0]
	v_pk_fma_f32 v[72:73], v[72:73], v[92:93], v[204:205]
	v_pk_fma_f32 v[60:61], v[60:61], v[92:93], v[208:209]
	v_pk_fma_f32 v[48:49], v[48:49], v[92:93], v[212:213]
	v_pk_fma_f32 v[32:33], v[32:33], v[92:93], v[108:109]
	v_pk_mul_f32 v[216:217], v[110:111], v[202:203] op_sel_hi:[1,0]
	v_pk_mul_f32 v[242:243], v[110:111], v[206:207] op_sel_hi:[1,0]
	v_pk_mul_f32 v[244:245], v[110:111], v[210:211] op_sel_hi:[1,0]
	v_pk_mul_f32 v[110:111], v[110:111], v[214:215] op_sel_hi:[1,0]
	v_pk_fma_f32 v[74:75], v[74:75], v[94:95], v[216:217]
	v_pk_fma_f32 v[62:63], v[62:63], v[94:95], v[242:243]
	v_pk_fma_f32 v[50:51], v[50:51], v[94:95], v[244:245]
	v_pk_fma_f32 v[34:35], v[34:35], v[94:95], v[110:111]
	v_pk_mul_f32 v[204:205], v[170:171], v[202:203] op_sel_hi:[1,0]
	v_pk_mul_f32 v[208:209], v[170:171], v[206:207] op_sel_hi:[1,0]
	v_pk_mul_f32 v[212:213], v[170:171], v[210:211] op_sel_hi:[1,0]
	v_pk_mul_f32 v[170:171], v[170:171], v[214:215] op_sel_hi:[1,0]
	v_pk_fma_f32 v[68:69], v[68:69], v[96:97], v[204:205]
	v_pk_fma_f32 v[52:53], v[52:53], v[96:97], v[208:209]
	v_pk_fma_f32 v[40:41], v[40:41], v[96:97], v[212:213]
	v_pk_fma_f32 v[24:25], v[24:25], v[96:97], v[170:171]
	v_pk_mul_f32 v[216:217], v[172:173], v[202:203] op_sel_hi:[1,0]
	v_pk_mul_f32 v[242:243], v[172:173], v[206:207] op_sel_hi:[1,0]
	v_pk_mul_f32 v[244:245], v[172:173], v[210:211] op_sel_hi:[1,0]
	v_pk_mul_f32 v[172:173], v[172:173], v[214:215] op_sel_hi:[1,0]
	v_pk_fma_f32 v[70:71], v[70:71], v[98:99], v[216:217]
	v_pk_fma_f32 v[54:55], v[54:55], v[98:99], v[242:243]
	v_pk_fma_f32 v[42:43], v[42:43], v[98:99], v[244:245]
	v_pk_fma_f32 v[26:27], v[26:27], v[98:99], v[172:173]
	v_pk_mul_f32 v[204:205], v[174:175], v[202:203] op_sel_hi:[1,0]
	v_pk_mul_f32 v[208:209], v[174:175], v[206:207] op_sel_hi:[1,0]
	v_pk_mul_f32 v[212:213], v[174:175], v[210:211] op_sel_hi:[1,0]
	v_pk_mul_f32 v[174:175], v[174:175], v[214:215] op_sel_hi:[1,0]
	v_pk_fma_f32 v[64:65], v[64:65], v[100:101], v[204:205]
	v_pk_fma_f32 v[44:45], v[44:45], v[100:101], v[208:209]
	v_pk_fma_f32 v[28:29], v[28:29], v[100:101], v[212:213]
	v_pk_fma_f32 v[16:17], v[16:17], v[100:101], v[174:175]
	v_pk_mul_f32 v[216:217], v[176:177], v[202:203] op_sel_hi:[1,0]
	v_pk_mul_f32 v[242:243], v[176:177], v[206:207] op_sel_hi:[1,0]
	v_pk_mul_f32 v[244:245], v[176:177], v[210:211] op_sel_hi:[1,0]
	v_pk_mul_f32 v[176:177], v[176:177], v[214:215] op_sel_hi:[1,0]
	v_pk_fma_f32 v[66:67], v[66:67], v[102:103], v[216:217]
	v_pk_fma_f32 v[46:47], v[46:47], v[102:103], v[242:243]
	v_pk_fma_f32 v[30:31], v[30:31], v[102:103], v[244:245]
	v_pk_fma_f32 v[18:19], v[18:19], v[102:103], v[176:177]
	v_pk_mul_f32 v[204:205], v[178:179], v[202:203] op_sel_hi:[1,0]
	v_pk_mul_f32 v[208:209], v[178:179], v[206:207] op_sel_hi:[1,0]
	v_pk_mul_f32 v[212:213], v[178:179], v[210:211] op_sel_hi:[1,0]
	v_pk_mul_f32 v[178:179], v[178:179], v[214:215] op_sel_hi:[1,0]
	v_pk_fma_f32 v[56:57], v[56:57], v[104:105], v[204:205]
	v_pk_fma_f32 v[36:37], v[36:37], v[104:105], v[208:209]
	v_pk_fma_f32 v[20:21], v[20:21], v[104:105], v[212:213]
	v_pk_fma_f32 v[12:13], v[12:13], v[104:105], v[178:179]
	v_pk_mul_f32 v[216:217], v[180:181], v[202:203] op_sel_hi:[1,0]
	v_pk_mul_f32 v[242:243], v[180:181], v[206:207] op_sel_hi:[1,0]
	v_pk_mul_f32 v[244:245], v[180:181], v[210:211] op_sel_hi:[1,0]
	v_pk_mul_f32 v[180:181], v[180:181], v[214:215] op_sel_hi:[1,0]
	v_pk_fma_f32 v[58:59], v[58:59], v[106:107], v[216:217]
	v_pk_fma_f32 v[38:39], v[38:39], v[106:107], v[242:243]
	v_pk_fma_f32 v[22:23], v[22:23], v[106:107], v[244:245]
	v_pk_fma_f32 v[14:15], v[14:15], v[106:107], v[180:181]
	ds_read_b128 v[92:95], v218 offset:1024
	ds_read_b128 v[96:99], v218 offset:1040
	ds_read_b128 v[100:103], v218 offset:1056
	ds_read_b128 v[104:107], v218 offset:1072
	ds_read_b128 v[76:79], v219 offset:0
	ds_read_b128 v[80:83], v219 offset:16
	ds_read_b128 v[84:87], v219 offset:32
	ds_read_b128 v[88:91], v219 offset:48
	s_waitcnt lgkmcnt(8)
	v_pk_fma_f32 v[72:73], v[198:199], v[182:183], v[72:73] op_sel_hi:[0,1,1]
	v_pk_fma_f32 v[60:61], v[198:199], v[182:183], v[60:61] op_sel:[1,0,0]
	v_pk_fma_f32 v[48:49], v[200:201], v[182:183], v[48:49] op_sel_hi:[0,1,1]
	v_pk_fma_f32 v[32:33], v[200:201], v[182:183], v[32:33] op_sel:[1,0,0]
	v_pk_fma_f32 v[74:75], v[198:199], v[184:185], v[74:75] op_sel_hi:[0,1,1]
	v_pk_fma_f32 v[62:63], v[198:199], v[184:185], v[62:63] op_sel:[1,0,0]
	v_pk_fma_f32 v[50:51], v[200:201], v[184:185], v[50:51] op_sel_hi:[0,1,1]
	v_pk_fma_f32 v[34:35], v[200:201], v[184:185], v[34:35] op_sel:[1,0,0]
	v_pk_fma_f32 v[68:69], v[198:199], v[186:187], v[68:69] op_sel_hi:[0,1,1]
	v_pk_fma_f32 v[52:53], v[198:199], v[186:187], v[52:53] op_sel:[1,0,0]
	v_pk_fma_f32 v[40:41], v[200:201], v[186:187], v[40:41] op_sel_hi:[0,1,1]
	v_pk_fma_f32 v[24:25], v[200:201], v[186:187], v[24:25] op_sel:[1,0,0]
	v_pk_fma_f32 v[70:71], v[198:199], v[188:189], v[70:71] op_sel_hi:[0,1,1]
	v_pk_fma_f32 v[54:55], v[198:199], v[188:189], v[54:55] op_sel:[1,0,0]
	v_pk_fma_f32 v[42:43], v[200:201], v[188:189], v[42:43] op_sel_hi:[0,1,1]
	v_pk_fma_f32 v[26:27], v[200:201], v[188:189], v[26:27] op_sel:[1,0,0]
	v_pk_fma_f32 v[64:65], v[198:199], v[190:191], v[64:65] op_sel_hi:[0,1,1]
	v_pk_fma_f32 v[44:45], v[198:199], v[190:191], v[44:45] op_sel:[1,0,0]
	v_pk_fma_f32 v[28:29], v[200:201], v[190:191], v[28:29] op_sel_hi:[0,1,1]
	v_pk_fma_f32 v[16:17], v[200:201], v[190:191], v[16:17] op_sel:[1,0,0]
	v_pk_fma_f32 v[66:67], v[198:199], v[192:193], v[66:67] op_sel_hi:[0,1,1]
	v_pk_fma_f32 v[46:47], v[198:199], v[192:193], v[46:47] op_sel:[1,0,0]
	v_pk_fma_f32 v[30:31], v[200:201], v[192:193], v[30:31] op_sel_hi:[0,1,1]
	v_pk_fma_f32 v[18:19], v[200:201], v[192:193], v[18:19] op_sel:[1,0,0]
	v_pk_fma_f32 v[56:57], v[198:199], v[194:195], v[56:57] op_sel_hi:[0,1,1]
	v_pk_fma_f32 v[36:37], v[198:199], v[194:195], v[36:37] op_sel:[1,0,0]
	v_pk_fma_f32 v[20:21], v[200:201], v[194:195], v[20:21] op_sel_hi:[0,1,1]
	v_pk_fma_f32 v[12:13], v[200:201], v[194:195], v[12:13] op_sel:[1,0,0]
	v_pk_fma_f32 v[58:59], v[198:199], v[196:197], v[58:59] op_sel_hi:[0,1,1]
	v_pk_fma_f32 v[38:39], v[198:199], v[196:197], v[38:39] op_sel:[1,0,0]
	v_pk_fma_f32 v[22:23], v[200:201], v[196:197], v[22:23] op_sel_hi:[0,1,1]
	v_pk_fma_f32 v[14:15], v[200:201], v[196:197], v[14:15] op_sel:[1,0,0]
	s_waitcnt lgkmcnt(4)
	v_pk_mul_f32 v[202:203], v[72:73], v[92:93]
	v_pk_mul_f32 v[204:205], v[74:75], v[94:95]
	v_pk_mul_f32 v[206:207], v[60:61], v[92:93]
	v_pk_mul_f32 v[208:209], v[62:63], v[94:95]
	v_pk_mul_f32 v[210:211], v[48:49], v[92:93]
	v_pk_mul_f32 v[212:213], v[50:51], v[94:95]
	v_pk_mul_f32 v[214:215], v[32:33], v[92:93]
	v_pk_mul_f32 v[216:217], v[34:35], v[94:95]
	v_pk_fma_f32 v[202:203], v[68:69], v[96:97], v[202:203]
	v_pk_fma_f32 v[204:205], v[70:71], v[98:99], v[204:205]
	v_pk_fma_f32 v[206:207], v[52:53], v[96:97], v[206:207]
	v_pk_fma_f32 v[208:209], v[54:55], v[98:99], v[208:209]
	v_pk_fma_f32 v[210:211], v[40:41], v[96:97], v[210:211]
	v_pk_fma_f32 v[212:213], v[42:43], v[98:99], v[212:213]
	v_pk_fma_f32 v[214:215], v[24:25], v[96:97], v[214:215]
	v_pk_fma_f32 v[216:217], v[26:27], v[98:99], v[216:217]
	v_pk_fma_f32 v[202:203], v[64:65], v[100:101], v[202:203]
	v_pk_fma_f32 v[204:205], v[66:67], v[102:103], v[204:205]
	v_pk_fma_f32 v[206:207], v[44:45], v[100:101], v[206:207]
	v_pk_fma_f32 v[208:209], v[46:47], v[102:103], v[208:209]
	v_pk_fma_f32 v[210:211], v[28:29], v[100:101], v[210:211]
	v_pk_fma_f32 v[212:213], v[30:31], v[102:103], v[212:213]
	v_pk_fma_f32 v[214:215], v[16:17], v[100:101], v[214:215]
	v_pk_fma_f32 v[216:217], v[18:19], v[102:103], v[216:217]
	v_pk_fma_f32 v[202:203], v[56:57], v[104:105], v[202:203]
	v_pk_fma_f32 v[204:205], v[58:59], v[106:107], v[204:205]
	v_pk_fma_f32 v[206:207], v[36:37], v[104:105], v[206:207]
	v_pk_fma_f32 v[208:209], v[38:39], v[106:107], v[208:209]
	v_pk_fma_f32 v[210:211], v[20:21], v[104:105], v[210:211]
	v_pk_fma_f32 v[212:213], v[22:23], v[106:107], v[212:213]
	v_pk_fma_f32 v[214:215], v[12:13], v[104:105], v[214:215]
	v_pk_fma_f32 v[216:217], v[14:15], v[106:107], v[216:217]
	v_pk_add_f32 v[202:203], v[202:203], v[204:205]
	v_pk_add_f32 v[206:207], v[206:207], v[208:209]
	v_pk_add_f32 v[210:211], v[210:211], v[212:213]
	v_pk_add_f32 v[214:215], v[214:215], v[216:217]
	ds_read_b128 v[92:95], v219 offset:256
	v_add_f32_e32 v202, v202, v203
	v_add_f32_e32 v206, v206, v207
	v_add_f32_e32 v210, v210, v211
	v_add_f32_e32 v214, v214, v215
	ds_read_b128 v[96:99], v219 offset:272
	v_add_f32_dpp v202, v202, v202 quad_perm:[1,0,3,2] row_mask:0xf bank_mask:0xf bound_ctrl:1
	v_add_f32_dpp v206, v206, v206 quad_perm:[1,0,3,2] row_mask:0xf bank_mask:0xf bound_ctrl:1
	v_add_f32_dpp v210, v210, v210 quad_perm:[1,0,3,2] row_mask:0xf bank_mask:0xf bound_ctrl:1
	v_add_f32_dpp v214, v214, v214 quad_perm:[1,0,3,2] row_mask:0xf bank_mask:0xf bound_ctrl:1
	ds_read_b128 v[100:103], v219 offset:288
	v_add_f32_dpp v202, v202, v202 quad_perm:[2,3,0,1] row_mask:0xf bank_mask:0xf bound_ctrl:1
	v_add_f32_dpp v206, v206, v206 quad_perm:[2,3,0,1] row_mask:0xf bank_mask:0xf bound_ctrl:1
	v_add_f32_dpp v210, v210, v210 quad_perm:[2,3,0,1] row_mask:0xf bank_mask:0xf bound_ctrl:1
	v_add_f32_dpp v214, v214, v214 quad_perm:[2,3,0,1] row_mask:0xf bank_mask:0xf bound_ctrl:1
	ds_read_b128 v[104:107], v219 offset:304
	ds_read_b128 v[108:111], v219 offset:512
	v_cvt_pk_bf16_f32 v240, v202, v206
	v_cvt_pk_bf16_f32 v241, v210, v214
	ds_read_b128 v[170:173], v219 offset:528
	ds_read_b128 v[174:177], v219 offset:544
	s_mov_b64 exec, s[6:7]
	global_store_dwordx2 v[238:239], v[240:241], off
	s_mov_b64 exec, -1
	ds_read_b128 v[178:181], v219 offset:560
	ds_read_b128 v[198:201], v223 offset:1280
	v_lshl_add_u64 v[238:239], v[238:239], 0, s[80:81]
	s_waitcnt lgkmcnt(9)
	v_pk_mul_f32 v[202:203], v[72:73], v[76:77]
	v_pk_mul_f32 v[204:205], v[74:75], v[78:79]
	v_pk_mul_f32 v[206:207], v[60:61], v[76:77]
	v_pk_mul_f32 v[208:209], v[62:63], v[78:79]
	v_pk_mul_f32 v[210:211], v[48:49], v[76:77]
	v_pk_mul_f32 v[212:213], v[50:51], v[78:79]
	v_pk_mul_f32 v[214:215], v[32:33], v[76:77]
	v_pk_mul_f32 v[216:217], v[34:35], v[78:79]
	v_pk_fma_f32 v[202:203], v[68:69], v[80:81], v[202:203]
	v_pk_fma_f32 v[204:205], v[70:71], v[82:83], v[204:205]
	v_pk_fma_f32 v[206:207], v[52:53], v[80:81], v[206:207]
	v_pk_fma_f32 v[208:209], v[54:55], v[82:83], v[208:209]
	v_pk_fma_f32 v[210:211], v[40:41], v[80:81], v[210:211]
	v_pk_fma_f32 v[212:213], v[42:43], v[82:83], v[212:213]
	v_pk_fma_f32 v[214:215], v[24:25], v[80:81], v[214:215]
	v_pk_fma_f32 v[216:217], v[26:27], v[82:83], v[216:217]
	v_pk_fma_f32 v[202:203], v[64:65], v[84:85], v[202:203]
	v_pk_fma_f32 v[204:205], v[66:67], v[86:87], v[204:205]
	v_pk_fma_f32 v[206:207], v[44:45], v[84:85], v[206:207]
	v_pk_fma_f32 v[208:209], v[46:47], v[86:87], v[208:209]
	v_pk_fma_f32 v[210:211], v[28:29], v[84:85], v[210:211]
	v_pk_fma_f32 v[212:213], v[30:31], v[86:87], v[212:213]
	v_pk_fma_f32 v[214:215], v[16:17], v[84:85], v[214:215]
	v_pk_fma_f32 v[216:217], v[18:19], v[86:87], v[216:217]
	v_pk_fma_f32 v[202:203], v[56:57], v[88:89], v[202:203]
	v_pk_fma_f32 v[204:205], v[58:59], v[90:91], v[204:205]
	v_pk_fma_f32 v[206:207], v[36:37], v[88:89], v[206:207]
	v_pk_fma_f32 v[208:209], v[38:39], v[90:91], v[208:209]
	v_pk_fma_f32 v[210:211], v[20:21], v[88:89], v[210:211]
	v_pk_fma_f32 v[212:213], v[22:23], v[90:91], v[212:213]
	v_pk_fma_f32 v[214:215], v[12:13], v[88:89], v[214:215]
	v_pk_fma_f32 v[216:217], v[14:15], v[90:91], v[216:217]
	s_waitcnt lgkmcnt(1)
	v_pk_add_f32 v[202:203], v[202:203], v[204:205]
	v_pk_add_f32 v[206:207], v[206:207], v[208:209]
	v_pk_add_f32 v[210:211], v[210:211], v[212:213]
	v_pk_add_f32 v[214:215], v[214:215], v[216:217]
	ds_read_b128 v[182:185], v219 offset:768
	v_add_f32_e32 v202, v202, v203
	v_add_f32_e32 v206, v206, v207
	v_add_f32_e32 v210, v210, v211
	v_add_f32_e32 v214, v214, v215
	ds_read_b128 v[186:189], v219 offset:784
	v_add_f32_dpp v202, v202, v202 quad_perm:[1,0,3,2] row_mask:0xf bank_mask:0xf bound_ctrl:1
	v_add_f32_dpp v206, v206, v206 quad_perm:[1,0,3,2] row_mask:0xf bank_mask:0xf bound_ctrl:1
	v_add_f32_dpp v210, v210, v210 quad_perm:[1,0,3,2] row_mask:0xf bank_mask:0xf bound_ctrl:1
	v_add_f32_dpp v214, v214, v214 quad_perm:[1,0,3,2] row_mask:0xf bank_mask:0xf bound_ctrl:1
	ds_read_b128 v[190:193], v219 offset:800
	v_add_f32_dpp v202, v202, v202 quad_perm:[2,3,0,1] row_mask:0xf bank_mask:0xf bound_ctrl:1
	v_add_f32_dpp v206, v206, v206 quad_perm:[2,3,0,1] row_mask:0xf bank_mask:0xf bound_ctrl:1
	v_add_f32_dpp v210, v210, v210 quad_perm:[2,3,0,1] row_mask:0xf bank_mask:0xf bound_ctrl:1
	v_add_f32_dpp v214, v214, v214 quad_perm:[2,3,0,1] row_mask:0xf bank_mask:0xf bound_ctrl:1
	ds_read_b128 v[194:197], v219 offset:816
	v_pk_mul_f32 v[204:205], v[108:109], v[202:203] op_sel_hi:[1,0]
	v_pk_mul_f32 v[208:209], v[108:109], v[206:207] op_sel_hi:[1,0]
	v_pk_mul_f32 v[212:213], v[108:109], v[210:211] op_sel_hi:[1,0]
	v_pk_mul_f32 v[108:109], v[108:109], v[214:215] op_sel_hi:[1,0]
	v_pk_fma_f32 v[72:73], v[72:73], v[92:93], v[204:205]
	v_pk_fma_f32 v[60:61], v[60:61], v[92:93], v[208:209]
	v_pk_fma_f32 v[48:49], v[48:49], v[92:93], v[212:213]
	v_pk_fma_f32 v[32:33], v[32:33], v[92:93], v[108:109]
	v_pk_mul_f32 v[216:217], v[110:111], v[202:203] op_sel_hi:[1,0]
	v_pk_mul_f32 v[242:243], v[110:111], v[206:207] op_sel_hi:[1,0]
	v_pk_mul_f32 v[244:245], v[110:111], v[210:211] op_sel_hi:[1,0]
	v_pk_mul_f32 v[110:111], v[110:111], v[214:215] op_sel_hi:[1,0]
	v_pk_fma_f32 v[74:75], v[74:75], v[94:95], v[216:217]
	v_pk_fma_f32 v[62:63], v[62:63], v[94:95], v[242:243]
	v_pk_fma_f32 v[50:51], v[50:51], v[94:95], v[244:245]
	v_pk_fma_f32 v[34:35], v[34:35], v[94:95], v[110:111]
	v_pk_mul_f32 v[204:205], v[170:171], v[202:203] op_sel_hi:[1,0]
	v_pk_mul_f32 v[208:209], v[170:171], v[206:207] op_sel_hi:[1,0]
	v_pk_mul_f32 v[212:213], v[170:171], v[210:211] op_sel_hi:[1,0]
	v_pk_mul_f32 v[170:171], v[170:171], v[214:215] op_sel_hi:[1,0]
	v_pk_fma_f32 v[68:69], v[68:69], v[96:97], v[204:205]
	v_pk_fma_f32 v[52:53], v[52:53], v[96:97], v[208:209]
	v_pk_fma_f32 v[40:41], v[40:41], v[96:97], v[212:213]
	v_pk_fma_f32 v[24:25], v[24:25], v[96:97], v[170:171]
	v_pk_mul_f32 v[216:217], v[172:173], v[202:203] op_sel_hi:[1,0]
	v_pk_mul_f32 v[242:243], v[172:173], v[206:207] op_sel_hi:[1,0]
	v_pk_mul_f32 v[244:245], v[172:173], v[210:211] op_sel_hi:[1,0]
	v_pk_mul_f32 v[172:173], v[172:173], v[214:215] op_sel_hi:[1,0]
	v_pk_fma_f32 v[70:71], v[70:71], v[98:99], v[216:217]
	v_pk_fma_f32 v[54:55], v[54:55], v[98:99], v[242:243]
	v_pk_fma_f32 v[42:43], v[42:43], v[98:99], v[244:245]
	v_pk_fma_f32 v[26:27], v[26:27], v[98:99], v[172:173]
	v_pk_mul_f32 v[204:205], v[174:175], v[202:203] op_sel_hi:[1,0]
	v_pk_mul_f32 v[208:209], v[174:175], v[206:207] op_sel_hi:[1,0]
	v_pk_mul_f32 v[212:213], v[174:175], v[210:211] op_sel_hi:[1,0]
	v_pk_mul_f32 v[174:175], v[174:175], v[214:215] op_sel_hi:[1,0]
	v_pk_fma_f32 v[64:65], v[64:65], v[100:101], v[204:205]
	v_pk_fma_f32 v[44:45], v[44:45], v[100:101], v[208:209]
	v_pk_fma_f32 v[28:29], v[28:29], v[100:101], v[212:213]
	v_pk_fma_f32 v[16:17], v[16:17], v[100:101], v[174:175]
	v_pk_mul_f32 v[216:217], v[176:177], v[202:203] op_sel_hi:[1,0]
	v_pk_mul_f32 v[242:243], v[176:177], v[206:207] op_sel_hi:[1,0]
	v_pk_mul_f32 v[244:245], v[176:177], v[210:211] op_sel_hi:[1,0]
	v_pk_mul_f32 v[176:177], v[176:177], v[214:215] op_sel_hi:[1,0]
	v_pk_fma_f32 v[66:67], v[66:67], v[102:103], v[216:217]
	v_pk_fma_f32 v[46:47], v[46:47], v[102:103], v[242:243]
	v_pk_fma_f32 v[30:31], v[30:31], v[102:103], v[244:245]
	v_pk_fma_f32 v[18:19], v[18:19], v[102:103], v[176:177]
	v_pk_mul_f32 v[204:205], v[178:179], v[202:203] op_sel_hi:[1,0]
	v_pk_mul_f32 v[208:209], v[178:179], v[206:207] op_sel_hi:[1,0]
	v_pk_mul_f32 v[212:213], v[178:179], v[210:211] op_sel_hi:[1,0]
	v_pk_mul_f32 v[178:179], v[178:179], v[214:215] op_sel_hi:[1,0]
	v_pk_fma_f32 v[56:57], v[56:57], v[104:105], v[204:205]
	v_pk_fma_f32 v[36:37], v[36:37], v[104:105], v[208:209]
	v_pk_fma_f32 v[20:21], v[20:21], v[104:105], v[212:213]
	v_pk_fma_f32 v[12:13], v[12:13], v[104:105], v[178:179]
	v_pk_mul_f32 v[216:217], v[180:181], v[202:203] op_sel_hi:[1,0]
	v_pk_mul_f32 v[242:243], v[180:181], v[206:207] op_sel_hi:[1,0]
	v_pk_mul_f32 v[244:245], v[180:181], v[210:211] op_sel_hi:[1,0]
	v_pk_mul_f32 v[180:181], v[180:181], v[214:215] op_sel_hi:[1,0]
	v_pk_fma_f32 v[58:59], v[58:59], v[106:107], v[216:217]
	v_pk_fma_f32 v[38:39], v[38:39], v[106:107], v[242:243]
	v_pk_fma_f32 v[22:23], v[22:23], v[106:107], v[244:245]
	v_pk_fma_f32 v[14:15], v[14:15], v[106:107], v[180:181]
	ds_read_b128 v[92:95], v219 offset:1024
	ds_read_b128 v[96:99], v219 offset:1040
	ds_read_b128 v[100:103], v219 offset:1056
	ds_read_b128 v[104:107], v219 offset:1072
	ds_read_b128 v[76:79], v220 offset:0
	ds_read_b128 v[80:83], v220 offset:16
	ds_read_b128 v[84:87], v220 offset:32
	ds_read_b128 v[88:91], v220 offset:48
	s_waitcnt lgkmcnt(8)
	v_pk_fma_f32 v[72:73], v[198:199], v[182:183], v[72:73] op_sel_hi:[0,1,1]
	v_pk_fma_f32 v[60:61], v[198:199], v[182:183], v[60:61] op_sel:[1,0,0]
	v_pk_fma_f32 v[48:49], v[200:201], v[182:183], v[48:49] op_sel_hi:[0,1,1]
	v_pk_fma_f32 v[32:33], v[200:201], v[182:183], v[32:33] op_sel:[1,0,0]
	v_pk_fma_f32 v[74:75], v[198:199], v[184:185], v[74:75] op_sel_hi:[0,1,1]
	v_pk_fma_f32 v[62:63], v[198:199], v[184:185], v[62:63] op_sel:[1,0,0]
	v_pk_fma_f32 v[50:51], v[200:201], v[184:185], v[50:51] op_sel_hi:[0,1,1]
	v_pk_fma_f32 v[34:35], v[200:201], v[184:185], v[34:35] op_sel:[1,0,0]
	v_pk_fma_f32 v[68:69], v[198:199], v[186:187], v[68:69] op_sel_hi:[0,1,1]
	v_pk_fma_f32 v[52:53], v[198:199], v[186:187], v[52:53] op_sel:[1,0,0]
	v_pk_fma_f32 v[40:41], v[200:201], v[186:187], v[40:41] op_sel_hi:[0,1,1]
	v_pk_fma_f32 v[24:25], v[200:201], v[186:187], v[24:25] op_sel:[1,0,0]
	v_pk_fma_f32 v[70:71], v[198:199], v[188:189], v[70:71] op_sel_hi:[0,1,1]
	v_pk_fma_f32 v[54:55], v[198:199], v[188:189], v[54:55] op_sel:[1,0,0]
	v_pk_fma_f32 v[42:43], v[200:201], v[188:189], v[42:43] op_sel_hi:[0,1,1]
	v_pk_fma_f32 v[26:27], v[200:201], v[188:189], v[26:27] op_sel:[1,0,0]
	v_pk_fma_f32 v[64:65], v[198:199], v[190:191], v[64:65] op_sel_hi:[0,1,1]
	v_pk_fma_f32 v[44:45], v[198:199], v[190:191], v[44:45] op_sel:[1,0,0]
	v_pk_fma_f32 v[28:29], v[200:201], v[190:191], v[28:29] op_sel_hi:[0,1,1]
	v_pk_fma_f32 v[16:17], v[200:201], v[190:191], v[16:17] op_sel:[1,0,0]
	v_pk_fma_f32 v[66:67], v[198:199], v[192:193], v[66:67] op_sel_hi:[0,1,1]
	v_pk_fma_f32 v[46:47], v[198:199], v[192:193], v[46:47] op_sel:[1,0,0]
	v_pk_fma_f32 v[30:31], v[200:201], v[192:193], v[30:31] op_sel_hi:[0,1,1]
	v_pk_fma_f32 v[18:19], v[200:201], v[192:193], v[18:19] op_sel:[1,0,0]
	v_pk_fma_f32 v[56:57], v[198:199], v[194:195], v[56:57] op_sel_hi:[0,1,1]
	v_pk_fma_f32 v[36:37], v[198:199], v[194:195], v[36:37] op_sel:[1,0,0]
	v_pk_fma_f32 v[20:21], v[200:201], v[194:195], v[20:21] op_sel_hi:[0,1,1]
	v_pk_fma_f32 v[12:13], v[200:201], v[194:195], v[12:13] op_sel:[1,0,0]
	v_pk_fma_f32 v[58:59], v[198:199], v[196:197], v[58:59] op_sel_hi:[0,1,1]
	v_pk_fma_f32 v[38:39], v[198:199], v[196:197], v[38:39] op_sel:[1,0,0]
	v_pk_fma_f32 v[22:23], v[200:201], v[196:197], v[22:23] op_sel_hi:[0,1,1]
	v_pk_fma_f32 v[14:15], v[200:201], v[196:197], v[14:15] op_sel:[1,0,0]
	s_waitcnt lgkmcnt(4)
	v_pk_mul_f32 v[202:203], v[72:73], v[92:93]
	v_pk_mul_f32 v[204:205], v[74:75], v[94:95]
	v_pk_mul_f32 v[206:207], v[60:61], v[92:93]
	v_pk_mul_f32 v[208:209], v[62:63], v[94:95]
	v_pk_mul_f32 v[210:211], v[48:49], v[92:93]
	v_pk_mul_f32 v[212:213], v[50:51], v[94:95]
	v_pk_mul_f32 v[214:215], v[32:33], v[92:93]
	v_pk_mul_f32 v[216:217], v[34:35], v[94:95]
	v_pk_fma_f32 v[202:203], v[68:69], v[96:97], v[202:203]
	v_pk_fma_f32 v[204:205], v[70:71], v[98:99], v[204:205]
	v_pk_fma_f32 v[206:207], v[52:53], v[96:97], v[206:207]
	v_pk_fma_f32 v[208:209], v[54:55], v[98:99], v[208:209]
	v_pk_fma_f32 v[210:211], v[40:41], v[96:97], v[210:211]
	v_pk_fma_f32 v[212:213], v[42:43], v[98:99], v[212:213]
	v_pk_fma_f32 v[214:215], v[24:25], v[96:97], v[214:215]
	v_pk_fma_f32 v[216:217], v[26:27], v[98:99], v[216:217]
	v_pk_fma_f32 v[202:203], v[64:65], v[100:101], v[202:203]
	v_pk_fma_f32 v[204:205], v[66:67], v[102:103], v[204:205]
	v_pk_fma_f32 v[206:207], v[44:45], v[100:101], v[206:207]
	v_pk_fma_f32 v[208:209], v[46:47], v[102:103], v[208:209]
	v_pk_fma_f32 v[210:211], v[28:29], v[100:101], v[210:211]
	v_pk_fma_f32 v[212:213], v[30:31], v[102:103], v[212:213]
	v_pk_fma_f32 v[214:215], v[16:17], v[100:101], v[214:215]
	v_pk_fma_f32 v[216:217], v[18:19], v[102:103], v[216:217]
	v_pk_fma_f32 v[202:203], v[56:57], v[104:105], v[202:203]
	v_pk_fma_f32 v[204:205], v[58:59], v[106:107], v[204:205]
	v_pk_fma_f32 v[206:207], v[36:37], v[104:105], v[206:207]
	v_pk_fma_f32 v[208:209], v[38:39], v[106:107], v[208:209]
	v_pk_fma_f32 v[210:211], v[20:21], v[104:105], v[210:211]
	v_pk_fma_f32 v[212:213], v[22:23], v[106:107], v[212:213]
	v_pk_fma_f32 v[214:215], v[12:13], v[104:105], v[214:215]
	v_pk_fma_f32 v[216:217], v[14:15], v[106:107], v[216:217]
	v_pk_add_f32 v[202:203], v[202:203], v[204:205]
	v_pk_add_f32 v[206:207], v[206:207], v[208:209]
	v_pk_add_f32 v[210:211], v[210:211], v[212:213]
	v_pk_add_f32 v[214:215], v[214:215], v[216:217]
	ds_read_b128 v[92:95], v220 offset:256
	v_add_f32_e32 v202, v202, v203
	v_add_f32_e32 v206, v206, v207
	v_add_f32_e32 v210, v210, v211
	v_add_f32_e32 v214, v214, v215
	ds_read_b128 v[96:99], v220 offset:272
	v_add_f32_dpp v202, v202, v202 quad_perm:[1,0,3,2] row_mask:0xf bank_mask:0xf bound_ctrl:1
	v_add_f32_dpp v206, v206, v206 quad_perm:[1,0,3,2] row_mask:0xf bank_mask:0xf bound_ctrl:1
	v_add_f32_dpp v210, v210, v210 quad_perm:[1,0,3,2] row_mask:0xf bank_mask:0xf bound_ctrl:1
	v_add_f32_dpp v214, v214, v214 quad_perm:[1,0,3,2] row_mask:0xf bank_mask:0xf bound_ctrl:1
	ds_read_b128 v[100:103], v220 offset:288
	v_add_f32_dpp v202, v202, v202 quad_perm:[2,3,0,1] row_mask:0xf bank_mask:0xf bound_ctrl:1
	v_add_f32_dpp v206, v206, v206 quad_perm:[2,3,0,1] row_mask:0xf bank_mask:0xf bound_ctrl:1
	v_add_f32_dpp v210, v210, v210 quad_perm:[2,3,0,1] row_mask:0xf bank_mask:0xf bound_ctrl:1
	v_add_f32_dpp v214, v214, v214 quad_perm:[2,3,0,1] row_mask:0xf bank_mask:0xf bound_ctrl:1
	ds_read_b128 v[104:107], v220 offset:304
	ds_read_b128 v[108:111], v220 offset:512
	v_cvt_pk_bf16_f32 v240, v202, v206
	v_cvt_pk_bf16_f32 v241, v210, v214
	ds_read_b128 v[170:173], v220 offset:528
	ds_read_b128 v[174:177], v220 offset:544
	s_mov_b64 exec, s[6:7]
	global_store_dwordx2 v[238:239], v[240:241], off
	s_mov_b64 exec, -1
	ds_read_b128 v[178:181], v220 offset:560
	ds_read_b128 v[198:201], v236 offset:1280
	v_lshl_add_u64 v[238:239], v[238:239], 0, s[80:81]
	s_waitcnt lgkmcnt(9)
	v_pk_mul_f32 v[202:203], v[72:73], v[76:77]
	v_pk_mul_f32 v[204:205], v[74:75], v[78:79]
	v_pk_mul_f32 v[206:207], v[60:61], v[76:77]
	v_pk_mul_f32 v[208:209], v[62:63], v[78:79]
	v_pk_mul_f32 v[210:211], v[48:49], v[76:77]
	v_pk_mul_f32 v[212:213], v[50:51], v[78:79]
	v_pk_mul_f32 v[214:215], v[32:33], v[76:77]
	v_pk_mul_f32 v[216:217], v[34:35], v[78:79]
	v_pk_fma_f32 v[202:203], v[68:69], v[80:81], v[202:203]
	v_pk_fma_f32 v[204:205], v[70:71], v[82:83], v[204:205]
	v_pk_fma_f32 v[206:207], v[52:53], v[80:81], v[206:207]
	v_pk_fma_f32 v[208:209], v[54:55], v[82:83], v[208:209]
	v_pk_fma_f32 v[210:211], v[40:41], v[80:81], v[210:211]
	v_pk_fma_f32 v[212:213], v[42:43], v[82:83], v[212:213]
	v_pk_fma_f32 v[214:215], v[24:25], v[80:81], v[214:215]
	v_pk_fma_f32 v[216:217], v[26:27], v[82:83], v[216:217]
	v_pk_fma_f32 v[202:203], v[64:65], v[84:85], v[202:203]
	v_pk_fma_f32 v[204:205], v[66:67], v[86:87], v[204:205]
	v_pk_fma_f32 v[206:207], v[44:45], v[84:85], v[206:207]
	v_pk_fma_f32 v[208:209], v[46:47], v[86:87], v[208:209]
	v_pk_fma_f32 v[210:211], v[28:29], v[84:85], v[210:211]
	v_pk_fma_f32 v[212:213], v[30:31], v[86:87], v[212:213]
	v_pk_fma_f32 v[214:215], v[16:17], v[84:85], v[214:215]
	v_pk_fma_f32 v[216:217], v[18:19], v[86:87], v[216:217]
	v_pk_fma_f32 v[202:203], v[56:57], v[88:89], v[202:203]
	v_pk_fma_f32 v[204:205], v[58:59], v[90:91], v[204:205]
	v_pk_fma_f32 v[206:207], v[36:37], v[88:89], v[206:207]
	v_pk_fma_f32 v[208:209], v[38:39], v[90:91], v[208:209]
	v_pk_fma_f32 v[210:211], v[20:21], v[88:89], v[210:211]
	v_pk_fma_f32 v[212:213], v[22:23], v[90:91], v[212:213]
	v_pk_fma_f32 v[214:215], v[12:13], v[88:89], v[214:215]
	v_pk_fma_f32 v[216:217], v[14:15], v[90:91], v[216:217]
	s_waitcnt lgkmcnt(1)
	v_pk_add_f32 v[202:203], v[202:203], v[204:205]
	v_pk_add_f32 v[206:207], v[206:207], v[208:209]
	v_pk_add_f32 v[210:211], v[210:211], v[212:213]
	v_pk_add_f32 v[214:215], v[214:215], v[216:217]
	ds_read_b128 v[182:185], v220 offset:768
	v_add_f32_e32 v202, v202, v203
	v_add_f32_e32 v206, v206, v207
	v_add_f32_e32 v210, v210, v211
	v_add_f32_e32 v214, v214, v215
	ds_read_b128 v[186:189], v220 offset:784
	v_add_f32_dpp v202, v202, v202 quad_perm:[1,0,3,2] row_mask:0xf bank_mask:0xf bound_ctrl:1
	v_add_f32_dpp v206, v206, v206 quad_perm:[1,0,3,2] row_mask:0xf bank_mask:0xf bound_ctrl:1
	v_add_f32_dpp v210, v210, v210 quad_perm:[1,0,3,2] row_mask:0xf bank_mask:0xf bound_ctrl:1
	v_add_f32_dpp v214, v214, v214 quad_perm:[1,0,3,2] row_mask:0xf bank_mask:0xf bound_ctrl:1
	ds_read_b128 v[190:193], v220 offset:800
	v_add_f32_dpp v202, v202, v202 quad_perm:[2,3,0,1] row_mask:0xf bank_mask:0xf bound_ctrl:1
	v_add_f32_dpp v206, v206, v206 quad_perm:[2,3,0,1] row_mask:0xf bank_mask:0xf bound_ctrl:1
	v_add_f32_dpp v210, v210, v210 quad_perm:[2,3,0,1] row_mask:0xf bank_mask:0xf bound_ctrl:1
	v_add_f32_dpp v214, v214, v214 quad_perm:[2,3,0,1] row_mask:0xf bank_mask:0xf bound_ctrl:1
	ds_read_b128 v[194:197], v220 offset:816
	v_pk_mul_f32 v[204:205], v[108:109], v[202:203] op_sel_hi:[1,0]
	v_pk_mul_f32 v[208:209], v[108:109], v[206:207] op_sel_hi:[1,0]
	v_pk_mul_f32 v[212:213], v[108:109], v[210:211] op_sel_hi:[1,0]
	v_pk_mul_f32 v[108:109], v[108:109], v[214:215] op_sel_hi:[1,0]
	v_pk_fma_f32 v[72:73], v[72:73], v[92:93], v[204:205]
	v_pk_fma_f32 v[60:61], v[60:61], v[92:93], v[208:209]
	v_pk_fma_f32 v[48:49], v[48:49], v[92:93], v[212:213]
	v_pk_fma_f32 v[32:33], v[32:33], v[92:93], v[108:109]
	v_pk_mul_f32 v[216:217], v[110:111], v[202:203] op_sel_hi:[1,0]
	v_pk_mul_f32 v[242:243], v[110:111], v[206:207] op_sel_hi:[1,0]
	v_pk_mul_f32 v[244:245], v[110:111], v[210:211] op_sel_hi:[1,0]
	v_pk_mul_f32 v[110:111], v[110:111], v[214:215] op_sel_hi:[1,0]
	v_pk_fma_f32 v[74:75], v[74:75], v[94:95], v[216:217]
	v_pk_fma_f32 v[62:63], v[62:63], v[94:95], v[242:243]
	v_pk_fma_f32 v[50:51], v[50:51], v[94:95], v[244:245]
	v_pk_fma_f32 v[34:35], v[34:35], v[94:95], v[110:111]
	v_pk_mul_f32 v[204:205], v[170:171], v[202:203] op_sel_hi:[1,0]
	v_pk_mul_f32 v[208:209], v[170:171], v[206:207] op_sel_hi:[1,0]
	v_pk_mul_f32 v[212:213], v[170:171], v[210:211] op_sel_hi:[1,0]
	v_pk_mul_f32 v[170:171], v[170:171], v[214:215] op_sel_hi:[1,0]
	v_pk_fma_f32 v[68:69], v[68:69], v[96:97], v[204:205]
	v_pk_fma_f32 v[52:53], v[52:53], v[96:97], v[208:209]
	v_pk_fma_f32 v[40:41], v[40:41], v[96:97], v[212:213]
	v_pk_fma_f32 v[24:25], v[24:25], v[96:97], v[170:171]
	v_pk_mul_f32 v[216:217], v[172:173], v[202:203] op_sel_hi:[1,0]
	v_pk_mul_f32 v[242:243], v[172:173], v[206:207] op_sel_hi:[1,0]
	v_pk_mul_f32 v[244:245], v[172:173], v[210:211] op_sel_hi:[1,0]
	v_pk_mul_f32 v[172:173], v[172:173], v[214:215] op_sel_hi:[1,0]
	v_pk_fma_f32 v[70:71], v[70:71], v[98:99], v[216:217]
	v_pk_fma_f32 v[54:55], v[54:55], v[98:99], v[242:243]
	v_pk_fma_f32 v[42:43], v[42:43], v[98:99], v[244:245]
	v_pk_fma_f32 v[26:27], v[26:27], v[98:99], v[172:173]
	v_pk_mul_f32 v[204:205], v[174:175], v[202:203] op_sel_hi:[1,0]
	v_pk_mul_f32 v[208:209], v[174:175], v[206:207] op_sel_hi:[1,0]
	v_pk_mul_f32 v[212:213], v[174:175], v[210:211] op_sel_hi:[1,0]
	v_pk_mul_f32 v[174:175], v[174:175], v[214:215] op_sel_hi:[1,0]
	v_pk_fma_f32 v[64:65], v[64:65], v[100:101], v[204:205]
	v_pk_fma_f32 v[44:45], v[44:45], v[100:101], v[208:209]
	v_pk_fma_f32 v[28:29], v[28:29], v[100:101], v[212:213]
	v_pk_fma_f32 v[16:17], v[16:17], v[100:101], v[174:175]
	v_pk_mul_f32 v[216:217], v[176:177], v[202:203] op_sel_hi:[1,0]
	v_pk_mul_f32 v[242:243], v[176:177], v[206:207] op_sel_hi:[1,0]
	v_pk_mul_f32 v[244:245], v[176:177], v[210:211] op_sel_hi:[1,0]
	v_pk_mul_f32 v[176:177], v[176:177], v[214:215] op_sel_hi:[1,0]
	v_pk_fma_f32 v[66:67], v[66:67], v[102:103], v[216:217]
	v_pk_fma_f32 v[46:47], v[46:47], v[102:103], v[242:243]
	v_pk_fma_f32 v[30:31], v[30:31], v[102:103], v[244:245]
	v_pk_fma_f32 v[18:19], v[18:19], v[102:103], v[176:177]
	v_pk_mul_f32 v[204:205], v[178:179], v[202:203] op_sel_hi:[1,0]
	v_pk_mul_f32 v[208:209], v[178:179], v[206:207] op_sel_hi:[1,0]
	v_pk_mul_f32 v[212:213], v[178:179], v[210:211] op_sel_hi:[1,0]
	v_pk_mul_f32 v[178:179], v[178:179], v[214:215] op_sel_hi:[1,0]
	v_pk_fma_f32 v[56:57], v[56:57], v[104:105], v[204:205]
	v_pk_fma_f32 v[36:37], v[36:37], v[104:105], v[208:209]
	v_pk_fma_f32 v[20:21], v[20:21], v[104:105], v[212:213]
	v_pk_fma_f32 v[12:13], v[12:13], v[104:105], v[178:179]
	v_pk_mul_f32 v[216:217], v[180:181], v[202:203] op_sel_hi:[1,0]
	v_pk_mul_f32 v[242:243], v[180:181], v[206:207] op_sel_hi:[1,0]
	v_pk_mul_f32 v[244:245], v[180:181], v[210:211] op_sel_hi:[1,0]
	v_pk_mul_f32 v[180:181], v[180:181], v[214:215] op_sel_hi:[1,0]
	v_pk_fma_f32 v[58:59], v[58:59], v[106:107], v[216:217]
	v_pk_fma_f32 v[38:39], v[38:39], v[106:107], v[242:243]
	v_pk_fma_f32 v[22:23], v[22:23], v[106:107], v[244:245]
	v_pk_fma_f32 v[14:15], v[14:15], v[106:107], v[180:181]
	ds_read_b128 v[92:95], v220 offset:1024
	ds_read_b128 v[96:99], v220 offset:1040
	ds_read_b128 v[100:103], v220 offset:1056
	ds_read_b128 v[104:107], v220 offset:1072
	ds_read_b128 v[76:79], v221 offset:0
	ds_read_b128 v[80:83], v221 offset:16
	ds_read_b128 v[84:87], v221 offset:32
	ds_read_b128 v[88:91], v221 offset:48
	s_waitcnt lgkmcnt(8)
	v_pk_fma_f32 v[72:73], v[198:199], v[182:183], v[72:73] op_sel_hi:[0,1,1]
	v_pk_fma_f32 v[60:61], v[198:199], v[182:183], v[60:61] op_sel:[1,0,0]
	v_pk_fma_f32 v[48:49], v[200:201], v[182:183], v[48:49] op_sel_hi:[0,1,1]
	v_pk_fma_f32 v[32:33], v[200:201], v[182:183], v[32:33] op_sel:[1,0,0]
	v_pk_fma_f32 v[74:75], v[198:199], v[184:185], v[74:75] op_sel_hi:[0,1,1]
	v_pk_fma_f32 v[62:63], v[198:199], v[184:185], v[62:63] op_sel:[1,0,0]
	v_pk_fma_f32 v[50:51], v[200:201], v[184:185], v[50:51] op_sel_hi:[0,1,1]
	v_pk_fma_f32 v[34:35], v[200:201], v[184:185], v[34:35] op_sel:[1,0,0]
	v_pk_fma_f32 v[68:69], v[198:199], v[186:187], v[68:69] op_sel_hi:[0,1,1]
	v_pk_fma_f32 v[52:53], v[198:199], v[186:187], v[52:53] op_sel:[1,0,0]
	v_pk_fma_f32 v[40:41], v[200:201], v[186:187], v[40:41] op_sel_hi:[0,1,1]
	v_pk_fma_f32 v[24:25], v[200:201], v[186:187], v[24:25] op_sel:[1,0,0]
	v_pk_fma_f32 v[70:71], v[198:199], v[188:189], v[70:71] op_sel_hi:[0,1,1]
	v_pk_fma_f32 v[54:55], v[198:199], v[188:189], v[54:55] op_sel:[1,0,0]
	v_pk_fma_f32 v[42:43], v[200:201], v[188:189], v[42:43] op_sel_hi:[0,1,1]
	v_pk_fma_f32 v[26:27], v[200:201], v[188:189], v[26:27] op_sel:[1,0,0]
	v_pk_fma_f32 v[64:65], v[198:199], v[190:191], v[64:65] op_sel_hi:[0,1,1]
	v_pk_fma_f32 v[44:45], v[198:199], v[190:191], v[44:45] op_sel:[1,0,0]
	v_pk_fma_f32 v[28:29], v[200:201], v[190:191], v[28:29] op_sel_hi:[0,1,1]
	v_pk_fma_f32 v[16:17], v[200:201], v[190:191], v[16:17] op_sel:[1,0,0]
	v_pk_fma_f32 v[66:67], v[198:199], v[192:193], v[66:67] op_sel_hi:[0,1,1]
	v_pk_fma_f32 v[46:47], v[198:199], v[192:193], v[46:47] op_sel:[1,0,0]
	v_pk_fma_f32 v[30:31], v[200:201], v[192:193], v[30:31] op_sel_hi:[0,1,1]
	v_pk_fma_f32 v[18:19], v[200:201], v[192:193], v[18:19] op_sel:[1,0,0]
	v_pk_fma_f32 v[56:57], v[198:199], v[194:195], v[56:57] op_sel_hi:[0,1,1]
	v_pk_fma_f32 v[36:37], v[198:199], v[194:195], v[36:37] op_sel:[1,0,0]
	v_pk_fma_f32 v[20:21], v[200:201], v[194:195], v[20:21] op_sel_hi:[0,1,1]
	v_pk_fma_f32 v[12:13], v[200:201], v[194:195], v[12:13] op_sel:[1,0,0]
	v_pk_fma_f32 v[58:59], v[198:199], v[196:197], v[58:59] op_sel_hi:[0,1,1]
	v_pk_fma_f32 v[38:39], v[198:199], v[196:197], v[38:39] op_sel:[1,0,0]
	v_pk_fma_f32 v[22:23], v[200:201], v[196:197], v[22:23] op_sel_hi:[0,1,1]
	v_pk_fma_f32 v[14:15], v[200:201], v[196:197], v[14:15] op_sel:[1,0,0]
	s_waitcnt lgkmcnt(4)
	v_pk_mul_f32 v[202:203], v[72:73], v[92:93]
	v_pk_mul_f32 v[204:205], v[74:75], v[94:95]
	v_pk_mul_f32 v[206:207], v[60:61], v[92:93]
	v_pk_mul_f32 v[208:209], v[62:63], v[94:95]
	v_pk_mul_f32 v[210:211], v[48:49], v[92:93]
	v_pk_mul_f32 v[212:213], v[50:51], v[94:95]
	v_pk_mul_f32 v[214:215], v[32:33], v[92:93]
	v_pk_mul_f32 v[216:217], v[34:35], v[94:95]
	v_pk_fma_f32 v[202:203], v[68:69], v[96:97], v[202:203]
	v_pk_fma_f32 v[204:205], v[70:71], v[98:99], v[204:205]
	v_pk_fma_f32 v[206:207], v[52:53], v[96:97], v[206:207]
	v_pk_fma_f32 v[208:209], v[54:55], v[98:99], v[208:209]
	v_pk_fma_f32 v[210:211], v[40:41], v[96:97], v[210:211]
	v_pk_fma_f32 v[212:213], v[42:43], v[98:99], v[212:213]
	v_pk_fma_f32 v[214:215], v[24:25], v[96:97], v[214:215]
	v_pk_fma_f32 v[216:217], v[26:27], v[98:99], v[216:217]
	v_pk_fma_f32 v[202:203], v[64:65], v[100:101], v[202:203]
	v_pk_fma_f32 v[204:205], v[66:67], v[102:103], v[204:205]
	v_pk_fma_f32 v[206:207], v[44:45], v[100:101], v[206:207]
	v_pk_fma_f32 v[208:209], v[46:47], v[102:103], v[208:209]
	v_pk_fma_f32 v[210:211], v[28:29], v[100:101], v[210:211]
	v_pk_fma_f32 v[212:213], v[30:31], v[102:103], v[212:213]
	v_pk_fma_f32 v[214:215], v[16:17], v[100:101], v[214:215]
	v_pk_fma_f32 v[216:217], v[18:19], v[102:103], v[216:217]
	v_pk_fma_f32 v[202:203], v[56:57], v[104:105], v[202:203]
	v_pk_fma_f32 v[204:205], v[58:59], v[106:107], v[204:205]
	v_pk_fma_f32 v[206:207], v[36:37], v[104:105], v[206:207]
	v_pk_fma_f32 v[208:209], v[38:39], v[106:107], v[208:209]
	v_pk_fma_f32 v[210:211], v[20:21], v[104:105], v[210:211]
	v_pk_fma_f32 v[212:213], v[22:23], v[106:107], v[212:213]
	v_pk_fma_f32 v[214:215], v[12:13], v[104:105], v[214:215]
	v_pk_fma_f32 v[216:217], v[14:15], v[106:107], v[216:217]
	v_pk_add_f32 v[202:203], v[202:203], v[204:205]
	v_pk_add_f32 v[206:207], v[206:207], v[208:209]
	v_pk_add_f32 v[210:211], v[210:211], v[212:213]
	v_pk_add_f32 v[214:215], v[214:215], v[216:217]
	ds_read_b128 v[92:95], v221 offset:256
	v_add_f32_e32 v202, v202, v203
	v_add_f32_e32 v206, v206, v207
	v_add_f32_e32 v210, v210, v211
	v_add_f32_e32 v214, v214, v215
	ds_read_b128 v[96:99], v221 offset:272
	v_add_f32_dpp v202, v202, v202 quad_perm:[1,0,3,2] row_mask:0xf bank_mask:0xf bound_ctrl:1
	v_add_f32_dpp v206, v206, v206 quad_perm:[1,0,3,2] row_mask:0xf bank_mask:0xf bound_ctrl:1
	v_add_f32_dpp v210, v210, v210 quad_perm:[1,0,3,2] row_mask:0xf bank_mask:0xf bound_ctrl:1
	v_add_f32_dpp v214, v214, v214 quad_perm:[1,0,3,2] row_mask:0xf bank_mask:0xf bound_ctrl:1
	ds_read_b128 v[100:103], v221 offset:288
	v_add_f32_dpp v202, v202, v202 quad_perm:[2,3,0,1] row_mask:0xf bank_mask:0xf bound_ctrl:1
	v_add_f32_dpp v206, v206, v206 quad_perm:[2,3,0,1] row_mask:0xf bank_mask:0xf bound_ctrl:1
	v_add_f32_dpp v210, v210, v210 quad_perm:[2,3,0,1] row_mask:0xf bank_mask:0xf bound_ctrl:1
	v_add_f32_dpp v214, v214, v214 quad_perm:[2,3,0,1] row_mask:0xf bank_mask:0xf bound_ctrl:1
	ds_read_b128 v[104:107], v221 offset:304
	ds_read_b128 v[108:111], v221 offset:512
	v_cvt_pk_bf16_f32 v240, v202, v206
	v_cvt_pk_bf16_f32 v241, v210, v214
	ds_read_b128 v[170:173], v221 offset:528
	ds_read_b128 v[174:177], v221 offset:544
	s_mov_b64 exec, s[6:7]
	global_store_dwordx2 v[238:239], v[240:241], off
	s_mov_b64 exec, -1
	ds_read_b128 v[178:181], v221 offset:560
	ds_read_b128 v[198:201], v237 offset:1280
	v_lshl_add_u64 v[238:239], v[238:239], 0, s[80:81]
	s_waitcnt lgkmcnt(9)
	v_pk_mul_f32 v[202:203], v[72:73], v[76:77]
	v_pk_mul_f32 v[204:205], v[74:75], v[78:79]
	v_pk_mul_f32 v[206:207], v[60:61], v[76:77]
	v_pk_mul_f32 v[208:209], v[62:63], v[78:79]
	v_pk_mul_f32 v[210:211], v[48:49], v[76:77]
	v_pk_mul_f32 v[212:213], v[50:51], v[78:79]
	v_pk_mul_f32 v[214:215], v[32:33], v[76:77]
	v_pk_mul_f32 v[216:217], v[34:35], v[78:79]
	v_pk_fma_f32 v[202:203], v[68:69], v[80:81], v[202:203]
	v_pk_fma_f32 v[204:205], v[70:71], v[82:83], v[204:205]
	v_pk_fma_f32 v[206:207], v[52:53], v[80:81], v[206:207]
	v_pk_fma_f32 v[208:209], v[54:55], v[82:83], v[208:209]
	v_pk_fma_f32 v[210:211], v[40:41], v[80:81], v[210:211]
	v_pk_fma_f32 v[212:213], v[42:43], v[82:83], v[212:213]
	v_pk_fma_f32 v[214:215], v[24:25], v[80:81], v[214:215]
	v_pk_fma_f32 v[216:217], v[26:27], v[82:83], v[216:217]
	v_pk_fma_f32 v[202:203], v[64:65], v[84:85], v[202:203]
	v_pk_fma_f32 v[204:205], v[66:67], v[86:87], v[204:205]
	v_pk_fma_f32 v[206:207], v[44:45], v[84:85], v[206:207]
	v_pk_fma_f32 v[208:209], v[46:47], v[86:87], v[208:209]
	v_pk_fma_f32 v[210:211], v[28:29], v[84:85], v[210:211]
	v_pk_fma_f32 v[212:213], v[30:31], v[86:87], v[212:213]
	v_pk_fma_f32 v[214:215], v[16:17], v[84:85], v[214:215]
	v_pk_fma_f32 v[216:217], v[18:19], v[86:87], v[216:217]
	v_pk_fma_f32 v[202:203], v[56:57], v[88:89], v[202:203]
	v_pk_fma_f32 v[204:205], v[58:59], v[90:91], v[204:205]
	v_pk_fma_f32 v[206:207], v[36:37], v[88:89], v[206:207]
	v_pk_fma_f32 v[208:209], v[38:39], v[90:91], v[208:209]
	v_pk_fma_f32 v[210:211], v[20:21], v[88:89], v[210:211]
	v_pk_fma_f32 v[212:213], v[22:23], v[90:91], v[212:213]
	v_pk_fma_f32 v[214:215], v[12:13], v[88:89], v[214:215]
	v_pk_fma_f32 v[216:217], v[14:15], v[90:91], v[216:217]
	s_waitcnt lgkmcnt(1)
	v_pk_add_f32 v[202:203], v[202:203], v[204:205]
	v_pk_add_f32 v[206:207], v[206:207], v[208:209]
	v_pk_add_f32 v[210:211], v[210:211], v[212:213]
	v_pk_add_f32 v[214:215], v[214:215], v[216:217]
	ds_read_b128 v[182:185], v221 offset:768
	v_add_f32_e32 v202, v202, v203
	v_add_f32_e32 v206, v206, v207
	v_add_f32_e32 v210, v210, v211
	v_add_f32_e32 v214, v214, v215
	ds_read_b128 v[186:189], v221 offset:784
	v_add_f32_dpp v202, v202, v202 quad_perm:[1,0,3,2] row_mask:0xf bank_mask:0xf bound_ctrl:1
	v_add_f32_dpp v206, v206, v206 quad_perm:[1,0,3,2] row_mask:0xf bank_mask:0xf bound_ctrl:1
	v_add_f32_dpp v210, v210, v210 quad_perm:[1,0,3,2] row_mask:0xf bank_mask:0xf bound_ctrl:1
	v_add_f32_dpp v214, v214, v214 quad_perm:[1,0,3,2] row_mask:0xf bank_mask:0xf bound_ctrl:1
	ds_read_b128 v[190:193], v221 offset:800
	v_add_f32_dpp v202, v202, v202 quad_perm:[2,3,0,1] row_mask:0xf bank_mask:0xf bound_ctrl:1
	v_add_f32_dpp v206, v206, v206 quad_perm:[2,3,0,1] row_mask:0xf bank_mask:0xf bound_ctrl:1
	v_add_f32_dpp v210, v210, v210 quad_perm:[2,3,0,1] row_mask:0xf bank_mask:0xf bound_ctrl:1
	v_add_f32_dpp v214, v214, v214 quad_perm:[2,3,0,1] row_mask:0xf bank_mask:0xf bound_ctrl:1
	ds_read_b128 v[194:197], v221 offset:816
	v_pk_mul_f32 v[204:205], v[108:109], v[202:203] op_sel_hi:[1,0]
	v_pk_mul_f32 v[208:209], v[108:109], v[206:207] op_sel_hi:[1,0]
	v_pk_mul_f32 v[212:213], v[108:109], v[210:211] op_sel_hi:[1,0]
	v_pk_mul_f32 v[108:109], v[108:109], v[214:215] op_sel_hi:[1,0]
	v_pk_fma_f32 v[72:73], v[72:73], v[92:93], v[204:205]
	v_pk_fma_f32 v[60:61], v[60:61], v[92:93], v[208:209]
	v_pk_fma_f32 v[48:49], v[48:49], v[92:93], v[212:213]
	v_pk_fma_f32 v[32:33], v[32:33], v[92:93], v[108:109]
	v_pk_mul_f32 v[216:217], v[110:111], v[202:203] op_sel_hi:[1,0]
	v_pk_mul_f32 v[242:243], v[110:111], v[206:207] op_sel_hi:[1,0]
	v_pk_mul_f32 v[244:245], v[110:111], v[210:211] op_sel_hi:[1,0]
	v_pk_mul_f32 v[110:111], v[110:111], v[214:215] op_sel_hi:[1,0]
	v_pk_fma_f32 v[74:75], v[74:75], v[94:95], v[216:217]
	v_pk_fma_f32 v[62:63], v[62:63], v[94:95], v[242:243]
	v_pk_fma_f32 v[50:51], v[50:51], v[94:95], v[244:245]
	v_pk_fma_f32 v[34:35], v[34:35], v[94:95], v[110:111]
	v_pk_mul_f32 v[204:205], v[170:171], v[202:203] op_sel_hi:[1,0]
	v_pk_mul_f32 v[208:209], v[170:171], v[206:207] op_sel_hi:[1,0]
	v_pk_mul_f32 v[212:213], v[170:171], v[210:211] op_sel_hi:[1,0]
	v_pk_mul_f32 v[170:171], v[170:171], v[214:215] op_sel_hi:[1,0]
	v_pk_fma_f32 v[68:69], v[68:69], v[96:97], v[204:205]
	v_pk_fma_f32 v[52:53], v[52:53], v[96:97], v[208:209]
	v_pk_fma_f32 v[40:41], v[40:41], v[96:97], v[212:213]
	v_pk_fma_f32 v[24:25], v[24:25], v[96:97], v[170:171]
	v_pk_mul_f32 v[216:217], v[172:173], v[202:203] op_sel_hi:[1,0]
	v_pk_mul_f32 v[242:243], v[172:173], v[206:207] op_sel_hi:[1,0]
	v_pk_mul_f32 v[244:245], v[172:173], v[210:211] op_sel_hi:[1,0]
	v_pk_mul_f32 v[172:173], v[172:173], v[214:215] op_sel_hi:[1,0]
	v_pk_fma_f32 v[70:71], v[70:71], v[98:99], v[216:217]
	v_pk_fma_f32 v[54:55], v[54:55], v[98:99], v[242:243]
	v_pk_fma_f32 v[42:43], v[42:43], v[98:99], v[244:245]
	v_pk_fma_f32 v[26:27], v[26:27], v[98:99], v[172:173]
	v_pk_mul_f32 v[204:205], v[174:175], v[202:203] op_sel_hi:[1,0]
	v_pk_mul_f32 v[208:209], v[174:175], v[206:207] op_sel_hi:[1,0]
	v_pk_mul_f32 v[212:213], v[174:175], v[210:211] op_sel_hi:[1,0]
	v_pk_mul_f32 v[174:175], v[174:175], v[214:215] op_sel_hi:[1,0]
	v_pk_fma_f32 v[64:65], v[64:65], v[100:101], v[204:205]
	v_pk_fma_f32 v[44:45], v[44:45], v[100:101], v[208:209]
	v_pk_fma_f32 v[28:29], v[28:29], v[100:101], v[212:213]
	v_pk_fma_f32 v[16:17], v[16:17], v[100:101], v[174:175]
	v_pk_mul_f32 v[216:217], v[176:177], v[202:203] op_sel_hi:[1,0]
	v_pk_mul_f32 v[242:243], v[176:177], v[206:207] op_sel_hi:[1,0]
	v_pk_mul_f32 v[244:245], v[176:177], v[210:211] op_sel_hi:[1,0]
	v_pk_mul_f32 v[176:177], v[176:177], v[214:215] op_sel_hi:[1,0]
	v_pk_fma_f32 v[66:67], v[66:67], v[102:103], v[216:217]
	v_pk_fma_f32 v[46:47], v[46:47], v[102:103], v[242:243]
	v_pk_fma_f32 v[30:31], v[30:31], v[102:103], v[244:245]
	v_pk_fma_f32 v[18:19], v[18:19], v[102:103], v[176:177]
	v_pk_mul_f32 v[204:205], v[178:179], v[202:203] op_sel_hi:[1,0]
	v_pk_mul_f32 v[208:209], v[178:179], v[206:207] op_sel_hi:[1,0]
	v_pk_mul_f32 v[212:213], v[178:179], v[210:211] op_sel_hi:[1,0]
	v_pk_mul_f32 v[178:179], v[178:179], v[214:215] op_sel_hi:[1,0]
	v_pk_fma_f32 v[56:57], v[56:57], v[104:105], v[204:205]
	v_pk_fma_f32 v[36:37], v[36:37], v[104:105], v[208:209]
	v_pk_fma_f32 v[20:21], v[20:21], v[104:105], v[212:213]
	v_pk_fma_f32 v[12:13], v[12:13], v[104:105], v[178:179]
	v_pk_mul_f32 v[216:217], v[180:181], v[202:203] op_sel_hi:[1,0]
	v_pk_mul_f32 v[242:243], v[180:181], v[206:207] op_sel_hi:[1,0]
	v_pk_mul_f32 v[244:245], v[180:181], v[210:211] op_sel_hi:[1,0]
	v_pk_mul_f32 v[180:181], v[180:181], v[214:215] op_sel_hi:[1,0]
	v_pk_fma_f32 v[58:59], v[58:59], v[106:107], v[216:217]
	v_pk_fma_f32 v[38:39], v[38:39], v[106:107], v[242:243]
	v_pk_fma_f32 v[22:23], v[22:23], v[106:107], v[244:245]
	v_pk_fma_f32 v[14:15], v[14:15], v[106:107], v[180:181]
	ds_read_b128 v[92:95], v221 offset:1024
	ds_read_b128 v[96:99], v221 offset:1040
	ds_read_b128 v[100:103], v221 offset:1056
	ds_read_b128 v[104:107], v221 offset:1072
	s_waitcnt lgkmcnt(4)
	v_pk_fma_f32 v[72:73], v[198:199], v[182:183], v[72:73] op_sel_hi:[0,1,1]
	v_pk_fma_f32 v[60:61], v[198:199], v[182:183], v[60:61] op_sel:[1,0,0]
	v_pk_fma_f32 v[48:49], v[200:201], v[182:183], v[48:49] op_sel_hi:[0,1,1]
	v_pk_fma_f32 v[32:33], v[200:201], v[182:183], v[32:33] op_sel:[1,0,0]
	v_pk_fma_f32 v[74:75], v[198:199], v[184:185], v[74:75] op_sel_hi:[0,1,1]
	v_pk_fma_f32 v[62:63], v[198:199], v[184:185], v[62:63] op_sel:[1,0,0]
	v_pk_fma_f32 v[50:51], v[200:201], v[184:185], v[50:51] op_sel_hi:[0,1,1]
	v_pk_fma_f32 v[34:35], v[200:201], v[184:185], v[34:35] op_sel:[1,0,0]
	v_pk_fma_f32 v[68:69], v[198:199], v[186:187], v[68:69] op_sel_hi:[0,1,1]
	v_pk_fma_f32 v[52:53], v[198:199], v[186:187], v[52:53] op_sel:[1,0,0]
	v_pk_fma_f32 v[40:41], v[200:201], v[186:187], v[40:41] op_sel_hi:[0,1,1]
	v_pk_fma_f32 v[24:25], v[200:201], v[186:187], v[24:25] op_sel:[1,0,0]
	v_pk_fma_f32 v[70:71], v[198:199], v[188:189], v[70:71] op_sel_hi:[0,1,1]
	v_pk_fma_f32 v[54:55], v[198:199], v[188:189], v[54:55] op_sel:[1,0,0]
	v_pk_fma_f32 v[42:43], v[200:201], v[188:189], v[42:43] op_sel_hi:[0,1,1]
	v_pk_fma_f32 v[26:27], v[200:201], v[188:189], v[26:27] op_sel:[1,0,0]
	v_pk_fma_f32 v[64:65], v[198:199], v[190:191], v[64:65] op_sel_hi:[0,1,1]
	v_pk_fma_f32 v[44:45], v[198:199], v[190:191], v[44:45] op_sel:[1,0,0]
	v_pk_fma_f32 v[28:29], v[200:201], v[190:191], v[28:29] op_sel_hi:[0,1,1]
	v_pk_fma_f32 v[16:17], v[200:201], v[190:191], v[16:17] op_sel:[1,0,0]
	v_pk_fma_f32 v[66:67], v[198:199], v[192:193], v[66:67] op_sel_hi:[0,1,1]
	v_pk_fma_f32 v[46:47], v[198:199], v[192:193], v[46:47] op_sel:[1,0,0]
	v_pk_fma_f32 v[30:31], v[200:201], v[192:193], v[30:31] op_sel_hi:[0,1,1]
	v_pk_fma_f32 v[18:19], v[200:201], v[192:193], v[18:19] op_sel:[1,0,0]
	v_pk_fma_f32 v[56:57], v[198:199], v[194:195], v[56:57] op_sel_hi:[0,1,1]
	v_pk_fma_f32 v[36:37], v[198:199], v[194:195], v[36:37] op_sel:[1,0,0]
	v_pk_fma_f32 v[20:21], v[200:201], v[194:195], v[20:21] op_sel_hi:[0,1,1]
	v_pk_fma_f32 v[12:13], v[200:201], v[194:195], v[12:13] op_sel:[1,0,0]
	v_pk_fma_f32 v[58:59], v[198:199], v[196:197], v[58:59] op_sel_hi:[0,1,1]
	v_pk_fma_f32 v[38:39], v[198:199], v[196:197], v[38:39] op_sel:[1,0,0]
	v_pk_fma_f32 v[22:23], v[200:201], v[196:197], v[22:23] op_sel_hi:[0,1,1]
	v_pk_fma_f32 v[14:15], v[200:201], v[196:197], v[14:15] op_sel:[1,0,0]
	s_waitcnt lgkmcnt(0)
	v_pk_mul_f32 v[202:203], v[72:73], v[92:93]
	v_pk_mul_f32 v[204:205], v[74:75], v[94:95]
	v_pk_mul_f32 v[206:207], v[60:61], v[92:93]
	v_pk_mul_f32 v[208:209], v[62:63], v[94:95]
	v_pk_mul_f32 v[210:211], v[48:49], v[92:93]
	v_pk_mul_f32 v[212:213], v[50:51], v[94:95]
	v_pk_mul_f32 v[214:215], v[32:33], v[92:93]
	v_pk_mul_f32 v[216:217], v[34:35], v[94:95]
	v_pk_fma_f32 v[202:203], v[68:69], v[96:97], v[202:203]
	v_pk_fma_f32 v[204:205], v[70:71], v[98:99], v[204:205]
	v_pk_fma_f32 v[206:207], v[52:53], v[96:97], v[206:207]
	v_pk_fma_f32 v[208:209], v[54:55], v[98:99], v[208:209]
	v_pk_fma_f32 v[210:211], v[40:41], v[96:97], v[210:211]
	v_pk_fma_f32 v[212:213], v[42:43], v[98:99], v[212:213]
	v_pk_fma_f32 v[214:215], v[24:25], v[96:97], v[214:215]
	v_pk_fma_f32 v[216:217], v[26:27], v[98:99], v[216:217]
	v_pk_fma_f32 v[202:203], v[64:65], v[100:101], v[202:203]
	v_pk_fma_f32 v[204:205], v[66:67], v[102:103], v[204:205]
	v_pk_fma_f32 v[206:207], v[44:45], v[100:101], v[206:207]
	v_pk_fma_f32 v[208:209], v[46:47], v[102:103], v[208:209]
	v_pk_fma_f32 v[210:211], v[28:29], v[100:101], v[210:211]
	v_pk_fma_f32 v[212:213], v[30:31], v[102:103], v[212:213]
	v_pk_fma_f32 v[214:215], v[16:17], v[100:101], v[214:215]
	v_pk_fma_f32 v[216:217], v[18:19], v[102:103], v[216:217]
	v_pk_fma_f32 v[202:203], v[56:57], v[104:105], v[202:203]
	v_pk_fma_f32 v[204:205], v[58:59], v[106:107], v[204:205]
	v_pk_fma_f32 v[206:207], v[36:37], v[104:105], v[206:207]
	v_pk_fma_f32 v[208:209], v[38:39], v[106:107], v[208:209]
	v_pk_fma_f32 v[210:211], v[20:21], v[104:105], v[210:211]
	v_pk_fma_f32 v[212:213], v[22:23], v[106:107], v[212:213]
	v_pk_fma_f32 v[214:215], v[12:13], v[104:105], v[214:215]
	v_pk_fma_f32 v[216:217], v[14:15], v[106:107], v[216:217]
	v_pk_add_f32 v[202:203], v[202:203], v[204:205]
	v_pk_add_f32 v[206:207], v[206:207], v[208:209]
	v_pk_add_f32 v[210:211], v[210:211], v[212:213]
	v_pk_add_f32 v[214:215], v[214:215], v[216:217]
	v_add_f32_e32 v202, v202, v203
	v_add_f32_e32 v206, v206, v207
	v_add_f32_e32 v210, v210, v211
	v_add_f32_e32 v214, v214, v215
	v_add_f32_dpp v202, v202, v202 quad_perm:[1,0,3,2] row_mask:0xf bank_mask:0xf bound_ctrl:1
	v_add_f32_dpp v206, v206, v206 quad_perm:[1,0,3,2] row_mask:0xf bank_mask:0xf bound_ctrl:1
	v_add_f32_dpp v210, v210, v210 quad_perm:[1,0,3,2] row_mask:0xf bank_mask:0xf bound_ctrl:1
	v_add_f32_dpp v214, v214, v214 quad_perm:[1,0,3,2] row_mask:0xf bank_mask:0xf bound_ctrl:1
	v_add_f32_dpp v202, v202, v202 quad_perm:[2,3,0,1] row_mask:0xf bank_mask:0xf bound_ctrl:1
	v_add_f32_dpp v206, v206, v206 quad_perm:[2,3,0,1] row_mask:0xf bank_mask:0xf bound_ctrl:1
	v_add_f32_dpp v210, v210, v210 quad_perm:[2,3,0,1] row_mask:0xf bank_mask:0xf bound_ctrl:1
	v_add_f32_dpp v214, v214, v214 quad_perm:[2,3,0,1] row_mask:0xf bank_mask:0xf bound_ctrl:1
	s_nop 0
	v_cvt_pk_bf16_f32 v240, v202, v206
	v_cvt_pk_bf16_f32 v241, v210, v214
	s_mov_b64 exec, s[6:7]
	global_store_dwordx2 v[238:239], v[240:241], off
	s_mov_b64 exec, -1
	s_waitcnt lgkmcnt(0)

.LBB0_1016:
	s_or_b64 exec, exec, s[14:15]
	s_lshl_b32 s14, s36, 1
	s_add_u32 s14, s39, s14
	v_lshlrev_b32_e32 v72, 16, v52
	v_and_b32_e32 v73, 0xffff0000, v52
	v_add_f32_e32 v52, v66, v67
	s_addc_u32 s15, s50, 0
	s_mul_i32 s20, s33, 0x180000
	v_max_f32_e32 v52, 0x179abe15, v52
	s_add_u32 s14, s14, s20
	s_waitcnt vmcnt(0)
	v_cvt_f32_u32_sdwa v60, v54 dst_sel:DWORD dst_unused:UNUSED_PAD src0_sel:WORD_0
	v_cvt_f32_u32_sdwa v61, v54 dst_sel:DWORD dst_unused:UNUSED_PAD src0_sel:WORD_1
	v_cvt_f32_u32_sdwa v54, v55 dst_sel:DWORD dst_unused:UNUSED_PAD src0_sel:WORD_0
	v_cvt_f32_u32_sdwa v55, v55 dst_sel:DWORD dst_unused:UNUSED_PAD src0_sel:WORD_1
	v_rsq_f32_e32 v52, v52
	s_addc_u32 s15, s15, 0
	v_lshl_add_u64 v[92:93], v[120:121], 1, s[14:15]
	s_and_b64 s[14:15], s[10:11], exec
	s_cselect_b32 s14, 4, 0x3f8
	v_add_u32_e32 v183, s2, v117
	v_pk_fma_f32 v[70:71], v[54:55], s[56:57], 0.5 op_sel_hi:[1,0,0]
	v_lshlrev_b32_e32 v74, 16, v53
	v_and_b32_e32 v75, 0xffff0000, v53
	v_pk_mul_f32 v[54:55], v[62:63], v[52:53] op_sel_hi:[1,0] neg_lo:[0,1] neg_hi:[0,1]
	v_pk_mul_f32 v[52:53], v[64:65], v[52:53] op_sel_hi:[1,0] neg_lo:[0,1] neg_hi:[0,1]
	v_add_u32_e32 v94, s14, v183
	v_pk_fma_f32 v[68:69], v[60:61], s[56:57], 0.5 op_sel_hi:[1,0,0]
	ds_write_b128 v230, v[52:55]
	ds_write_b128 v230, v[68:71] offset:256
	v_pk_mul_f32 v[54:55], v[56:57], v[54:55] neg_lo:[0,1] neg_hi:[0,1]
	v_pk_mul_f32 v[52:53], v[58:59], v[52:53] neg_lo:[0,1] neg_hi:[0,1]
	v_ashrrev_i32_e32 v95, 31, v94
	ds_write_b128 v230, v[52:55] offset:512
	ds_write_b128 v230, v[48:51] offset:768
	ds_write_b128 v230, v[44:47] offset:1024
	ds_write_b128 v230, v[72:75] offset:1280
	v_lshl_add_u64 v[44:45], s[30:31], 0, v[94:95]
	v_lshlrev_b64 v[44:45], 7, v[44:45]
	v_lshlrev_b32_e32 v48, 1, v112
	v_or_b32_e32 v44, v44, v48
	v_lshl_add_u64 v[46:47], s[86:87], 0, v[44:45]
	global_load_dwordx2 v[96:97], v[46:47], off
	v_lshl_add_u64 v[46:47], s[90:91], 0, v[44:45]
	s_cselect_b32 s14, 8, 0x3f4
	global_load_dwordx2 v[98:99], v[46:47], off
	v_lshl_add_u64 v[46:47], s[88:89], 0, v[44:45]
	v_add_u32_e32 v102, s14, v183
	global_load_dwordx2 v[100:101], v[46:47], off
	v_lshl_add_u64 v[46:47], s[16:17], 0, v[44:45]
	v_lshl_add_u64 v[44:45], s[34:35], 0, v[44:45]
	v_ashrrev_i32_e32 v103, 31, v102
	global_load_dwordx2 v[104:105], v[46:47], off
	global_load_dwordx2 v[106:107], v[44:45], off
	v_lshl_add_u64 v[44:45], s[30:31], 0, v[102:103]
	v_lshlrev_b64 v[44:45], 7, v[44:45]
	v_or_b32_e32 v44, v44, v48
	v_lshl_add_u64 v[46:47], s[86:87], 0, v[44:45]
	global_load_dwordx2 v[108:109], v[46:47], off
	v_lshl_add_u64 v[46:47], s[90:91], 0, v[44:45]
	global_load_dwordx2 v[110:111], v[46:47], off
	v_lshl_add_u64 v[46:47], s[88:89], 0, v[44:45]
	global_load_dwordx2 v[124:125], v[46:47], off
	v_lshl_add_u64 v[46:47], s[16:17], 0, v[44:45]
	v_lshl_add_u64 v[44:45], s[34:35], 0, v[44:45]
	global_load_dwordx2 v[126:127], v[46:47], off
	global_load_dwordx2 v[128:129], v[44:45], off
	s_lshl_b32 s14, s33, 2
	s_add_u32 s36, s12, s14
	s_addc_u32 s37, s13, 0
	s_and_b64 s[12:13], s[10:11], exec
	s_mov_b32 s14, 0
	s_cselect_b32 s33, 0, 0x1200
	s_and_b64 s[82:83], s[10:11], exec
	s_mov_b32 s92, 0x1200
	s_cselect_b32 s92, 0, s92
	s_mov_b32 s93, 0xc00
	s_cselect_b32 s93, 0x600, s93
	s_mov_b32 s96, 0x600
	s_cselect_b32 s96, 0xc00, s96
	s_mov_b32 s97, 0
	s_cselect_b32 s97, 0x1200, s97
	s_mov_b32 s80, 0xffffff80
	s_cselect_b32 s80, 0x80, s80
	s_cselect_b32 s81, 0, -1
	s_cselect_b32 s98, 0, 3
	v_add_u32_e32 v218, s92, v232
	v_add_u32_e32 v219, s93, v232
	v_add_u32_e32 v220, s96, v232
	v_add_u32_e32 v221, s97, v232
	v_lshl_add_u32 v228, v120, 2, s57
	v_add_u32_e32 v222, s92, v228
	v_add_u32_e32 v223, s93, v228
	v_add_u32_e32 v224, s96, v228
	v_add_u32_e32 v228, s97, v228

.LBB0_1018:
	s_add_i32 s82, s49, s98
	s_ashr_i32 s83, s82, 31
	s_lshl_b64 s[82:83], s[82:83], 7
	v_lshl_add_u64 v[250:251], v[92:93], 0, s[82:83]
	ds_read_b128 v[60:63], v218 offset:256
	ds_read_b128 v[64:67], v218 offset:272
	ds_read_b128 v[68:71], v218 offset:288
	ds_read_b128 v[72:75], v218 offset:304
	ds_read_b128 v[76:79], v218 offset:512
	ds_read_b128 v[80:83], v218 offset:528
	ds_read_b128 v[84:87], v218 offset:544
	ds_read_b128 v[88:91], v218 offset:560
	ds_read_b64 v[178:179], v222 offset:1280
	s_waitcnt lgkmcnt(9)
	v_pk_mul_f32 v[158:159], v[12:13], v[44:45]
	v_pk_mul_f32 v[160:161], v[14:15], v[46:47]
	v_pk_mul_f32 v[162:163], v[40:41], v[44:45]
	v_pk_mul_f32 v[164:165], v[42:43], v[46:47]
	v_pk_fma_f32 v[158:159], v[16:17], v[48:49], v[158:159]
	v_pk_fma_f32 v[160:161], v[18:19], v[50:51], v[160:161]
	v_pk_fma_f32 v[162:163], v[36:37], v[48:49], v[162:163]
	v_pk_fma_f32 v[164:165], v[38:39], v[50:51], v[164:165]
	v_pk_fma_f32 v[158:159], v[20:21], v[52:53], v[158:159]
	v_pk_fma_f32 v[160:161], v[22:23], v[54:55], v[160:161]
	v_pk_fma_f32 v[162:163], v[32:33], v[52:53], v[162:163]
	v_pk_fma_f32 v[164:165], v[34:35], v[54:55], v[164:165]
	v_pk_fma_f32 v[158:159], v[24:25], v[56:57], v[158:159]
	v_pk_fma_f32 v[160:161], v[26:27], v[58:59], v[160:161]
	v_pk_fma_f32 v[162:163], v[28:29], v[56:57], v[162:163]
	v_pk_fma_f32 v[164:165], v[30:31], v[58:59], v[164:165]
	v_pk_add_f32 v[158:159], v[158:159], v[160:161]
	v_pk_add_f32 v[162:163], v[162:163], v[164:165]
	s_waitcnt lgkmcnt(1)
	v_add_f32_e32 v158, v158, v159
	v_add_f32_e32 v162, v162, v163
	ds_read_b128 v[202:205], v218 offset:768
	ds_read_b128 v[206:209], v218 offset:784
	v_add_f32_dpp v158, v158, v158 quad_perm:[1,0,3,2] row_mask:0xf bank_mask:0xf bound_ctrl:1
	v_add_f32_dpp v162, v162, v162 quad_perm:[1,0,3,2] row_mask:0xf bank_mask:0xf bound_ctrl:1
	ds_read_b128 v[210:213], v218 offset:800
	ds_read_b128 v[214:217], v218 offset:816
	v_add_f32_dpp v158, v158, v158 quad_perm:[2,3,0,1] row_mask:0xf bank_mask:0xf bound_ctrl:1
	v_add_f32_dpp v162, v162, v162 quad_perm:[2,3,0,1] row_mask:0xf bank_mask:0xf bound_ctrl:1
	ds_read_b128 v[234:237], v218 offset:1024
	ds_read_b128 v[238:241], v218 offset:1040
	ds_read_b128 v[242:245], v218 offset:1056
	ds_read_b128 v[246:249], v218 offset:1072
	v_pk_mul_f32 v[170:171], v[76:77], v[158:159] op_sel_hi:[1,0]
	v_pk_mul_f32 v[76:77], v[76:77], v[162:163] op_sel_hi:[1,0]
	v_pk_fma_f32 v[12:13], v[12:13], v[60:61], v[170:171]
	v_pk_fma_f32 v[40:41], v[40:41], v[60:61], v[76:77]
	v_pk_mul_f32 v[172:173], v[78:79], v[158:159] op_sel_hi:[1,0]
	v_pk_mul_f32 v[78:79], v[78:79], v[162:163] op_sel_hi:[1,0]
	v_pk_fma_f32 v[14:15], v[14:15], v[62:63], v[172:173]
	v_pk_fma_f32 v[42:43], v[42:43], v[62:63], v[78:79]
	v_pk_mul_f32 v[174:175], v[80:81], v[158:159] op_sel_hi:[1,0]
	v_pk_mul_f32 v[80:81], v[80:81], v[162:163] op_sel_hi:[1,0]
	v_pk_fma_f32 v[16:17], v[16:17], v[64:65], v[174:175]
	v_pk_fma_f32 v[36:37], v[36:37], v[64:65], v[80:81]
	v_pk_mul_f32 v[176:177], v[82:83], v[158:159] op_sel_hi:[1,0]
	v_pk_mul_f32 v[82:83], v[82:83], v[162:163] op_sel_hi:[1,0]
	v_pk_fma_f32 v[18:19], v[18:19], v[66:67], v[176:177]
	v_pk_fma_f32 v[38:39], v[38:39], v[66:67], v[82:83]
	v_pk_mul_f32 v[170:171], v[84:85], v[158:159] op_sel_hi:[1,0]
	v_pk_mul_f32 v[84:85], v[84:85], v[162:163] op_sel_hi:[1,0]
	v_pk_fma_f32 v[20:21], v[20:21], v[68:69], v[170:171]
	v_pk_fma_f32 v[32:33], v[32:33], v[68:69], v[84:85]
	v_pk_mul_f32 v[172:173], v[86:87], v[158:159] op_sel_hi:[1,0]
	v_pk_mul_f32 v[86:87], v[86:87], v[162:163] op_sel_hi:[1,0]
	v_pk_fma_f32 v[22:23], v[22:23], v[70:71], v[172:173]
	v_pk_fma_f32 v[34:35], v[34:35], v[70:71], v[86:87]
	v_pk_mul_f32 v[174:175], v[88:89], v[158:159] op_sel_hi:[1,0]
	v_pk_mul_f32 v[88:89], v[88:89], v[162:163] op_sel_hi:[1,0]
	v_pk_fma_f32 v[24:25], v[24:25], v[72:73], v[174:175]
	v_pk_fma_f32 v[28:29], v[28:29], v[72:73], v[88:89]
	v_pk_mul_f32 v[176:177], v[90:91], v[158:159] op_sel_hi:[1,0]
	v_pk_mul_f32 v[90:91], v[90:91], v[162:163] op_sel_hi:[1,0]
	v_pk_fma_f32 v[26:27], v[26:27], v[74:75], v[176:177]
	v_pk_fma_f32 v[30:31], v[30:31], v[74:75], v[90:91]
	ds_read_b128 v[44:47], v219 offset:0
	ds_read_b128 v[48:51], v219 offset:16
	ds_read_b128 v[52:55], v219 offset:32
	ds_read_b128 v[56:59], v219 offset:48
	s_waitcnt lgkmcnt(8)
	v_pk_fma_f32 v[142:143], v[178:179], v[202:203], v[12:13] op_sel_hi:[0,1,1]
	v_pk_fma_f32 v[186:187], v[178:179], v[202:203], v[40:41] op_sel:[1,0,0]
	v_pk_fma_f32 v[144:145], v[178:179], v[204:205], v[14:15] op_sel_hi:[0,1,1]
	v_pk_fma_f32 v[188:189], v[178:179], v[204:205], v[42:43] op_sel:[1,0,0]
	v_pk_fma_f32 v[146:147], v[178:179], v[206:207], v[16:17] op_sel_hi:[0,1,1]
	v_pk_fma_f32 v[190:191], v[178:179], v[206:207], v[36:37] op_sel:[1,0,0]
	v_pk_fma_f32 v[148:149], v[178:179], v[208:209], v[18:19] op_sel_hi:[0,1,1]
	v_pk_fma_f32 v[192:193], v[178:179], v[208:209], v[38:39] op_sel:[1,0,0]
	v_pk_fma_f32 v[150:151], v[178:179], v[210:211], v[20:21] op_sel_hi:[0,1,1]
	v_pk_fma_f32 v[194:195], v[178:179], v[210:211], v[32:33] op_sel:[1,0,0]
	v_pk_fma_f32 v[152:153], v[178:179], v[212:213], v[22:23] op_sel_hi:[0,1,1]
	v_pk_fma_f32 v[196:197], v[178:179], v[212:213], v[34:35] op_sel:[1,0,0]
	v_pk_fma_f32 v[154:155], v[178:179], v[214:215], v[24:25] op_sel_hi:[0,1,1]
	v_pk_fma_f32 v[198:199], v[178:179], v[214:215], v[28:29] op_sel:[1,0,0]
	v_pk_fma_f32 v[156:157], v[178:179], v[216:217], v[26:27] op_sel_hi:[0,1,1]
	v_pk_fma_f32 v[200:201], v[178:179], v[216:217], v[30:31] op_sel:[1,0,0]
	s_waitcnt lgkmcnt(4)
	v_pk_mul_f32 v[170:171], v[142:143], v[234:235]
	v_pk_mul_f32 v[172:173], v[144:145], v[236:237]
	v_pk_mul_f32 v[174:175], v[186:187], v[234:235]
	v_pk_mul_f32 v[176:177], v[188:189], v[236:237]
	v_pk_fma_f32 v[170:171], v[146:147], v[238:239], v[170:171]
	v_pk_fma_f32 v[172:173], v[148:149], v[240:241], v[172:173]
	v_pk_fma_f32 v[174:175], v[190:191], v[238:239], v[174:175]
	v_pk_fma_f32 v[176:177], v[192:193], v[240:241], v[176:177]
	v_pk_fma_f32 v[170:171], v[150:151], v[242:243], v[170:171]
	v_pk_fma_f32 v[172:173], v[152:153], v[244:245], v[172:173]
	v_pk_fma_f32 v[174:175], v[194:195], v[242:243], v[174:175]
	v_pk_fma_f32 v[176:177], v[196:197], v[244:245], v[176:177]
	v_pk_fma_f32 v[170:171], v[154:155], v[246:247], v[170:171]
	v_pk_fma_f32 v[172:173], v[156:157], v[248:249], v[172:173]
	v_pk_fma_f32 v[174:175], v[198:199], v[246:247], v[174:175]
	v_pk_fma_f32 v[176:177], v[200:201], v[248:249], v[176:177]
	v_pk_add_f32 v[170:171], v[170:171], v[172:173]
	v_pk_add_f32 v[174:175], v[174:175], v[176:177]
	ds_read_b128 v[60:63], v219 offset:256
	v_add_f32_e32 v170, v170, v171
	v_add_f32_e32 v174, v174, v175
	ds_read_b128 v[64:67], v219 offset:272
	ds_read_b128 v[68:71], v219 offset:288
	v_add_f32_dpp v170, v170, v170 quad_perm:[1,0,3,2] row_mask:0xf bank_mask:0xf bound_ctrl:1
	v_add_f32_dpp v174, v174, v174 quad_perm:[1,0,3,2] row_mask:0xf bank_mask:0xf bound_ctrl:1
	ds_read_b128 v[72:75], v219 offset:304
	ds_read_b128 v[76:79], v219 offset:512
	v_add_f32_dpp v170, v170, v170 quad_perm:[2,3,0,1] row_mask:0xf bank_mask:0xf bound_ctrl:1
	v_add_f32_dpp v174, v174, v174 quad_perm:[2,3,0,1] row_mask:0xf bank_mask:0xf bound_ctrl:1
	ds_read_b128 v[80:83], v219 offset:528
	ds_read_b128 v[84:87], v219 offset:544
	v_cvt_pk_bf16_f32 v180, v170, v174
	s_mov_b64 exec, s[6:7]
	global_store_dword v[250:251], v180, off
	s_mov_b64 exec, -1
	ds_read_b128 v[88:91], v219 offset:560
	ds_read_b64 v[178:179], v223 offset:1280
	v_lshl_add_u64 v[250:251], v[250:251], 0, s[80:81]
	s_waitcnt lgkmcnt(9)
	v_pk_mul_f32 v[158:159], v[142:143], v[44:45]
	v_pk_mul_f32 v[160:161], v[144:145], v[46:47]
	v_pk_mul_f32 v[162:163], v[186:187], v[44:45]
	v_pk_mul_f32 v[164:165], v[188:189], v[46:47]
	v_pk_fma_f32 v[158:159], v[146:147], v[48:49], v[158:159]
	v_pk_fma_f32 v[160:161], v[148:149], v[50:51], v[160:161]
	v_pk_fma_f32 v[162:163], v[190:191], v[48:49], v[162:163]
	v_pk_fma_f32 v[164:165], v[192:193], v[50:51], v[164:165]
	v_pk_fma_f32 v[158:159], v[150:151], v[52:53], v[158:159]
	v_pk_fma_f32 v[160:161], v[152:153], v[54:55], v[160:161]
	v_pk_fma_f32 v[162:163], v[194:195], v[52:53], v[162:163]
	v_pk_fma_f32 v[164:165], v[196:197], v[54:55], v[164:165]
	v_pk_fma_f32 v[158:159], v[154:155], v[56:57], v[158:159]
	v_pk_fma_f32 v[160:161], v[156:157], v[58:59], v[160:161]
	v_pk_fma_f32 v[162:163], v[198:199], v[56:57], v[162:163]
	v_pk_fma_f32 v[164:165], v[200:201], v[58:59], v[164:165]
	v_pk_add_f32 v[158:159], v[158:159], v[160:161]
	v_pk_add_f32 v[162:163], v[162:163], v[164:165]
	s_waitcnt lgkmcnt(1)
	v_add_f32_e32 v158, v158, v159
	v_add_f32_e32 v162, v162, v163
	ds_read_b128 v[202:205], v219 offset:768
	ds_read_b128 v[206:209], v219 offset:784
	v_add_f32_dpp v158, v158, v158 quad_perm:[1,0,3,2] row_mask:0xf bank_mask:0xf bound_ctrl:1
	v_add_f32_dpp v162, v162, v162 quad_perm:[1,0,3,2] row_mask:0xf bank_mask:0xf bound_ctrl:1
	ds_read_b128 v[210:213], v219 offset:800
	ds_read_b128 v[214:217], v219 offset:816
	v_add_f32_dpp v158, v158, v158 quad_perm:[2,3,0,1] row_mask:0xf bank_mask:0xf bound_ctrl:1
	v_add_f32_dpp v162, v162, v162 quad_perm:[2,3,0,1] row_mask:0xf bank_mask:0xf bound_ctrl:1
	ds_read_b128 v[234:237], v219 offset:1024
	ds_read_b128 v[238:241], v219 offset:1040
	ds_read_b128 v[242:245], v219 offset:1056
	ds_read_b128 v[246:249], v219 offset:1072
	v_pk_mul_f32 v[170:171], v[76:77], v[158:159] op_sel_hi:[1,0]
	v_pk_mul_f32 v[76:77], v[76:77], v[162:163] op_sel_hi:[1,0]
	v_pk_fma_f32 v[142:143], v[142:143], v[60:61], v[170:171]
	v_pk_fma_f32 v[186:187], v[186:187], v[60:61], v[76:77]
	v_pk_mul_f32 v[172:173], v[78:79], v[158:159] op_sel_hi:[1,0]
	v_pk_mul_f32 v[78:79], v[78:79], v[162:163] op_sel_hi:[1,0]
	v_pk_fma_f32 v[144:145], v[144:145], v[62:63], v[172:173]
	v_pk_fma_f32 v[188:189], v[188:189], v[62:63], v[78:79]
	v_pk_mul_f32 v[174:175], v[80:81], v[158:159] op_sel_hi:[1,0]
	v_pk_mul_f32 v[80:81], v[80:81], v[162:163] op_sel_hi:[1,0]
	v_pk_fma_f32 v[146:147], v[146:147], v[64:65], v[174:175]
	v_pk_fma_f32 v[190:191], v[190:191], v[64:65], v[80:81]
	v_pk_mul_f32 v[176:177], v[82:83], v[158:159] op_sel_hi:[1,0]
	v_pk_mul_f32 v[82:83], v[82:83], v[162:163] op_sel_hi:[1,0]
	v_pk_fma_f32 v[148:149], v[148:149], v[66:67], v[176:177]
	v_pk_fma_f32 v[192:193], v[192:193], v[66:67], v[82:83]
	v_pk_mul_f32 v[170:171], v[84:85], v[158:159] op_sel_hi:[1,0]
	v_pk_mul_f32 v[84:85], v[84:85], v[162:163] op_sel_hi:[1,0]
	v_pk_fma_f32 v[150:151], v[150:151], v[68:69], v[170:171]
	v_pk_fma_f32 v[194:195], v[194:195], v[68:69], v[84:85]
	v_pk_mul_f32 v[172:173], v[86:87], v[158:159] op_sel_hi:[1,0]
	v_pk_mul_f32 v[86:87], v[86:87], v[162:163] op_sel_hi:[1,0]
	v_pk_fma_f32 v[152:153], v[152:153], v[70:71], v[172:173]
	v_pk_fma_f32 v[196:197], v[196:197], v[70:71], v[86:87]
	v_pk_mul_f32 v[174:175], v[88:89], v[158:159] op_sel_hi:[1,0]
	v_pk_mul_f32 v[88:89], v[88:89], v[162:163] op_sel_hi:[1,0]
	v_pk_fma_f32 v[154:155], v[154:155], v[72:73], v[174:175]
	v_pk_fma_f32 v[198:199], v[198:199], v[72:73], v[88:89]
	v_pk_mul_f32 v[176:177], v[90:91], v[158:159] op_sel_hi:[1,0]
	v_pk_mul_f32 v[90:91], v[90:91], v[162:163] op_sel_hi:[1,0]
	v_pk_fma_f32 v[156:157], v[156:157], v[74:75], v[176:177]
	v_pk_fma_f32 v[200:201], v[200:201], v[74:75], v[90:91]
	ds_read_b128 v[44:47], v220 offset:0
	ds_read_b128 v[48:51], v220 offset:16
	ds_read_b128 v[52:55], v220 offset:32
	ds_read_b128 v[56:59], v220 offset:48
	s_waitcnt lgkmcnt(8)
	v_pk_fma_f32 v[12:13], v[178:179], v[202:203], v[142:143] op_sel_hi:[0,1,1]
	v_pk_fma_f32 v[40:41], v[178:179], v[202:203], v[186:187] op_sel:[1,0,0]
	v_pk_fma_f32 v[14:15], v[178:179], v[204:205], v[144:145] op_sel_hi:[0,1,1]
	v_pk_fma_f32 v[42:43], v[178:179], v[204:205], v[188:189] op_sel:[1,0,0]
	v_pk_fma_f32 v[16:17], v[178:179], v[206:207], v[146:147] op_sel_hi:[0,1,1]
	v_pk_fma_f32 v[36:37], v[178:179], v[206:207], v[190:191] op_sel:[1,0,0]
	v_pk_fma_f32 v[18:19], v[178:179], v[208:209], v[148:149] op_sel_hi:[0,1,1]
	v_pk_fma_f32 v[38:39], v[178:179], v[208:209], v[192:193] op_sel:[1,0,0]
	v_pk_fma_f32 v[20:21], v[178:179], v[210:211], v[150:151] op_sel_hi:[0,1,1]
	v_pk_fma_f32 v[32:33], v[178:179], v[210:211], v[194:195] op_sel:[1,0,0]
	v_pk_fma_f32 v[22:23], v[178:179], v[212:213], v[152:153] op_sel_hi:[0,1,1]
	v_pk_fma_f32 v[34:35], v[178:179], v[212:213], v[196:197] op_sel:[1,0,0]
	v_pk_fma_f32 v[24:25], v[178:179], v[214:215], v[154:155] op_sel_hi:[0,1,1]
	v_pk_fma_f32 v[28:29], v[178:179], v[214:215], v[198:199] op_sel:[1,0,0]
	v_pk_fma_f32 v[26:27], v[178:179], v[216:217], v[156:157] op_sel_hi:[0,1,1]
	v_pk_fma_f32 v[30:31], v[178:179], v[216:217], v[200:201] op_sel:[1,0,0]
	s_waitcnt lgkmcnt(4)
	v_pk_mul_f32 v[170:171], v[12:13], v[234:235]
	v_pk_mul_f32 v[172:173], v[14:15], v[236:237]
	v_pk_mul_f32 v[174:175], v[40:41], v[234:235]
	v_pk_mul_f32 v[176:177], v[42:43], v[236:237]
	v_pk_fma_f32 v[170:171], v[16:17], v[238:239], v[170:171]
	v_pk_fma_f32 v[172:173], v[18:19], v[240:241], v[172:173]
	v_pk_fma_f32 v[174:175], v[36:37], v[238:239], v[174:175]
	v_pk_fma_f32 v[176:177], v[38:39], v[240:241], v[176:177]
	v_pk_fma_f32 v[170:171], v[20:21], v[242:243], v[170:171]
	v_pk_fma_f32 v[172:173], v[22:23], v[244:245], v[172:173]
	v_pk_fma_f32 v[174:175], v[32:33], v[242:243], v[174:175]
	v_pk_fma_f32 v[176:177], v[34:35], v[244:245], v[176:177]
	v_pk_fma_f32 v[170:171], v[24:25], v[246:247], v[170:171]
	v_pk_fma_f32 v[172:173], v[26:27], v[248:249], v[172:173]
	v_pk_fma_f32 v[174:175], v[28:29], v[246:247], v[174:175]
	v_pk_fma_f32 v[176:177], v[30:31], v[248:249], v[176:177]
	v_pk_add_f32 v[170:171], v[170:171], v[172:173]
	v_pk_add_f32 v[174:175], v[174:175], v[176:177]
	ds_read_b128 v[60:63], v220 offset:256
	v_add_f32_e32 v170, v170, v171
	v_add_f32_e32 v174, v174, v175
	ds_read_b128 v[64:67], v220 offset:272
	ds_read_b128 v[68:71], v220 offset:288
	v_add_f32_dpp v170, v170, v170 quad_perm:[1,0,3,2] row_mask:0xf bank_mask:0xf bound_ctrl:1
	v_add_f32_dpp v174, v174, v174 quad_perm:[1,0,3,2] row_mask:0xf bank_mask:0xf bound_ctrl:1
	ds_read_b128 v[72:75], v220 offset:304
	ds_read_b128 v[76:79], v220 offset:512
	v_add_f32_dpp v170, v170, v170 quad_perm:[2,3,0,1] row_mask:0xf bank_mask:0xf bound_ctrl:1
	v_add_f32_dpp v174, v174, v174 quad_perm:[2,3,0,1] row_mask:0xf bank_mask:0xf bound_ctrl:1
	ds_read_b128 v[80:83], v220 offset:528
	ds_read_b128 v[84:87], v220 offset:544
	v_cvt_pk_bf16_f32 v180, v170, v174
	s_mov_b64 exec, s[6:7]
	global_store_dword v[250:251], v180, off
	s_mov_b64 exec, -1
	ds_read_b128 v[88:91], v220 offset:560
	ds_read_b64 v[178:179], v224 offset:1280
	v_lshl_add_u64 v[250:251], v[250:251], 0, s[80:81]
	s_waitcnt lgkmcnt(9)
	v_pk_mul_f32 v[158:159], v[12:13], v[44:45]
	v_pk_mul_f32 v[160:161], v[14:15], v[46:47]
	v_pk_mul_f32 v[162:163], v[40:41], v[44:45]
	v_pk_mul_f32 v[164:165], v[42:43], v[46:47]
	v_pk_fma_f32 v[158:159], v[16:17], v[48:49], v[158:159]
	v_pk_fma_f32 v[160:161], v[18:19], v[50:51], v[160:161]
	v_pk_fma_f32 v[162:163], v[36:37], v[48:49], v[162:163]
	v_pk_fma_f32 v[164:165], v[38:39], v[50:51], v[164:165]
	v_pk_fma_f32 v[158:159], v[20:21], v[52:53], v[158:159]
	v_pk_fma_f32 v[160:161], v[22:23], v[54:55], v[160:161]
	v_pk_fma_f32 v[162:163], v[32:33], v[52:53], v[162:163]
	v_pk_fma_f32 v[164:165], v[34:35], v[54:55], v[164:165]
	v_pk_fma_f32 v[158:159], v[24:25], v[56:57], v[158:159]
	v_pk_fma_f32 v[160:161], v[26:27], v[58:59], v[160:161]
	v_pk_fma_f32 v[162:163], v[28:29], v[56:57], v[162:163]
	v_pk_fma_f32 v[164:165], v[30:31], v[58:59], v[164:165]
	v_pk_add_f32 v[158:159], v[158:159], v[160:161]
	v_pk_add_f32 v[162:163], v[162:163], v[164:165]
	s_waitcnt lgkmcnt(1)
	v_add_f32_e32 v158, v158, v159
	v_add_f32_e32 v162, v162, v163
	ds_read_b128 v[202:205], v220 offset:768
	ds_read_b128 v[206:209], v220 offset:784
	v_add_f32_dpp v158, v158, v158 quad_perm:[1,0,3,2] row_mask:0xf bank_mask:0xf bound_ctrl:1
	v_add_f32_dpp v162, v162, v162 quad_perm:[1,0,3,2] row_mask:0xf bank_mask:0xf bound_ctrl:1
	ds_read_b128 v[210:213], v220 offset:800
	ds_read_b128 v[214:217], v220 offset:816
	v_add_f32_dpp v158, v158, v158 quad_perm:[2,3,0,1] row_mask:0xf bank_mask:0xf bound_ctrl:1
	v_add_f32_dpp v162, v162, v162 quad_perm:[2,3,0,1] row_mask:0xf bank_mask:0xf bound_ctrl:1
	ds_read_b128 v[234:237], v220 offset:1024
	ds_read_b128 v[238:241], v220 offset:1040
	ds_read_b128 v[242:245], v220 offset:1056
	ds_read_b128 v[246:249], v220 offset:1072
	v_pk_mul_f32 v[170:171], v[76:77], v[158:159] op_sel_hi:[1,0]
	v_pk_mul_f32 v[76:77], v[76:77], v[162:163] op_sel_hi:[1,0]
	v_pk_fma_f32 v[12:13], v[12:13], v[60:61], v[170:171]
	v_pk_fma_f32 v[40:41], v[40:41], v[60:61], v[76:77]
	v_pk_mul_f32 v[172:173], v[78:79], v[158:159] op_sel_hi:[1,0]
	v_pk_mul_f32 v[78:79], v[78:79], v[162:163] op_sel_hi:[1,0]
	v_pk_fma_f32 v[14:15], v[14:15], v[62:63], v[172:173]
	v_pk_fma_f32 v[42:43], v[42:43], v[62:63], v[78:79]
	v_pk_mul_f32 v[174:175], v[80:81], v[158:159] op_sel_hi:[1,0]
	v_pk_mul_f32 v[80:81], v[80:81], v[162:163] op_sel_hi:[1,0]
	v_pk_fma_f32 v[16:17], v[16:17], v[64:65], v[174:175]
	v_pk_fma_f32 v[36:37], v[36:37], v[64:65], v[80:81]
	v_pk_mul_f32 v[176:177], v[82:83], v[158:159] op_sel_hi:[1,0]
	v_pk_mul_f32 v[82:83], v[82:83], v[162:163] op_sel_hi:[1,0]
	v_pk_fma_f32 v[18:19], v[18:19], v[66:67], v[176:177]
	v_pk_fma_f32 v[38:39], v[38:39], v[66:67], v[82:83]
	v_pk_mul_f32 v[170:171], v[84:85], v[158:159] op_sel_hi:[1,0]
	v_pk_mul_f32 v[84:85], v[84:85], v[162:163] op_sel_hi:[1,0]
	v_pk_fma_f32 v[20:21], v[20:21], v[68:69], v[170:171]
	v_pk_fma_f32 v[32:33], v[32:33], v[68:69], v[84:85]
	v_pk_mul_f32 v[172:173], v[86:87], v[158:159] op_sel_hi:[1,0]
	v_pk_mul_f32 v[86:87], v[86:87], v[162:163] op_sel_hi:[1,0]
	v_pk_fma_f32 v[22:23], v[22:23], v[70:71], v[172:173]
	v_pk_fma_f32 v[34:35], v[34:35], v[70:71], v[86:87]
	v_pk_mul_f32 v[174:175], v[88:89], v[158:159] op_sel_hi:[1,0]
	v_pk_mul_f32 v[88:89], v[88:89], v[162:163] op_sel_hi:[1,0]
	v_pk_fma_f32 v[24:25], v[24:25], v[72:73], v[174:175]
	v_pk_fma_f32 v[28:29], v[28:29], v[72:73], v[88:89]
	v_pk_mul_f32 v[176:177], v[90:91], v[158:159] op_sel_hi:[1,0]
	v_pk_mul_f32 v[90:91], v[90:91], v[162:163] op_sel_hi:[1,0]
	v_pk_fma_f32 v[26:27], v[26:27], v[74:75], v[176:177]
	v_pk_fma_f32 v[30:31], v[30:31], v[74:75], v[90:91]
	ds_read_b128 v[44:47], v221 offset:0
	ds_read_b128 v[48:51], v221 offset:16
	ds_read_b128 v[52:55], v221 offset:32
	ds_read_b128 v[56:59], v221 offset:48
	s_waitcnt lgkmcnt(8)
	v_pk_fma_f32 v[142:143], v[178:179], v[202:203], v[12:13] op_sel_hi:[0,1,1]
	v_pk_fma_f32 v[186:187], v[178:179], v[202:203], v[40:41] op_sel:[1,0,0]
	v_pk_fma_f32 v[144:145], v[178:179], v[204:205], v[14:15] op_sel_hi:[0,1,1]
	v_pk_fma_f32 v[188:189], v[178:179], v[204:205], v[42:43] op_sel:[1,0,0]
	v_pk_fma_f32 v[146:147], v[178:179], v[206:207], v[16:17] op_sel_hi:[0,1,1]
	v_pk_fma_f32 v[190:191], v[178:179], v[206:207], v[36:37] op_sel:[1,0,0]
	v_pk_fma_f32 v[148:149], v[178:179], v[208:209], v[18:19] op_sel_hi:[0,1,1]
	v_pk_fma_f32 v[192:193], v[178:179], v[208:209], v[38:39] op_sel:[1,0,0]
	v_pk_fma_f32 v[150:151], v[178:179], v[210:211], v[20:21] op_sel_hi:[0,1,1]
	v_pk_fma_f32 v[194:195], v[178:179], v[210:211], v[32:33] op_sel:[1,0,0]
	v_pk_fma_f32 v[152:153], v[178:179], v[212:213], v[22:23] op_sel_hi:[0,1,1]
	v_pk_fma_f32 v[196:197], v[178:179], v[212:213], v[34:35] op_sel:[1,0,0]
	v_pk_fma_f32 v[154:155], v[178:179], v[214:215], v[24:25] op_sel_hi:[0,1,1]
	v_pk_fma_f32 v[198:199], v[178:179], v[214:215], v[28:29] op_sel:[1,0,0]
	v_pk_fma_f32 v[156:157], v[178:179], v[216:217], v[26:27] op_sel_hi:[0,1,1]
	v_pk_fma_f32 v[200:201], v[178:179], v[216:217], v[30:31] op_sel:[1,0,0]
	s_waitcnt lgkmcnt(4)
	v_pk_mul_f32 v[170:171], v[142:143], v[234:235]
	v_pk_mul_f32 v[172:173], v[144:145], v[236:237]
	v_pk_mul_f32 v[174:175], v[186:187], v[234:235]
	v_pk_mul_f32 v[176:177], v[188:189], v[236:237]
	v_pk_fma_f32 v[170:171], v[146:147], v[238:239], v[170:171]
	v_pk_fma_f32 v[172:173], v[148:149], v[240:241], v[172:173]
	v_pk_fma_f32 v[174:175], v[190:191], v[238:239], v[174:175]
	v_pk_fma_f32 v[176:177], v[192:193], v[240:241], v[176:177]
	v_pk_fma_f32 v[170:171], v[150:151], v[242:243], v[170:171]
	v_pk_fma_f32 v[172:173], v[152:153], v[244:245], v[172:173]
	v_pk_fma_f32 v[174:175], v[194:195], v[242:243], v[174:175]
	v_pk_fma_f32 v[176:177], v[196:197], v[244:245], v[176:177]
	v_pk_fma_f32 v[170:171], v[154:155], v[246:247], v[170:171]
	v_pk_fma_f32 v[172:173], v[156:157], v[248:249], v[172:173]
	v_pk_fma_f32 v[174:175], v[198:199], v[246:247], v[174:175]
	v_pk_fma_f32 v[176:177], v[200:201], v[248:249], v[176:177]
	v_pk_add_f32 v[170:171], v[170:171], v[172:173]
	v_pk_add_f32 v[174:175], v[174:175], v[176:177]
	ds_read_b128 v[60:63], v221 offset:256
	v_add_f32_e32 v170, v170, v171
	v_add_f32_e32 v174, v174, v175
	ds_read_b128 v[64:67], v221 offset:272
	ds_read_b128 v[68:71], v221 offset:288
	v_add_f32_dpp v170, v170, v170 quad_perm:[1,0,3,2] row_mask:0xf bank_mask:0xf bound_ctrl:1
	v_add_f32_dpp v174, v174, v174 quad_perm:[1,0,3,2] row_mask:0xf bank_mask:0xf bound_ctrl:1
	ds_read_b128 v[72:75], v221 offset:304
	ds_read_b128 v[76:79], v221 offset:512
	v_add_f32_dpp v170, v170, v170 quad_perm:[2,3,0,1] row_mask:0xf bank_mask:0xf bound_ctrl:1
	v_add_f32_dpp v174, v174, v174 quad_perm:[2,3,0,1] row_mask:0xf bank_mask:0xf bound_ctrl:1
	ds_read_b128 v[80:83], v221 offset:528
	ds_read_b128 v[84:87], v221 offset:544
	v_cvt_pk_bf16_f32 v180, v170, v174
	s_mov_b64 exec, s[6:7]
	global_store_dword v[250:251], v180, off
	s_mov_b64 exec, -1
	ds_read_b128 v[88:91], v221 offset:560
	ds_read_b64 v[178:179], v228 offset:1280
	v_lshl_add_u64 v[250:251], v[250:251], 0, s[80:81]
	s_waitcnt lgkmcnt(9)
	v_pk_mul_f32 v[158:159], v[142:143], v[44:45]
	v_pk_mul_f32 v[160:161], v[144:145], v[46:47]
	v_pk_mul_f32 v[162:163], v[186:187], v[44:45]
	v_pk_mul_f32 v[164:165], v[188:189], v[46:47]
	v_pk_fma_f32 v[158:159], v[146:147], v[48:49], v[158:159]
	v_pk_fma_f32 v[160:161], v[148:149], v[50:51], v[160:161]
	v_pk_fma_f32 v[162:163], v[190:191], v[48:49], v[162:163]
	v_pk_fma_f32 v[164:165], v[192:193], v[50:51], v[164:165]
	v_pk_fma_f32 v[158:159], v[150:151], v[52:53], v[158:159]
	v_pk_fma_f32 v[160:161], v[152:153], v[54:55], v[160:161]
	v_pk_fma_f32 v[162:163], v[194:195], v[52:53], v[162:163]
	v_pk_fma_f32 v[164:165], v[196:197], v[54:55], v[164:165]
	v_pk_fma_f32 v[158:159], v[154:155], v[56:57], v[158:159]
	v_pk_fma_f32 v[160:161], v[156:157], v[58:59], v[160:161]
	v_pk_fma_f32 v[162:163], v[198:199], v[56:57], v[162:163]
	v_pk_fma_f32 v[164:165], v[200:201], v[58:59], v[164:165]
	v_pk_add_f32 v[158:159], v[158:159], v[160:161]
	v_pk_add_f32 v[162:163], v[162:163], v[164:165]
	s_waitcnt lgkmcnt(1)
	v_add_f32_e32 v158, v158, v159
	v_add_f32_e32 v162, v162, v163
	ds_read_b128 v[202:205], v221 offset:768
	ds_read_b128 v[206:209], v221 offset:784
	v_add_f32_dpp v158, v158, v158 quad_perm:[1,0,3,2] row_mask:0xf bank_mask:0xf bound_ctrl:1
	v_add_f32_dpp v162, v162, v162 quad_perm:[1,0,3,2] row_mask:0xf bank_mask:0xf bound_ctrl:1
	ds_read_b128 v[210:213], v221 offset:800
	ds_read_b128 v[214:217], v221 offset:816
	v_add_f32_dpp v158, v158, v158 quad_perm:[2,3,0,1] row_mask:0xf bank_mask:0xf bound_ctrl:1
	v_add_f32_dpp v162, v162, v162 quad_perm:[2,3,0,1] row_mask:0xf bank_mask:0xf bound_ctrl:1
	ds_read_b128 v[234:237], v221 offset:1024
	ds_read_b128 v[238:241], v221 offset:1040
	ds_read_b128 v[242:245], v221 offset:1056
	ds_read_b128 v[246:249], v221 offset:1072
	v_pk_mul_f32 v[170:171], v[76:77], v[158:159] op_sel_hi:[1,0]
	v_pk_mul_f32 v[76:77], v[76:77], v[162:163] op_sel_hi:[1,0]
	v_pk_fma_f32 v[142:143], v[142:143], v[60:61], v[170:171]
	v_pk_fma_f32 v[186:187], v[186:187], v[60:61], v[76:77]
	v_pk_mul_f32 v[172:173], v[78:79], v[158:159] op_sel_hi:[1,0]
	v_pk_mul_f32 v[78:79], v[78:79], v[162:163] op_sel_hi:[1,0]
	v_pk_fma_f32 v[144:145], v[144:145], v[62:63], v[172:173]
	v_pk_fma_f32 v[188:189], v[188:189], v[62:63], v[78:79]
	v_pk_mul_f32 v[174:175], v[80:81], v[158:159] op_sel_hi:[1,0]
	v_pk_mul_f32 v[80:81], v[80:81], v[162:163] op_sel_hi:[1,0]
	v_pk_fma_f32 v[146:147], v[146:147], v[64:65], v[174:175]
	v_pk_fma_f32 v[190:191], v[190:191], v[64:65], v[80:81]
	v_pk_mul_f32 v[176:177], v[82:83], v[158:159] op_sel_hi:[1,0]
	v_pk_mul_f32 v[82:83], v[82:83], v[162:163] op_sel_hi:[1,0]
	v_pk_fma_f32 v[148:149], v[148:149], v[66:67], v[176:177]
	v_pk_fma_f32 v[192:193], v[192:193], v[66:67], v[82:83]
	v_pk_mul_f32 v[170:171], v[84:85], v[158:159] op_sel_hi:[1,0]
	v_pk_mul_f32 v[84:85], v[84:85], v[162:163] op_sel_hi:[1,0]
	v_pk_fma_f32 v[150:151], v[150:151], v[68:69], v[170:171]
	v_pk_fma_f32 v[194:195], v[194:195], v[68:69], v[84:85]
	v_pk_mul_f32 v[172:173], v[86:87], v[158:159] op_sel_hi:[1,0]
	v_pk_mul_f32 v[86:87], v[86:87], v[162:163] op_sel_hi:[1,0]
	v_pk_fma_f32 v[152:153], v[152:153], v[70:71], v[172:173]
	v_pk_fma_f32 v[196:197], v[196:197], v[70:71], v[86:87]
	v_pk_mul_f32 v[174:175], v[88:89], v[158:159] op_sel_hi:[1,0]
	v_pk_mul_f32 v[88:89], v[88:89], v[162:163] op_sel_hi:[1,0]
	v_pk_fma_f32 v[154:155], v[154:155], v[72:73], v[174:175]
	v_pk_fma_f32 v[198:199], v[198:199], v[72:73], v[88:89]
	v_pk_mul_f32 v[176:177], v[90:91], v[158:159] op_sel_hi:[1,0]
	v_pk_mul_f32 v[90:91], v[90:91], v[162:163] op_sel_hi:[1,0]
	v_pk_fma_f32 v[156:157], v[156:157], v[74:75], v[176:177]
	v_pk_fma_f32 v[200:201], v[200:201], v[74:75], v[90:91]
	s_waitcnt lgkmcnt(4)
	v_pk_fma_f32 v[12:13], v[178:179], v[202:203], v[142:143] op_sel_hi:[0,1,1]
	v_pk_fma_f32 v[40:41], v[178:179], v[202:203], v[186:187] op_sel:[1,0,0]
	v_pk_fma_f32 v[14:15], v[178:179], v[204:205], v[144:145] op_sel_hi:[0,1,1]
	v_pk_fma_f32 v[42:43], v[178:179], v[204:205], v[188:189] op_sel:[1,0,0]
	v_pk_fma_f32 v[16:17], v[178:179], v[206:207], v[146:147] op_sel_hi:[0,1,1]
	v_pk_fma_f32 v[36:37], v[178:179], v[206:207], v[190:191] op_sel:[1,0,0]
	v_pk_fma_f32 v[18:19], v[178:179], v[208:209], v[148:149] op_sel_hi:[0,1,1]
	v_pk_fma_f32 v[38:39], v[178:179], v[208:209], v[192:193] op_sel:[1,0,0]
	v_pk_fma_f32 v[20:21], v[178:179], v[210:211], v[150:151] op_sel_hi:[0,1,1]
	v_pk_fma_f32 v[32:33], v[178:179], v[210:211], v[194:195] op_sel:[1,0,0]
	v_pk_fma_f32 v[22:23], v[178:179], v[212:213], v[152:153] op_sel_hi:[0,1,1]
	v_pk_fma_f32 v[34:35], v[178:179], v[212:213], v[196:197] op_sel:[1,0,0]
	v_pk_fma_f32 v[24:25], v[178:179], v[214:215], v[154:155] op_sel_hi:[0,1,1]
	v_pk_fma_f32 v[28:29], v[178:179], v[214:215], v[198:199] op_sel:[1,0,0]
	v_pk_fma_f32 v[26:27], v[178:179], v[216:217], v[156:157] op_sel_hi:[0,1,1]
	v_pk_fma_f32 v[30:31], v[178:179], v[216:217], v[200:201] op_sel:[1,0,0]
	s_waitcnt lgkmcnt(0)
	v_pk_mul_f32 v[170:171], v[12:13], v[234:235]
	v_pk_mul_f32 v[172:173], v[14:15], v[236:237]
	v_pk_mul_f32 v[174:175], v[40:41], v[234:235]
	v_pk_mul_f32 v[176:177], v[42:43], v[236:237]
	v_pk_fma_f32 v[170:171], v[16:17], v[238:239], v[170:171]
	v_pk_fma_f32 v[172:173], v[18:19], v[240:241], v[172:173]
	v_pk_fma_f32 v[174:175], v[36:37], v[238:239], v[174:175]
	v_pk_fma_f32 v[176:177], v[38:39], v[240:241], v[176:177]
	v_pk_fma_f32 v[170:171], v[20:21], v[242:243], v[170:171]
	v_pk_fma_f32 v[172:173], v[22:23], v[244:245], v[172:173]
	v_pk_fma_f32 v[174:175], v[32:33], v[242:243], v[174:175]
	v_pk_fma_f32 v[176:177], v[34:35], v[244:245], v[176:177]
	v_pk_fma_f32 v[170:171], v[24:25], v[246:247], v[170:171]
	v_pk_fma_f32 v[172:173], v[26:27], v[248:249], v[172:173]
	v_pk_fma_f32 v[174:175], v[28:29], v[246:247], v[174:175]
	v_pk_fma_f32 v[176:177], v[30:31], v[248:249], v[176:177]
	v_pk_add_f32 v[170:171], v[170:171], v[172:173]
	v_pk_add_f32 v[174:175], v[174:175], v[176:177]
	s_nop 0
	v_add_f32_e32 v170, v170, v171
	v_add_f32_e32 v174, v174, v175
	s_nop 0
	s_nop 0
	v_add_f32_dpp v170, v170, v170 quad_perm:[1,0,3,2] row_mask:0xf bank_mask:0xf bound_ctrl:1
	v_add_f32_dpp v174, v174, v174 quad_perm:[1,0,3,2] row_mask:0xf bank_mask:0xf bound_ctrl:1
	s_nop 0
	s_nop 0
	v_add_f32_dpp v170, v170, v170 quad_perm:[2,3,0,1] row_mask:0xf bank_mask:0xf bound_ctrl:1
	v_add_f32_dpp v174, v174, v174 quad_perm:[2,3,0,1] row_mask:0xf bank_mask:0xf bound_ctrl:1
	s_nop 0
	s_nop 0
	v_cvt_pk_bf16_f32 v180, v170, v174
	s_mov_b64 exec, s[6:7]
	global_store_dword v[250:251], v180, off
	s_mov_b64 exec, -1
	s_waitcnt lgkmcnt(0)

.LBB0_1031:
	s_add_i32 s82, s43, s98
	s_ashr_i32 s83, s82, 31
	s_lshl_b64 s[82:83], s[82:83], 7
	v_lshl_add_u64 v[250:251], v[92:93], 0, s[82:83]
	ds_read_b128 v[60:63], v218 offset:256
	ds_read_b128 v[64:67], v218 offset:272
	ds_read_b128 v[68:71], v218 offset:288
	ds_read_b128 v[72:75], v218 offset:304
	ds_read_b128 v[76:79], v218 offset:512
	ds_read_b128 v[80:83], v218 offset:528
	ds_read_b128 v[84:87], v218 offset:544
	ds_read_b128 v[88:91], v218 offset:560
	ds_read_b64 v[178:179], v222 offset:1280
	s_waitcnt lgkmcnt(9)
	v_pk_mul_f32 v[158:159], v[12:13], v[44:45]
	v_pk_mul_f32 v[160:161], v[14:15], v[46:47]
	v_pk_mul_f32 v[162:163], v[40:41], v[44:45]
	v_pk_mul_f32 v[164:165], v[42:43], v[46:47]
	v_pk_fma_f32 v[158:159], v[16:17], v[48:49], v[158:159]
	v_pk_fma_f32 v[160:161], v[18:19], v[50:51], v[160:161]
	v_pk_fma_f32 v[162:163], v[36:37], v[48:49], v[162:163]
	v_pk_fma_f32 v[164:165], v[38:39], v[50:51], v[164:165]
	v_pk_fma_f32 v[158:159], v[20:21], v[52:53], v[158:159]
	v_pk_fma_f32 v[160:161], v[22:23], v[54:55], v[160:161]
	v_pk_fma_f32 v[162:163], v[32:33], v[52:53], v[162:163]
	v_pk_fma_f32 v[164:165], v[34:35], v[54:55], v[164:165]
	v_pk_fma_f32 v[158:159], v[24:25], v[56:57], v[158:159]
	v_pk_fma_f32 v[160:161], v[26:27], v[58:59], v[160:161]
	v_pk_fma_f32 v[162:163], v[28:29], v[56:57], v[162:163]
	v_pk_fma_f32 v[164:165], v[30:31], v[58:59], v[164:165]
	v_pk_add_f32 v[158:159], v[158:159], v[160:161]
	v_pk_add_f32 v[162:163], v[162:163], v[164:165]
	s_waitcnt lgkmcnt(1)
	v_add_f32_e32 v158, v158, v159
	v_add_f32_e32 v162, v162, v163
	ds_read_b128 v[202:205], v218 offset:768
	ds_read_b128 v[206:209], v218 offset:784
	v_add_f32_dpp v158, v158, v158 quad_perm:[1,0,3,2] row_mask:0xf bank_mask:0xf bound_ctrl:1
	v_add_f32_dpp v162, v162, v162 quad_perm:[1,0,3,2] row_mask:0xf bank_mask:0xf bound_ctrl:1
	ds_read_b128 v[210:213], v218 offset:800
	ds_read_b128 v[214:217], v218 offset:816
	v_add_f32_dpp v158, v158, v158 quad_perm:[2,3,0,1] row_mask:0xf bank_mask:0xf bound_ctrl:1
	v_add_f32_dpp v162, v162, v162 quad_perm:[2,3,0,1] row_mask:0xf bank_mask:0xf bound_ctrl:1
	ds_read_b128 v[234:237], v218 offset:1024
	ds_read_b128 v[238:241], v218 offset:1040
	ds_read_b128 v[242:245], v218 offset:1056
	ds_read_b128 v[246:249], v218 offset:1072
	v_pk_mul_f32 v[170:171], v[76:77], v[158:159] op_sel_hi:[1,0]
	v_pk_mul_f32 v[76:77], v[76:77], v[162:163] op_sel_hi:[1,0]
	v_pk_fma_f32 v[12:13], v[12:13], v[60:61], v[170:171]
	v_pk_fma_f32 v[40:41], v[40:41], v[60:61], v[76:77]
	v_pk_mul_f32 v[172:173], v[78:79], v[158:159] op_sel_hi:[1,0]
	v_pk_mul_f32 v[78:79], v[78:79], v[162:163] op_sel_hi:[1,0]
	v_pk_fma_f32 v[14:15], v[14:15], v[62:63], v[172:173]
	v_pk_fma_f32 v[42:43], v[42:43], v[62:63], v[78:79]
	v_pk_mul_f32 v[174:175], v[80:81], v[158:159] op_sel_hi:[1,0]
	v_pk_mul_f32 v[80:81], v[80:81], v[162:163] op_sel_hi:[1,0]
	v_pk_fma_f32 v[16:17], v[16:17], v[64:65], v[174:175]
	v_pk_fma_f32 v[36:37], v[36:37], v[64:65], v[80:81]
	v_pk_mul_f32 v[176:177], v[82:83], v[158:159] op_sel_hi:[1,0]
	v_pk_mul_f32 v[82:83], v[82:83], v[162:163] op_sel_hi:[1,0]
	v_pk_fma_f32 v[18:19], v[18:19], v[66:67], v[176:177]
	v_pk_fma_f32 v[38:39], v[38:39], v[66:67], v[82:83]
	v_pk_mul_f32 v[170:171], v[84:85], v[158:159] op_sel_hi:[1,0]
	v_pk_mul_f32 v[84:85], v[84:85], v[162:163] op_sel_hi:[1,0]
	v_pk_fma_f32 v[20:21], v[20:21], v[68:69], v[170:171]
	v_pk_fma_f32 v[32:33], v[32:33], v[68:69], v[84:85]
	v_pk_mul_f32 v[172:173], v[86:87], v[158:159] op_sel_hi:[1,0]
	v_pk_mul_f32 v[86:87], v[86:87], v[162:163] op_sel_hi:[1,0]
	v_pk_fma_f32 v[22:23], v[22:23], v[70:71], v[172:173]
	v_pk_fma_f32 v[34:35], v[34:35], v[70:71], v[86:87]
	v_pk_mul_f32 v[174:175], v[88:89], v[158:159] op_sel_hi:[1,0]
	v_pk_mul_f32 v[88:89], v[88:89], v[162:163] op_sel_hi:[1,0]
	v_pk_fma_f32 v[24:25], v[24:25], v[72:73], v[174:175]
	v_pk_fma_f32 v[28:29], v[28:29], v[72:73], v[88:89]
	v_pk_mul_f32 v[176:177], v[90:91], v[158:159] op_sel_hi:[1,0]
	v_pk_mul_f32 v[90:91], v[90:91], v[162:163] op_sel_hi:[1,0]
	v_pk_fma_f32 v[26:27], v[26:27], v[74:75], v[176:177]
	v_pk_fma_f32 v[30:31], v[30:31], v[74:75], v[90:91]
	ds_read_b128 v[44:47], v219 offset:0
	ds_read_b128 v[48:51], v219 offset:16
	ds_read_b128 v[52:55], v219 offset:32
	ds_read_b128 v[56:59], v219 offset:48
	s_waitcnt lgkmcnt(8)
	v_pk_fma_f32 v[142:143], v[178:179], v[202:203], v[12:13] op_sel_hi:[0,1,1]
	v_pk_fma_f32 v[186:187], v[178:179], v[202:203], v[40:41] op_sel:[1,0,0]
	v_pk_fma_f32 v[144:145], v[178:179], v[204:205], v[14:15] op_sel_hi:[0,1,1]
	v_pk_fma_f32 v[188:189], v[178:179], v[204:205], v[42:43] op_sel:[1,0,0]
	v_pk_fma_f32 v[146:147], v[178:179], v[206:207], v[16:17] op_sel_hi:[0,1,1]
	v_pk_fma_f32 v[190:191], v[178:179], v[206:207], v[36:37] op_sel:[1,0,0]
	v_pk_fma_f32 v[148:149], v[178:179], v[208:209], v[18:19] op_sel_hi:[0,1,1]
	v_pk_fma_f32 v[192:193], v[178:179], v[208:209], v[38:39] op_sel:[1,0,0]
	v_pk_fma_f32 v[150:151], v[178:179], v[210:211], v[20:21] op_sel_hi:[0,1,1]
	v_pk_fma_f32 v[194:195], v[178:179], v[210:211], v[32:33] op_sel:[1,0,0]
	v_pk_fma_f32 v[152:153], v[178:179], v[212:213], v[22:23] op_sel_hi:[0,1,1]
	v_pk_fma_f32 v[196:197], v[178:179], v[212:213], v[34:35] op_sel:[1,0,0]
	v_pk_fma_f32 v[154:155], v[178:179], v[214:215], v[24:25] op_sel_hi:[0,1,1]
	v_pk_fma_f32 v[198:199], v[178:179], v[214:215], v[28:29] op_sel:[1,0,0]
	v_pk_fma_f32 v[156:157], v[178:179], v[216:217], v[26:27] op_sel_hi:[0,1,1]
	v_pk_fma_f32 v[200:201], v[178:179], v[216:217], v[30:31] op_sel:[1,0,0]
	s_waitcnt lgkmcnt(4)
	v_pk_mul_f32 v[170:171], v[142:143], v[234:235]
	v_pk_mul_f32 v[172:173], v[144:145], v[236:237]
	v_pk_mul_f32 v[174:175], v[186:187], v[234:235]
	v_pk_mul_f32 v[176:177], v[188:189], v[236:237]
	v_pk_fma_f32 v[170:171], v[146:147], v[238:239], v[170:171]
	v_pk_fma_f32 v[172:173], v[148:149], v[240:241], v[172:173]
	v_pk_fma_f32 v[174:175], v[190:191], v[238:239], v[174:175]
	v_pk_fma_f32 v[176:177], v[192:193], v[240:241], v[176:177]
	v_pk_fma_f32 v[170:171], v[150:151], v[242:243], v[170:171]
	v_pk_fma_f32 v[172:173], v[152:153], v[244:245], v[172:173]
	v_pk_fma_f32 v[174:175], v[194:195], v[242:243], v[174:175]
	v_pk_fma_f32 v[176:177], v[196:197], v[244:245], v[176:177]
	v_pk_fma_f32 v[170:171], v[154:155], v[246:247], v[170:171]
	v_pk_fma_f32 v[172:173], v[156:157], v[248:249], v[172:173]
	v_pk_fma_f32 v[174:175], v[198:199], v[246:247], v[174:175]
	v_pk_fma_f32 v[176:177], v[200:201], v[248:249], v[176:177]
	v_pk_add_f32 v[170:171], v[170:171], v[172:173]
	v_pk_add_f32 v[174:175], v[174:175], v[176:177]
	ds_read_b128 v[60:63], v219 offset:256
	v_add_f32_e32 v170, v170, v171
	v_add_f32_e32 v174, v174, v175
	ds_read_b128 v[64:67], v219 offset:272
	ds_read_b128 v[68:71], v219 offset:288
	v_add_f32_dpp v170, v170, v170 quad_perm:[1,0,3,2] row_mask:0xf bank_mask:0xf bound_ctrl:1
	v_add_f32_dpp v174, v174, v174 quad_perm:[1,0,3,2] row_mask:0xf bank_mask:0xf bound_ctrl:1
	ds_read_b128 v[72:75], v219 offset:304
	ds_read_b128 v[76:79], v219 offset:512
	v_add_f32_dpp v170, v170, v170 quad_perm:[2,3,0,1] row_mask:0xf bank_mask:0xf bound_ctrl:1
	v_add_f32_dpp v174, v174, v174 quad_perm:[2,3,0,1] row_mask:0xf bank_mask:0xf bound_ctrl:1
	ds_read_b128 v[80:83], v219 offset:528
	ds_read_b128 v[84:87], v219 offset:544
	v_cvt_pk_bf16_f32 v180, v170, v174
	s_mov_b64 exec, s[6:7]
	global_store_dword v[250:251], v180, off
	s_mov_b64 exec, -1
	ds_read_b128 v[88:91], v219 offset:560
	ds_read_b64 v[178:179], v223 offset:1280
	v_lshl_add_u64 v[250:251], v[250:251], 0, s[80:81]
	s_waitcnt lgkmcnt(9)
	v_pk_mul_f32 v[158:159], v[142:143], v[44:45]
	v_pk_mul_f32 v[160:161], v[144:145], v[46:47]
	v_pk_mul_f32 v[162:163], v[186:187], v[44:45]
	v_pk_mul_f32 v[164:165], v[188:189], v[46:47]
	v_pk_fma_f32 v[158:159], v[146:147], v[48:49], v[158:159]
	v_pk_fma_f32 v[160:161], v[148:149], v[50:51], v[160:161]
	v_pk_fma_f32 v[162:163], v[190:191], v[48:49], v[162:163]
	v_pk_fma_f32 v[164:165], v[192:193], v[50:51], v[164:165]
	v_pk_fma_f32 v[158:159], v[150:151], v[52:53], v[158:159]
	v_pk_fma_f32 v[160:161], v[152:153], v[54:55], v[160:161]
	v_pk_fma_f32 v[162:163], v[194:195], v[52:53], v[162:163]
	v_pk_fma_f32 v[164:165], v[196:197], v[54:55], v[164:165]
	v_pk_fma_f32 v[158:159], v[154:155], v[56:57], v[158:159]
	v_pk_fma_f32 v[160:161], v[156:157], v[58:59], v[160:161]
	v_pk_fma_f32 v[162:163], v[198:199], v[56:57], v[162:163]
	v_pk_fma_f32 v[164:165], v[200:201], v[58:59], v[164:165]
	v_pk_add_f32 v[158:159], v[158:159], v[160:161]
	v_pk_add_f32 v[162:163], v[162:163], v[164:165]
	s_waitcnt lgkmcnt(1)
	v_add_f32_e32 v158, v158, v159
	v_add_f32_e32 v162, v162, v163
	ds_read_b128 v[202:205], v219 offset:768
	ds_read_b128 v[206:209], v219 offset:784
	v_add_f32_dpp v158, v158, v158 quad_perm:[1,0,3,2] row_mask:0xf bank_mask:0xf bound_ctrl:1
	v_add_f32_dpp v162, v162, v162 quad_perm:[1,0,3,2] row_mask:0xf bank_mask:0xf bound_ctrl:1
	ds_read_b128 v[210:213], v219 offset:800
	ds_read_b128 v[214:217], v219 offset:816
	v_add_f32_dpp v158, v158, v158 quad_perm:[2,3,0,1] row_mask:0xf bank_mask:0xf bound_ctrl:1
	v_add_f32_dpp v162, v162, v162 quad_perm:[2,3,0,1] row_mask:0xf bank_mask:0xf bound_ctrl:1
	ds_read_b128 v[234:237], v219 offset:1024
	ds_read_b128 v[238:241], v219 offset:1040
	ds_read_b128 v[242:245], v219 offset:1056
	ds_read_b128 v[246:249], v219 offset:1072
	v_pk_mul_f32 v[170:171], v[76:77], v[158:159] op_sel_hi:[1,0]
	v_pk_mul_f32 v[76:77], v[76:77], v[162:163] op_sel_hi:[1,0]
	v_pk_fma_f32 v[142:143], v[142:143], v[60:61], v[170:171]
	v_pk_fma_f32 v[186:187], v[186:187], v[60:61], v[76:77]
	v_pk_mul_f32 v[172:173], v[78:79], v[158:159] op_sel_hi:[1,0]
	v_pk_mul_f32 v[78:79], v[78:79], v[162:163] op_sel_hi:[1,0]
	v_pk_fma_f32 v[144:145], v[144:145], v[62:63], v[172:173]
	v_pk_fma_f32 v[188:189], v[188:189], v[62:63], v[78:79]
	v_pk_mul_f32 v[174:175], v[80:81], v[158:159] op_sel_hi:[1,0]
	v_pk_mul_f32 v[80:81], v[80:81], v[162:163] op_sel_hi:[1,0]
	v_pk_fma_f32 v[146:147], v[146:147], v[64:65], v[174:175]
	v_pk_fma_f32 v[190:191], v[190:191], v[64:65], v[80:81]
	v_pk_mul_f32 v[176:177], v[82:83], v[158:159] op_sel_hi:[1,0]
	v_pk_mul_f32 v[82:83], v[82:83], v[162:163] op_sel_hi:[1,0]
	v_pk_fma_f32 v[148:149], v[148:149], v[66:67], v[176:177]
	v_pk_fma_f32 v[192:193], v[192:193], v[66:67], v[82:83]
	v_pk_mul_f32 v[170:171], v[84:85], v[158:159] op_sel_hi:[1,0]
	v_pk_mul_f32 v[84:85], v[84:85], v[162:163] op_sel_hi:[1,0]
	v_pk_fma_f32 v[150:151], v[150:151], v[68:69], v[170:171]
	v_pk_fma_f32 v[194:195], v[194:195], v[68:69], v[84:85]
	v_pk_mul_f32 v[172:173], v[86:87], v[158:159] op_sel_hi:[1,0]
	v_pk_mul_f32 v[86:87], v[86:87], v[162:163] op_sel_hi:[1,0]
	v_pk_fma_f32 v[152:153], v[152:153], v[70:71], v[172:173]
	v_pk_fma_f32 v[196:197], v[196:197], v[70:71], v[86:87]
	v_pk_mul_f32 v[174:175], v[88:89], v[158:159] op_sel_hi:[1,0]
	v_pk_mul_f32 v[88:89], v[88:89], v[162:163] op_sel_hi:[1,0]
	v_pk_fma_f32 v[154:155], v[154:155], v[72:73], v[174:175]
	v_pk_fma_f32 v[198:199], v[198:199], v[72:73], v[88:89]
	v_pk_mul_f32 v[176:177], v[90:91], v[158:159] op_sel_hi:[1,0]
	v_pk_mul_f32 v[90:91], v[90:91], v[162:163] op_sel_hi:[1,0]
	v_pk_fma_f32 v[156:157], v[156:157], v[74:75], v[176:177]
	v_pk_fma_f32 v[200:201], v[200:201], v[74:75], v[90:91]
	ds_read_b128 v[44:47], v220 offset:0
	ds_read_b128 v[48:51], v220 offset:16
	ds_read_b128 v[52:55], v220 offset:32
	ds_read_b128 v[56:59], v220 offset:48
	s_waitcnt lgkmcnt(8)
	v_pk_fma_f32 v[12:13], v[178:179], v[202:203], v[142:143] op_sel_hi:[0,1,1]
	v_pk_fma_f32 v[40:41], v[178:179], v[202:203], v[186:187] op_sel:[1,0,0]
	v_pk_fma_f32 v[14:15], v[178:179], v[204:205], v[144:145] op_sel_hi:[0,1,1]
	v_pk_fma_f32 v[42:43], v[178:179], v[204:205], v[188:189] op_sel:[1,0,0]
	v_pk_fma_f32 v[16:17], v[178:179], v[206:207], v[146:147] op_sel_hi:[0,1,1]
	v_pk_fma_f32 v[36:37], v[178:179], v[206:207], v[190:191] op_sel:[1,0,0]
	v_pk_fma_f32 v[18:19], v[178:179], v[208:209], v[148:149] op_sel_hi:[0,1,1]
	v_pk_fma_f32 v[38:39], v[178:179], v[208:209], v[192:193] op_sel:[1,0,0]
	v_pk_fma_f32 v[20:21], v[178:179], v[210:211], v[150:151] op_sel_hi:[0,1,1]
	v_pk_fma_f32 v[32:33], v[178:179], v[210:211], v[194:195] op_sel:[1,0,0]
	v_pk_fma_f32 v[22:23], v[178:179], v[212:213], v[152:153] op_sel_hi:[0,1,1]
	v_pk_fma_f32 v[34:35], v[178:179], v[212:213], v[196:197] op_sel:[1,0,0]
	v_pk_fma_f32 v[24:25], v[178:179], v[214:215], v[154:155] op_sel_hi:[0,1,1]
	v_pk_fma_f32 v[28:29], v[178:179], v[214:215], v[198:199] op_sel:[1,0,0]
	v_pk_fma_f32 v[26:27], v[178:179], v[216:217], v[156:157] op_sel_hi:[0,1,1]
	v_pk_fma_f32 v[30:31], v[178:179], v[216:217], v[200:201] op_sel:[1,0,0]
	s_waitcnt lgkmcnt(4)
	v_pk_mul_f32 v[170:171], v[12:13], v[234:235]
	v_pk_mul_f32 v[172:173], v[14:15], v[236:237]
	v_pk_mul_f32 v[174:175], v[40:41], v[234:235]
	v_pk_mul_f32 v[176:177], v[42:43], v[236:237]
	v_pk_fma_f32 v[170:171], v[16:17], v[238:239], v[170:171]
	v_pk_fma_f32 v[172:173], v[18:19], v[240:241], v[172:173]
	v_pk_fma_f32 v[174:175], v[36:37], v[238:239], v[174:175]
	v_pk_fma_f32 v[176:177], v[38:39], v[240:241], v[176:177]
	v_pk_fma_f32 v[170:171], v[20:21], v[242:243], v[170:171]
	v_pk_fma_f32 v[172:173], v[22:23], v[244:245], v[172:173]
	v_pk_fma_f32 v[174:175], v[32:33], v[242:243], v[174:175]
	v_pk_fma_f32 v[176:177], v[34:35], v[244:245], v[176:177]
	v_pk_fma_f32 v[170:171], v[24:25], v[246:247], v[170:171]
	v_pk_fma_f32 v[172:173], v[26:27], v[248:249], v[172:173]
	v_pk_fma_f32 v[174:175], v[28:29], v[246:247], v[174:175]
	v_pk_fma_f32 v[176:177], v[30:31], v[248:249], v[176:177]
	v_pk_add_f32 v[170:171], v[170:171], v[172:173]
	v_pk_add_f32 v[174:175], v[174:175], v[176:177]
	ds_read_b128 v[60:63], v220 offset:256
	v_add_f32_e32 v170, v170, v171
	v_add_f32_e32 v174, v174, v175
	ds_read_b128 v[64:67], v220 offset:272
	ds_read_b128 v[68:71], v220 offset:288
	v_add_f32_dpp v170, v170, v170 quad_perm:[1,0,3,2] row_mask:0xf bank_mask:0xf bound_ctrl:1
	v_add_f32_dpp v174, v174, v174 quad_perm:[1,0,3,2] row_mask:0xf bank_mask:0xf bound_ctrl:1
	ds_read_b128 v[72:75], v220 offset:304
	ds_read_b128 v[76:79], v220 offset:512
	v_add_f32_dpp v170, v170, v170 quad_perm:[2,3,0,1] row_mask:0xf bank_mask:0xf bound_ctrl:1
	v_add_f32_dpp v174, v174, v174 quad_perm:[2,3,0,1] row_mask:0xf bank_mask:0xf bound_ctrl:1
	ds_read_b128 v[80:83], v220 offset:528
	ds_read_b128 v[84:87], v220 offset:544
	v_cvt_pk_bf16_f32 v180, v170, v174
	s_mov_b64 exec, s[6:7]
	global_store_dword v[250:251], v180, off
	s_mov_b64 exec, -1
	ds_read_b128 v[88:91], v220 offset:560
	ds_read_b64 v[178:179], v224 offset:1280
	v_lshl_add_u64 v[250:251], v[250:251], 0, s[80:81]
	s_waitcnt lgkmcnt(9)
	v_pk_mul_f32 v[158:159], v[12:13], v[44:45]
	v_pk_mul_f32 v[160:161], v[14:15], v[46:47]
	v_pk_mul_f32 v[162:163], v[40:41], v[44:45]
	v_pk_mul_f32 v[164:165], v[42:43], v[46:47]
	v_pk_fma_f32 v[158:159], v[16:17], v[48:49], v[158:159]
	v_pk_fma_f32 v[160:161], v[18:19], v[50:51], v[160:161]
	v_pk_fma_f32 v[162:163], v[36:37], v[48:49], v[162:163]
	v_pk_fma_f32 v[164:165], v[38:39], v[50:51], v[164:165]
	v_pk_fma_f32 v[158:159], v[20:21], v[52:53], v[158:159]
	v_pk_fma_f32 v[160:161], v[22:23], v[54:55], v[160:161]
	v_pk_fma_f32 v[162:163], v[32:33], v[52:53], v[162:163]
	v_pk_fma_f32 v[164:165], v[34:35], v[54:55], v[164:165]
	v_pk_fma_f32 v[158:159], v[24:25], v[56:57], v[158:159]
	v_pk_fma_f32 v[160:161], v[26:27], v[58:59], v[160:161]
	v_pk_fma_f32 v[162:163], v[28:29], v[56:57], v[162:163]
	v_pk_fma_f32 v[164:165], v[30:31], v[58:59], v[164:165]
	v_pk_add_f32 v[158:159], v[158:159], v[160:161]
	v_pk_add_f32 v[162:163], v[162:163], v[164:165]
	s_waitcnt lgkmcnt(1)
	v_add_f32_e32 v158, v158, v159
	v_add_f32_e32 v162, v162, v163
	ds_read_b128 v[202:205], v220 offset:768
	ds_read_b128 v[206:209], v220 offset:784
	v_add_f32_dpp v158, v158, v158 quad_perm:[1,0,3,2] row_mask:0xf bank_mask:0xf bound_ctrl:1
	v_add_f32_dpp v162, v162, v162 quad_perm:[1,0,3,2] row_mask:0xf bank_mask:0xf bound_ctrl:1
	ds_read_b128 v[210:213], v220 offset:800
	ds_read_b128 v[214:217], v220 offset:816
	v_add_f32_dpp v158, v158, v158 quad_perm:[2,3,0,1] row_mask:0xf bank_mask:0xf bound_ctrl:1
	v_add_f32_dpp v162, v162, v162 quad_perm:[2,3,0,1] row_mask:0xf bank_mask:0xf bound_ctrl:1
	ds_read_b128 v[234:237], v220 offset:1024
	ds_read_b128 v[238:241], v220 offset:1040
	ds_read_b128 v[242:245], v220 offset:1056
	ds_read_b128 v[246:249], v220 offset:1072
	v_pk_mul_f32 v[170:171], v[76:77], v[158:159] op_sel_hi:[1,0]
	v_pk_mul_f32 v[76:77], v[76:77], v[162:163] op_sel_hi:[1,0]
	v_pk_fma_f32 v[12:13], v[12:13], v[60:61], v[170:171]
	v_pk_fma_f32 v[40:41], v[40:41], v[60:61], v[76:77]
	v_pk_mul_f32 v[172:173], v[78:79], v[158:159] op_sel_hi:[1,0]
	v_pk_mul_f32 v[78:79], v[78:79], v[162:163] op_sel_hi:[1,0]
	v_pk_fma_f32 v[14:15], v[14:15], v[62:63], v[172:173]
	v_pk_fma_f32 v[42:43], v[42:43], v[62:63], v[78:79]
	v_pk_mul_f32 v[174:175], v[80:81], v[158:159] op_sel_hi:[1,0]
	v_pk_mul_f32 v[80:81], v[80:81], v[162:163] op_sel_hi:[1,0]
	v_pk_fma_f32 v[16:17], v[16:17], v[64:65], v[174:175]
	v_pk_fma_f32 v[36:37], v[36:37], v[64:65], v[80:81]
	v_pk_mul_f32 v[176:177], v[82:83], v[158:159] op_sel_hi:[1,0]
	v_pk_mul_f32 v[82:83], v[82:83], v[162:163] op_sel_hi:[1,0]
	v_pk_fma_f32 v[18:19], v[18:19], v[66:67], v[176:177]
	v_pk_fma_f32 v[38:39], v[38:39], v[66:67], v[82:83]
	v_pk_mul_f32 v[170:171], v[84:85], v[158:159] op_sel_hi:[1,0]
	v_pk_mul_f32 v[84:85], v[84:85], v[162:163] op_sel_hi:[1,0]
	v_pk_fma_f32 v[20:21], v[20:21], v[68:69], v[170:171]
	v_pk_fma_f32 v[32:33], v[32:33], v[68:69], v[84:85]
	v_pk_mul_f32 v[172:173], v[86:87], v[158:159] op_sel_hi:[1,0]
	v_pk_mul_f32 v[86:87], v[86:87], v[162:163] op_sel_hi:[1,0]
	v_pk_fma_f32 v[22:23], v[22:23], v[70:71], v[172:173]
	v_pk_fma_f32 v[34:35], v[34:35], v[70:71], v[86:87]
	v_pk_mul_f32 v[174:175], v[88:89], v[158:159] op_sel_hi:[1,0]
	v_pk_mul_f32 v[88:89], v[88:89], v[162:163] op_sel_hi:[1,0]
	v_pk_fma_f32 v[24:25], v[24:25], v[72:73], v[174:175]
	v_pk_fma_f32 v[28:29], v[28:29], v[72:73], v[88:89]
	v_pk_mul_f32 v[176:177], v[90:91], v[158:159] op_sel_hi:[1,0]
	v_pk_mul_f32 v[90:91], v[90:91], v[162:163] op_sel_hi:[1,0]
	v_pk_fma_f32 v[26:27], v[26:27], v[74:75], v[176:177]
	v_pk_fma_f32 v[30:31], v[30:31], v[74:75], v[90:91]
	ds_read_b128 v[44:47], v221 offset:0
	ds_read_b128 v[48:51], v221 offset:16
	ds_read_b128 v[52:55], v221 offset:32
	ds_read_b128 v[56:59], v221 offset:48
	s_waitcnt lgkmcnt(8)
	v_pk_fma_f32 v[142:143], v[178:179], v[202:203], v[12:13] op_sel_hi:[0,1,1]
	v_pk_fma_f32 v[186:187], v[178:179], v[202:203], v[40:41] op_sel:[1,0,0]
	v_pk_fma_f32 v[144:145], v[178:179], v[204:205], v[14:15] op_sel_hi:[0,1,1]
	v_pk_fma_f32 v[188:189], v[178:179], v[204:205], v[42:43] op_sel:[1,0,0]
	v_pk_fma_f32 v[146:147], v[178:179], v[206:207], v[16:17] op_sel_hi:[0,1,1]
	v_pk_fma_f32 v[190:191], v[178:179], v[206:207], v[36:37] op_sel:[1,0,0]
	v_pk_fma_f32 v[148:149], v[178:179], v[208:209], v[18:19] op_sel_hi:[0,1,1]
	v_pk_fma_f32 v[192:193], v[178:179], v[208:209], v[38:39] op_sel:[1,0,0]
	v_pk_fma_f32 v[150:151], v[178:179], v[210:211], v[20:21] op_sel_hi:[0,1,1]
	v_pk_fma_f32 v[194:195], v[178:179], v[210:211], v[32:33] op_sel:[1,0,0]
	v_pk_fma_f32 v[152:153], v[178:179], v[212:213], v[22:23] op_sel_hi:[0,1,1]
	v_pk_fma_f32 v[196:197], v[178:179], v[212:213], v[34:35] op_sel:[1,0,0]
	v_pk_fma_f32 v[154:155], v[178:179], v[214:215], v[24:25] op_sel_hi:[0,1,1]
	v_pk_fma_f32 v[198:199], v[178:179], v[214:215], v[28:29] op_sel:[1,0,0]
	v_pk_fma_f32 v[156:157], v[178:179], v[216:217], v[26:27] op_sel_hi:[0,1,1]
	v_pk_fma_f32 v[200:201], v[178:179], v[216:217], v[30:31] op_sel:[1,0,0]
	s_waitcnt lgkmcnt(4)
	v_pk_mul_f32 v[170:171], v[142:143], v[234:235]
	v_pk_mul_f32 v[172:173], v[144:145], v[236:237]
	v_pk_mul_f32 v[174:175], v[186:187], v[234:235]
	v_pk_mul_f32 v[176:177], v[188:189], v[236:237]
	v_pk_fma_f32 v[170:171], v[146:147], v[238:239], v[170:171]
	v_pk_fma_f32 v[172:173], v[148:149], v[240:241], v[172:173]
	v_pk_fma_f32 v[174:175], v[190:191], v[238:239], v[174:175]
	v_pk_fma_f32 v[176:177], v[192:193], v[240:241], v[176:177]
	v_pk_fma_f32 v[170:171], v[150:151], v[242:243], v[170:171]
	v_pk_fma_f32 v[172:173], v[152:153], v[244:245], v[172:173]
	v_pk_fma_f32 v[174:175], v[194:195], v[242:243], v[174:175]
	v_pk_fma_f32 v[176:177], v[196:197], v[244:245], v[176:177]
	v_pk_fma_f32 v[170:171], v[154:155], v[246:247], v[170:171]
	v_pk_fma_f32 v[172:173], v[156:157], v[248:249], v[172:173]
	v_pk_fma_f32 v[174:175], v[198:199], v[246:247], v[174:175]
	v_pk_fma_f32 v[176:177], v[200:201], v[248:249], v[176:177]
	v_pk_add_f32 v[170:171], v[170:171], v[172:173]
	v_pk_add_f32 v[174:175], v[174:175], v[176:177]
	ds_read_b128 v[60:63], v221 offset:256
	v_add_f32_e32 v170, v170, v171
	v_add_f32_e32 v174, v174, v175
	ds_read_b128 v[64:67], v221 offset:272
	ds_read_b128 v[68:71], v221 offset:288
	v_add_f32_dpp v170, v170, v170 quad_perm:[1,0,3,2] row_mask:0xf bank_mask:0xf bound_ctrl:1
	v_add_f32_dpp v174, v174, v174 quad_perm:[1,0,3,2] row_mask:0xf bank_mask:0xf bound_ctrl:1
	ds_read_b128 v[72:75], v221 offset:304
	ds_read_b128 v[76:79], v221 offset:512
	v_add_f32_dpp v170, v170, v170 quad_perm:[2,3,0,1] row_mask:0xf bank_mask:0xf bound_ctrl:1
	v_add_f32_dpp v174, v174, v174 quad_perm:[2,3,0,1] row_mask:0xf bank_mask:0xf bound_ctrl:1
	ds_read_b128 v[80:83], v221 offset:528
	ds_read_b128 v[84:87], v221 offset:544
	v_cvt_pk_bf16_f32 v180, v170, v174
	s_mov_b64 exec, s[6:7]
	global_store_dword v[250:251], v180, off
	s_mov_b64 exec, -1
	ds_read_b128 v[88:91], v221 offset:560
	ds_read_b64 v[178:179], v228 offset:1280
	v_lshl_add_u64 v[250:251], v[250:251], 0, s[80:81]
	s_waitcnt lgkmcnt(9)
	v_pk_mul_f32 v[158:159], v[142:143], v[44:45]
	v_pk_mul_f32 v[160:161], v[144:145], v[46:47]
	v_pk_mul_f32 v[162:163], v[186:187], v[44:45]
	v_pk_mul_f32 v[164:165], v[188:189], v[46:47]
	v_pk_fma_f32 v[158:159], v[146:147], v[48:49], v[158:159]
	v_pk_fma_f32 v[160:161], v[148:149], v[50:51], v[160:161]
	v_pk_fma_f32 v[162:163], v[190:191], v[48:49], v[162:163]
	v_pk_fma_f32 v[164:165], v[192:193], v[50:51], v[164:165]
	v_pk_fma_f32 v[158:159], v[150:151], v[52:53], v[158:159]
	v_pk_fma_f32 v[160:161], v[152:153], v[54:55], v[160:161]
	v_pk_fma_f32 v[162:163], v[194:195], v[52:53], v[162:163]
	v_pk_fma_f32 v[164:165], v[196:197], v[54:55], v[164:165]
	v_pk_fma_f32 v[158:159], v[154:155], v[56:57], v[158:159]
	v_pk_fma_f32 v[160:161], v[156:157], v[58:59], v[160:161]
	v_pk_fma_f32 v[162:163], v[198:199], v[56:57], v[162:163]
	v_pk_fma_f32 v[164:165], v[200:201], v[58:59], v[164:165]
	v_pk_add_f32 v[158:159], v[158:159], v[160:161]
	v_pk_add_f32 v[162:163], v[162:163], v[164:165]
	s_waitcnt lgkmcnt(1)
	v_add_f32_e32 v158, v158, v159
	v_add_f32_e32 v162, v162, v163
	ds_read_b128 v[202:205], v221 offset:768
	ds_read_b128 v[206:209], v221 offset:784
	v_add_f32_dpp v158, v158, v158 quad_perm:[1,0,3,2] row_mask:0xf bank_mask:0xf bound_ctrl:1
	v_add_f32_dpp v162, v162, v162 quad_perm:[1,0,3,2] row_mask:0xf bank_mask:0xf bound_ctrl:1
	ds_read_b128 v[210:213], v221 offset:800
	ds_read_b128 v[214:217], v221 offset:816
	v_add_f32_dpp v158, v158, v158 quad_perm:[2,3,0,1] row_mask:0xf bank_mask:0xf bound_ctrl:1
	v_add_f32_dpp v162, v162, v162 quad_perm:[2,3,0,1] row_mask:0xf bank_mask:0xf bound_ctrl:1
	ds_read_b128 v[234:237], v221 offset:1024
	ds_read_b128 v[238:241], v221 offset:1040
	ds_read_b128 v[242:245], v221 offset:1056
	ds_read_b128 v[246:249], v221 offset:1072
	v_pk_mul_f32 v[170:171], v[76:77], v[158:159] op_sel_hi:[1,0]
	v_pk_mul_f32 v[76:77], v[76:77], v[162:163] op_sel_hi:[1,0]
	v_pk_fma_f32 v[142:143], v[142:143], v[60:61], v[170:171]
	v_pk_fma_f32 v[186:187], v[186:187], v[60:61], v[76:77]
	v_pk_mul_f32 v[172:173], v[78:79], v[158:159] op_sel_hi:[1,0]
	v_pk_mul_f32 v[78:79], v[78:79], v[162:163] op_sel_hi:[1,0]
	v_pk_fma_f32 v[144:145], v[144:145], v[62:63], v[172:173]
	v_pk_fma_f32 v[188:189], v[188:189], v[62:63], v[78:79]
	v_pk_mul_f32 v[174:175], v[80:81], v[158:159] op_sel_hi:[1,0]
	v_pk_mul_f32 v[80:81], v[80:81], v[162:163] op_sel_hi:[1,0]
	v_pk_fma_f32 v[146:147], v[146:147], v[64:65], v[174:175]
	v_pk_fma_f32 v[190:191], v[190:191], v[64:65], v[80:81]
	v_pk_mul_f32 v[176:177], v[82:83], v[158:159] op_sel_hi:[1,0]
	v_pk_mul_f32 v[82:83], v[82:83], v[162:163] op_sel_hi:[1,0]
	v_pk_fma_f32 v[148:149], v[148:149], v[66:67], v[176:177]
	v_pk_fma_f32 v[192:193], v[192:193], v[66:67], v[82:83]
	v_pk_mul_f32 v[170:171], v[84:85], v[158:159] op_sel_hi:[1,0]
	v_pk_mul_f32 v[84:85], v[84:85], v[162:163] op_sel_hi:[1,0]
	v_pk_fma_f32 v[150:151], v[150:151], v[68:69], v[170:171]
	v_pk_fma_f32 v[194:195], v[194:195], v[68:69], v[84:85]
	v_pk_mul_f32 v[172:173], v[86:87], v[158:159] op_sel_hi:[1,0]
	v_pk_mul_f32 v[86:87], v[86:87], v[162:163] op_sel_hi:[1,0]
	v_pk_fma_f32 v[152:153], v[152:153], v[70:71], v[172:173]
	v_pk_fma_f32 v[196:197], v[196:197], v[70:71], v[86:87]
	v_pk_mul_f32 v[174:175], v[88:89], v[158:159] op_sel_hi:[1,0]
	v_pk_mul_f32 v[88:89], v[88:89], v[162:163] op_sel_hi:[1,0]
	v_pk_fma_f32 v[154:155], v[154:155], v[72:73], v[174:175]
	v_pk_fma_f32 v[198:199], v[198:199], v[72:73], v[88:89]
	v_pk_mul_f32 v[176:177], v[90:91], v[158:159] op_sel_hi:[1,0]
	v_pk_mul_f32 v[90:91], v[90:91], v[162:163] op_sel_hi:[1,0]
	v_pk_fma_f32 v[156:157], v[156:157], v[74:75], v[176:177]
	v_pk_fma_f32 v[200:201], v[200:201], v[74:75], v[90:91]
	s_waitcnt lgkmcnt(4)
	v_pk_fma_f32 v[12:13], v[178:179], v[202:203], v[142:143] op_sel_hi:[0,1,1]
	v_pk_fma_f32 v[40:41], v[178:179], v[202:203], v[186:187] op_sel:[1,0,0]
	v_pk_fma_f32 v[14:15], v[178:179], v[204:205], v[144:145] op_sel_hi:[0,1,1]
	v_pk_fma_f32 v[42:43], v[178:179], v[204:205], v[188:189] op_sel:[1,0,0]
	v_pk_fma_f32 v[16:17], v[178:179], v[206:207], v[146:147] op_sel_hi:[0,1,1]
	v_pk_fma_f32 v[36:37], v[178:179], v[206:207], v[190:191] op_sel:[1,0,0]
	v_pk_fma_f32 v[18:19], v[178:179], v[208:209], v[148:149] op_sel_hi:[0,1,1]
	v_pk_fma_f32 v[38:39], v[178:179], v[208:209], v[192:193] op_sel:[1,0,0]
	v_pk_fma_f32 v[20:21], v[178:179], v[210:211], v[150:151] op_sel_hi:[0,1,1]
	v_pk_fma_f32 v[32:33], v[178:179], v[210:211], v[194:195] op_sel:[1,0,0]
	v_pk_fma_f32 v[22:23], v[178:179], v[212:213], v[152:153] op_sel_hi:[0,1,1]
	v_pk_fma_f32 v[34:35], v[178:179], v[212:213], v[196:197] op_sel:[1,0,0]
	v_pk_fma_f32 v[24:25], v[178:179], v[214:215], v[154:155] op_sel_hi:[0,1,1]
	v_pk_fma_f32 v[28:29], v[178:179], v[214:215], v[198:199] op_sel:[1,0,0]
	v_pk_fma_f32 v[26:27], v[178:179], v[216:217], v[156:157] op_sel_hi:[0,1,1]
	v_pk_fma_f32 v[30:31], v[178:179], v[216:217], v[200:201] op_sel:[1,0,0]
	s_waitcnt lgkmcnt(0)
	v_pk_mul_f32 v[170:171], v[12:13], v[234:235]
	v_pk_mul_f32 v[172:173], v[14:15], v[236:237]
	v_pk_mul_f32 v[174:175], v[40:41], v[234:235]
	v_pk_mul_f32 v[176:177], v[42:43], v[236:237]
	v_pk_fma_f32 v[170:171], v[16:17], v[238:239], v[170:171]
	v_pk_fma_f32 v[172:173], v[18:19], v[240:241], v[172:173]
	v_pk_fma_f32 v[174:175], v[36:37], v[238:239], v[174:175]
	v_pk_fma_f32 v[176:177], v[38:39], v[240:241], v[176:177]
	v_pk_fma_f32 v[170:171], v[20:21], v[242:243], v[170:171]
	v_pk_fma_f32 v[172:173], v[22:23], v[244:245], v[172:173]
	v_pk_fma_f32 v[174:175], v[32:33], v[242:243], v[174:175]
	v_pk_fma_f32 v[176:177], v[34:35], v[244:245], v[176:177]
	v_pk_fma_f32 v[170:171], v[24:25], v[246:247], v[170:171]
	v_pk_fma_f32 v[172:173], v[26:27], v[248:249], v[172:173]
	v_pk_fma_f32 v[174:175], v[28:29], v[246:247], v[174:175]
	v_pk_fma_f32 v[176:177], v[30:31], v[248:249], v[176:177]
	v_pk_add_f32 v[170:171], v[170:171], v[172:173]
	v_pk_add_f32 v[174:175], v[174:175], v[176:177]
	s_nop 0
	v_add_f32_e32 v170, v170, v171
	v_add_f32_e32 v174, v174, v175
	s_nop 0
	s_nop 0
	v_add_f32_dpp v170, v170, v170 quad_perm:[1,0,3,2] row_mask:0xf bank_mask:0xf bound_ctrl:1
	v_add_f32_dpp v174, v174, v174 quad_perm:[1,0,3,2] row_mask:0xf bank_mask:0xf bound_ctrl:1
	s_nop 0
	s_nop 0
	v_add_f32_dpp v170, v170, v170 quad_perm:[2,3,0,1] row_mask:0xf bank_mask:0xf bound_ctrl:1
	v_add_f32_dpp v174, v174, v174 quad_perm:[2,3,0,1] row_mask:0xf bank_mask:0xf bound_ctrl:1
	s_nop 0
	s_nop 0
	v_cvt_pk_bf16_f32 v180, v170, v174
	s_mov_b64 exec, s[6:7]
	global_store_dword v[250:251], v180, off
	s_mov_b64 exec, -1
	s_waitcnt lgkmcnt(0)
